# stack: write-through stores w/o L2 write-back, direct XCD release, early invalidate, ws pointer kept in SGPRs, q-proj outputs plain
# baseline (speedup 1.0000x reference)
_Z6mk_fwd4Args:
	s_load_dword s56, s[0:1], 0xe8
	s_load_dwordx2 s[100:101], s[0:1], 0xd8
	v_lshrrev_b32_e32 v1, 6, v0
	s_mov_b32 s13, s2
	v_readfirstlane_b32 s52, v1
	s_waitcnt lgkmcnt(0)
	s_and_b32 s3, s56, 7
	s_cmp_lg_u32 s3, 0
	s_cbranch_scc1 .LBB0_2
	s_ashr_i32 s4, s2, 31
	s_lshr_b32 s4, s4, 29
	s_add_i32 s4, s2, s4
	s_ashr_i32 s5, s4, 3
	s_and_b32 s4, s4, -8
	s_ashr_i32 s3, s56, 3
	s_sub_i32 s4, s2, s4
	s_mul_i32 s3, s3, s4
	s_add_i32 s13, s3, s5
.LBB0_2:
	v_lshl_add_u32 v2, v0, 2, 0
	v_add_u32_e32 v2, 0x20000, v2
	v_mov_b32_e32 v3, 0
	ds_write2st64_b32 v2, v3, v3 offset1:8
	ds_write2st64_b32 v2, v3, v3 offset0:16 offset1:24
	v_or_b32_e32 v2, 0x800, v0
	s_mov_b64 s[4:5], -1
	s_and_saveexec_b64 s[6:7], s[4:5]
	v_lshl_add_u32 v4, v2, 2, 0
	v_add_u32_e32 v4, 0x20000, v4
	ds_write_b32 v4, v3
	s_or_b64 exec, exec, s[6:7]
	s_and_saveexec_b64 s[6:7], s[4:5]
	s_add_i32 s3, 0, 0x20000
	v_lshl_add_u32 v2, v2, 2, s3
	v_mov_b32_e32 v3, 0
	ds_write_b32 v2, v3 offset:2048
	s_or_b64 exec, exec, s[6:7]
	v_or_b32_e32 v2, 0xc00, v0
	v_cmp_gt_u32_e64 s[4:5], 7, 6
	v_cmp_gt_u32_e64 s[8:9], 7, 5
	s_and_saveexec_b64 s[6:7], s[8:9]
	v_lshl_add_u32 v3, v2, 2, 0
	v_add_u32_e32 v3, 0x20000, v3
	v_mov_b32_e32 v4, 0
	ds_write_b32 v3, v4
	s_or_b64 exec, exec, s[6:7]
	s_and_saveexec_b64 s[6:7], s[4:5]
	s_add_i32 s3, 0, 0x20000
	v_lshl_add_u32 v2, v2, 2, s3
	v_mov_b32_e32 v3, 0
	ds_write_b32 v2, v3 offset:2048
	s_or_b64 exec, exec, s[6:7]
	s_mov_b32 s4, 0
	s_waitcnt lgkmcnt(0)
	s_barrier
	s_ashr_i32 s5, s4, 31
	s_lshl_b64 s[4:5], s[4:5], 3
	s_add_u32 s4, s0, s4
	s_addc_u32 s5, s1, s5
	s_mov_b64 s[4:5], s[100:101]
	s_getreg_b32 s3, hwreg(HW_REG_XCC_ID, 0, 4)
	v_cmp_eq_u32_e64 s[90:91], 0, v0
	s_waitcnt lgkmcnt(0)
	s_add_u32 s8, s4, 0x1000
	v_writelane_b32 v253, s4, 0
	s_addc_u32 s9, s5, 0
	s_and_b32 s55, s3, 15
	v_writelane_b32 v253, s5, 1
	s_and_saveexec_b64 s[4:5], s[90:91]
	s_cbranch_execz .LBB0_13
	s_mov_b64 s[6:7], exec
	v_mbcnt_lo_u32_b32 v2, s6, 0
	v_mbcnt_hi_u32_b32 v2, s7, v2
	v_cmp_eq_u32_e32 vcc, 0, v2
	s_and_b64 s[10:11], exec, vcc
	s_mov_b64 exec, s[10:11]
	s_cbranch_execz .LBB0_13
	s_lshl_b32 s3, s55, 8
	s_bcnt1_i32_b64 s6, s[6:7]
	v_mov_b32_e32 v2, s3
	v_mov_b32_e32 v3, s6
	global_atomic_add v2, v3, s[8:9] offset:1024

.LBB0_16:
	s_or_b64 exec, exec, s[4:5]
	s_lshl_b32 s4, s13, 3
	s_add_i32 s12, s4, s52
	v_mov_b32_e32 v13, v0
	s_mov_b32 s4, 0
	s_ashr_i32 s5, s4, 31
	s_lshl_b32 s10, s56, 3
	s_lshl_b64 s[4:5], s[4:5], 3
	s_add_u32 s4, s0, s4
	s_addc_u32 s5, s1, s5
	s_mov_b64 s[4:5], s[100:101]
	s_mov_b32 s15, 0
	s_cmpk_lt_i32 s12, 0x2b40
	v_mov_b32_e32 v2, v0
	s_mov_b32 s16, 0
	s_cbranch_scc0 .LBB0_91
	s_lshl_b32 s14, s52, 14
	s_ashr_i32 s17, s16, 31
	s_lshl_b32 s11, s56, 4
	s_add_i32 s14, s14, 0
	s_lshl_b64 s[16:17], s[16:17], 3
	s_add_u32 s16, s0, s16
	s_addc_u32 s17, s1, s17
	s_mov_b64 s[26:27], s[100:101]
	v_bfe_u32 v18, v2, 5, 1
	v_and_b32_e32 v4, 31, v2
	v_and_b32_e32 v3, 7, v2
	v_bfe_u32 v19, v2, 3, 3
	s_waitcnt lgkmcnt(0)
	s_add_u32 s46, s26, 0x600000
	s_addc_u32 s47, s27, 0
	s_add_u32 s16, s26, 0x1e00000
	s_addc_u32 s17, s27, 0
	s_add_u32 s18, s26, 0x1600000
	s_addc_u32 s19, s27, 0
	s_add_u32 s20, s26, 0x1200000
	s_addc_u32 s21, s27, 0
	s_add_u32 s22, s26, 0x800000
	s_addc_u32 s23, s27, 0
	s_add_u32 s48, s26, 0x6600000
	s_addc_u32 s49, s27, 0
	s_add_u32 s24, s26, 0x4600000
	s_addc_u32 s25, s27, 0
	s_add_u32 s50, s26, 0x2600000
	v_mov_b32_e32 v11, 0
	v_lshlrev_b32_e32 v12, 3, v3
	v_lshl_add_u32 v5, v4, 2, s14
	v_mul_u32_u24_e32 v6, 0x84, v18
	v_mul_u32_u24_e32 v2, 0x420, v3
	v_lshlrev_b32_e32 v3, 2, v19
	v_lshlrev_b32_e32 v14, 2, v4
	s_addc_u32 s51, s27, 0
	v_add3_u32 v20, s14, v2, v3
	v_or_b32_e32 v21, 8, v19
	v_or_b32_e32 v22, 16, v19
	v_or_b32_e32 v23, 24, v19
	s_and_b32 s57, s52, 7
	v_mov_b32_e32 v16, v14
	v_mov_b32_e32 v17, v11
	v_lshlrev_b32_e32 v10, 1, v12
	v_add_u32_e32 v24, v5, v6
	s_mov_b32 s58, s12
	s_branch .LBB0_21

.LBB0_176:
	s_movk_i32 s8, 0xb60
	s_and_b64 s[4:5], s[4:5], exec
	s_cselect_b32 s4, s8, 0x2220
	s_cmp_gt_u32 s3, 1
	s_cselect_b32 s5, s4, 0
	s_ashr_i32 s31, s2, 2
	s_and_b32 s30, s2, 7
	s_and_b32 s4, s31, -8
	s_or_b32 s4, s4, s30
	v_writelane_b32 v253, s4, 2
	s_lshl_b32 s4, s4, 3
	s_add_i32 s4, s52, s4
	v_writelane_b32 v253, s4, 3
	s_cmp_le_u32 s34, s5
	s_mov_b32 s4, 0
	s_cbranch_scc1 .LBB0_252
	v_readlane_b32 s8, v253, 3
	s_add_i32 s35, s8, s5
	v_mov_b32_e32 v2, v0
	s_cmp_ge_i32 s35, s34
	s_cbranch_scc1 .LBB0_252
	s_ashr_i32 s5, s4, 31
	s_lshl_b64 s[4:5], s[4:5], 3
	s_add_u32 s4, s0, s4
	s_addc_u32 s5, s1, s5
	s_mov_b64 s[12:13], s[100:101]
	s_lshl_b32 s4, s52, 14
	s_add_i32 s4, s4, 0
	v_and_b32_e32 v3, 7, v2
	v_bfe_u32 v18, v2, 3, 3
	s_waitcnt lgkmcnt(0)
	s_add_u32 s36, s12, 0x600000
	s_addc_u32 s37, s13, 0
	s_add_u32 s38, s12, 0x700000
	s_addc_u32 s39, s13, 0
	s_add_u32 s40, s12, 0x1e00000
	s_addc_u32 s41, s13, 0
	s_add_u32 s42, s12, 0x1600000
	s_addc_u32 s43, s13, 0
	s_add_u32 s8, s12, 0x1400000
	s_addc_u32 s9, s13, 0
	s_add_u32 s10, s12, 0xd00000
	s_addc_u32 s11, s13, 0
	s_add_u32 s44, s12, 0x4600000
	s_addc_u32 s45, s13, 0
	v_bfe_u32 v13, v2, 5, 1
	s_add_u32 s46, s12, 0x2600000
	v_and_b32_e32 v4, 31, v2
	v_lshlrev_b32_e32 v12, 3, v3
	v_mul_u32_u24_e32 v2, 0x420, v3
	v_lshlrev_b32_e32 v3, 2, v18
	s_addc_u32 s47, s13, 0
	v_lshl_add_u32 v5, v4, 2, s4
	v_add3_u32 v19, s4, v2, v3
	s_and_b32 s4, s35, 0x1ff
	s_xor_b32 s48, s4, 0x100
	v_readlane_b32 s4, v253, 3
	v_mov_b32_e32 v11, 0
	v_mul_u32_u24_e32 v6, 0x84, v13
	s_and_b32 s49, s4, 31
	s_lshl_b32 s4, s35, 4
	v_lshlrev_b32_e32 v14, 2, v4
	s_mov_b32 s5, 0
	v_or_b32_e32 v20, 8, v18
	v_or_b32_e32 v21, 16, v18
	v_or_b32_e32 v22, 24, v18
	s_and_b32 s50, s52, 7
	s_add_i32 s51, s4, 0xfffbd000
	v_mov_b32_e32 v16, v14
	v_mov_b32_e32 v17, v11
	v_lshlrev_b32_e32 v10, 1, v12
	v_add_u32_e32 v23, v5, v6
	s_branch .LBB0_182

.LBB0_276:
	s_and_b32 s2, s46, 1
	s_cmp_eq_u32 s2, 0
	s_waitcnt lgkmcnt(0)
	s_cselect_b64 s[4:5], -1, 0
	v_writelane_b32 v254, s4, 26
	s_cmp_eq_u32 s2, 1
	v_cmp_ne_u32_e64 s[50:51], 1, v235
	v_writelane_b32 v254, s5, 27
	s_cselect_b64 s[4:5], -1, 0
	v_writelane_b32 v254, s4, 28
	s_mov_b64 s[2:3], -1
	s_and_b64 vcc, exec, s[4:5]
	v_writelane_b32 v254, s5, 29
	v_writelane_b32 v254, s46, 30
	v_writelane_b32 v254, s50, 31
	s_nop 1
	v_writelane_b32 v254, s51, 32
	s_cbranch_vccz .LBB0_482
	s_and_b64 vcc, exec, s[50:51]
	s_cbranch_vccnz .LBB0_444
	s_mov_b32 s2, s87
	s_lshr_b32 s15, s46, 1
	s_ashr_i32 s3, s2, 31
	s_lshl_b32 s10, s15, 2
	s_lshl_b64 s[2:3], s[2:3], 3
	s_add_u32 s2, s0, s2
	s_addc_u32 s3, s1, s3
	s_mov_b64 s[6:7], s[100:101]
	s_mov_b32 s2, s87
	s_mov_b32 s4, s87
	s_ashr_i32 s5, s4, 31
	s_lshl_b64 s[4:5], s[4:5], 3
	s_add_u32 s4, s0, s4
	s_addc_u32 s5, s1, s5
	s_mov_b64 s[4:5], s[100:101]
	v_mov_b32_e32 v2, v0
	v_mov_b32_e32 v7, v4
	s_waitcnt lgkmcnt(0)
	v_writelane_b32 v254, s4, 33
	s_nop 1
	v_writelane_b32 v254, s5, 34
	s_mov_b32 s4, s87
	s_ashr_i32 s5, s4, 31
	s_lshl_b64 s[4:5], s[4:5], 3
	s_add_u32 s4, s0, s4
	s_addc_u32 s5, s1, s5
	s_load_dwordx2 s[8:9], s[4:5], 0xd0
	s_mov_b32 s4, s87
	s_ashr_i32 s5, s4, 31
	s_lshl_b64 s[4:5], s[4:5], 3
	s_add_u32 s4, s0, s4
	s_addc_u32 s5, s1, s5
	s_mov_b64 s[4:5], s[100:101]
	v_readlane_b32 s12, v254, 2
	v_readlane_b32 s13, v254, 3
	s_add_u32 s10, s12, s10
	s_addc_u32 s11, s13, 0
	s_lshl_b64 s[10:11], s[10:11], 17
	s_waitcnt lgkmcnt(0)
	s_add_u32 s4, s4, s10
	s_mov_b32 s10, 18
	s_addc_u32 s5, s5, s11
	s_ashr_i32 s11, s10, 31
	s_lshl_b64 s[10:11], s[10:11], 3
	s_add_u32 s10, s0, s10
	s_addc_u32 s11, s1, s11
	s_load_dwordx2 s[10:11], s[10:11], 0x0
	s_waitcnt lgkmcnt(0)
	v_writelane_b32 v254, s10, 35
	v_readfirstlane_b32 s3, v2
	s_ashr_i32 s52, s3, 6
	v_lshlrev_b32_e32 v3, 1, v2
	s_lshl_b32 s18, s52, 5
	v_and_b32_e32 v5, 24, v3
	v_and_b32_e32 v3, 3, v2
	v_or3_b32 v38, v5, v3, s18
	v_and_b32_e32 v6, 48, v2
	v_lshl_add_u64 v[6:7], s[4:5], 0, v[6:7]
	s_mov_b64 s[4:5], 0x700000
	v_ashrrev_i32_e32 v39, 31, v38
	v_lshl_add_u64 v[40:41], v[6:7], 0, s[4:5]
	v_lshlrev_b64 v[6:7], 9, v[38:39]
	v_or_b32_e32 v38, 4, v38
	v_ashrrev_i32_e32 v39, 31, v38
	v_lshlrev_b64 v[38:39], 9, v[38:39]
	v_lshl_add_u64 v[6:7], v[40:41], 0, v[6:7]
	v_lshl_add_u64 v[38:39], v[40:41], 0, v[38:39]
	global_load_dwordx4 v[34:37], v[6:7], off
	global_load_dwordx4 v[30:33], v[6:7], off offset:64
	global_load_dwordx4 v[26:29], v[6:7], off offset:128
	global_load_dwordx4 v[22:25], v[6:7], off offset:192
	global_load_dwordx4 v[18:21], v[6:7], off offset:256
	global_load_dwordx4 v[14:17], v[6:7], off offset:320
	global_load_dwordx4 v[10:13], v[6:7], off offset:384
	s_nop 0
	global_load_dwordx4 v[6:9], v[6:7], off offset:448
	s_nop 0
	global_load_dwordx4 v[66:69], v[38:39], off
	global_load_dwordx4 v[62:65], v[38:39], off offset:64
	global_load_dwordx4 v[58:61], v[38:39], off offset:128
	global_load_dwordx4 v[54:57], v[38:39], off offset:192
	global_load_dwordx4 v[50:53], v[38:39], off offset:256
	global_load_dwordx4 v[46:49], v[38:39], off offset:320
	global_load_dwordx4 v[42:45], v[38:39], off offset:384
	s_nop 0
	global_load_dwordx4 v[38:41], v[38:39], off offset:448
	s_lshl_b32 s4, s74, 8
	s_movk_i32 s3, 0x10f
	v_writelane_b32 v254, s11, 36
	s_and_b32 s14, s4, 0xf00
	v_cmp_gt_i32_e32 vcc, s3, v2
	s_and_saveexec_b64 s[10:11], vcc
	s_cbranch_execz .LBB0_282
	v_add_u32_e32 v5, -15, v2
	v_add_u32_e32 v70, s14, v5
	v_cmp_lt_i32_e32 vcc, -1, v70
	v_mov_b32_e32 v70, 0
	s_and_saveexec_b64 s[12:13], vcc
	s_cbranch_execz .LBB0_281
	s_ashr_i32 s3, s2, 31
	s_lshl_b64 s[2:3], s[2:3], 3
	s_add_u32 s2, s0, s2
	s_addc_u32 s3, s1, s3
	s_mov_b64 s[2:3], s[100:101]
	v_readlane_b32 s5, v253, 6
	s_lshl_b32 s5, s5, 2
	v_add_u32_e32 v70, s4, v5
	v_ashrrev_i32_e32 v71, 31, v70
	s_waitcnt lgkmcnt(0)
	s_add_u32 s2, s2, s5
	s_addc_u32 s3, s3, 0
	v_lshl_add_u64 v[70:71], v[70:71], 2, s[2:3]
	s_mov_b32 s2, 0x100000
	v_add_co_u32_e32 v72, vcc, s2, v70
	s_mov_b32 s2, 0x104000
	s_nop 0
	v_addc_co_u32_e32 v73, vcc, 0, v71, vcc
	v_add_co_u32_e32 v74, vcc, s2, v70
	s_mov_b32 s2, 0x108000
	s_nop 0
	v_addc_co_u32_e32 v75, vcc, 0, v71, vcc
	v_add_co_u32_e32 v76, vcc, s2, v70
	s_mov_b32 s2, 0x10c000
	s_nop 0
	v_addc_co_u32_e32 v77, vcc, 0, v71, vcc
	v_add_co_u32_e32 v78, vcc, s2, v70
	s_mov_b32 s2, 0x110000
	s_nop 0
	v_addc_co_u32_e32 v79, vcc, 0, v71, vcc
	v_add_co_u32_e32 v80, vcc, s2, v70
	s_mov_b32 s2, 0x114000
	s_nop 0
	v_addc_co_u32_e32 v81, vcc, 0, v71, vcc
	v_add_co_u32_e32 v82, vcc, s2, v70
	s_mov_b32 s2, 0x118000
	s_nop 0
	v_addc_co_u32_e32 v83, vcc, 0, v71, vcc
	v_add_co_u32_e32 v84, vcc, s2, v70
	s_mov_b32 s2, 0x11c000
	s_nop 0
	v_addc_co_u32_e32 v85, vcc, 0, v71, vcc
	v_add_co_u32_e32 v86, vcc, s2, v70
	s_mov_b32 s2, 0x120000
	s_nop 0
	v_addc_co_u32_e32 v87, vcc, 0, v71, vcc
	v_add_co_u32_e32 v88, vcc, s2, v70
	s_mov_b32 s2, 0x124000
	s_nop 0
	v_addc_co_u32_e32 v89, vcc, 0, v71, vcc
	global_load_dword v72, v[72:73], off
	s_nop 0
	global_load_dword v74, v[74:75], off
	s_nop 0
	global_load_dword v76, v[76:77], off
	s_nop 0
	global_load_dword v78, v[78:79], off
	s_nop 0
	global_load_dword v80, v[80:81], off
	s_nop 0
	global_load_dword v82, v[82:83], off
	s_nop 0
	global_load_dword v86, v[86:87], off
	s_nop 0
	global_load_dword v84, v[84:85], off
	s_nop 0
	global_load_dword v73, v[88:89], off
	v_add_co_u32_e32 v88, vcc, s2, v70
	s_mov_b32 s2, 0x128000
	s_nop 0
	v_addc_co_u32_e32 v89, vcc, 0, v71, vcc
	global_load_dword v75, v[88:89], off
	v_add_co_u32_e32 v88, vcc, s2, v70
	s_mov_b32 s2, 0x12c000
	s_nop 0
	v_addc_co_u32_e32 v89, vcc, 0, v71, vcc
	global_load_dword v77, v[88:89], off
	v_add_co_u32_e32 v88, vcc, s2, v70
	s_mov_b32 s2, 0x130000
	s_nop 0
	v_addc_co_u32_e32 v89, vcc, 0, v71, vcc
	global_load_dword v79, v[88:89], off
	v_add_co_u32_e32 v88, vcc, s2, v70
	s_mov_b32 s2, 0x134000
	s_nop 0
	v_addc_co_u32_e32 v89, vcc, 0, v71, vcc
	global_load_dword v81, v[88:89], off
	v_add_co_u32_e32 v88, vcc, s2, v70
	s_mov_b32 s2, 0x138000
	s_nop 0
	v_addc_co_u32_e32 v89, vcc, 0, v71, vcc
	global_load_dword v83, v[88:89], off
	v_add_co_u32_e32 v88, vcc, s2, v70
	s_mov_b32 s2, 0x13c000
	s_nop 0
	v_addc_co_u32_e32 v89, vcc, 0, v71, vcc
	v_add_co_u32_e32 v70, vcc, s2, v70
	s_nop 1
	v_addc_co_u32_e32 v71, vcc, 0, v71, vcc
	global_load_dword v87, v[70:71], off
	global_load_dword v85, v[88:89], off
	s_waitcnt vmcnt(6)
	v_pk_add_f32 v[70:71], v[72:73], v[74:75]
	s_waitcnt vmcnt(4)
	v_pk_add_f32 v[72:73], v[76:77], v[78:79]
	s_nop 0
	v_pk_add_f32 v[70:71], v[70:71], v[72:73]
	s_waitcnt vmcnt(2)
	v_pk_add_f32 v[72:73], v[80:81], v[82:83]
	s_waitcnt vmcnt(0)
	v_pk_add_f32 v[74:75], v[84:85], v[86:87]
	s_nop 0
	v_pk_add_f32 v[72:73], v[72:73], v[74:75]
	s_nop 0
	v_pk_add_f32 v[70:71], v[70:71], v[72:73]
	s_nop 0
	v_add_f32_e32 v5, v70, v71
	v_fmamk_f32 v5, v5, 0x3a800000, v236
	v_cmp_gt_f32_e32 vcc, s44, v5
	v_mul_f32_e32 v70, 0x4f800000, v5
	s_nop 0
	v_cndmask_b32_e32 v5, v5, v70, vcc
	v_sqrt_f32_e32 v70, v5
	s_nop 0
	v_add_u32_e32 v71, -1, v70
	v_fma_f32 v72, -v71, v70, v5
	v_cmp_ge_f32_e64 s[2:3], 0, v72
	v_add_u32_e32 v72, 1, v70
	s_nop 0
	v_cndmask_b32_e64 v71, v70, v71, s[2:3]
	v_fma_f32 v70, -v72, v70, v5
	v_cmp_lt_f32_e64 s[2:3], 0, v70
	s_nop 1
	v_cndmask_b32_e64 v70, v71, v72, s[2:3]
	v_mul_f32_e32 v71, 0x37800000, v70
	v_cndmask_b32_e32 v70, v70, v71, vcc
	v_cmp_class_f32_e32 vcc, v5, v237
	s_nop 1
	v_cndmask_b32_e32 v5, v70, v5, vcc
	v_div_scale_f32 v70, s[2:3], v5, v5, 1.0
	v_rcp_f32_e32 v71, v70
	s_nop 0
	v_fma_f32 v72, -v70, v71, 1.0
	v_fmac_f32_e32 v71, v72, v71
	v_div_scale_f32 v72, vcc, 1.0, v5, 1.0
	v_mul_f32_e32 v73, v72, v71
	v_fma_f32 v74, -v70, v73, v72
	v_fmac_f32_e32 v73, v74, v71
	v_fma_f32 v70, -v70, v73, v72
	v_div_fmas_f32 v70, v70, v71, v73
	v_div_fixup_f32 v70, v70, v5, 1.0

.LBB0_482:
	s_and_b64 vcc, exec, s[2:3]
	s_cbranch_vccz .LBB0_760
	v_readlane_b32 s12, v253, 11
	s_mov_b32 s8, s87
	s_mov_b32 s6, s87
	s_mov_b32 s2, s87
	s_mov_b32 s4, s87
	v_mov_b32_e32 v6, v0
	v_readlane_b32 s13, v253, 12
	s_movk_i32 s11, 0x400
	v_readfirstlane_b32 s10, v6
	s_andn2_b64 vcc, exec, s[12:13]
	s_cbranch_vccnz .LBB0_514
	v_lshlrev_b32_e32 v3, 4, v6
	v_add_u32_e32 v2, 0x2000, v3
	s_ashr_i32 s9, s8, 31
	v_ashrrev_i32_e32 v5, 31, v2
	s_lshr_b32 s3, s46, 1
	s_lshl_b64 s[8:9], s[8:9], 3
	v_lshrrev_b32_e32 v5, 22, v5
	s_add_u32 s8, s0, s8
	v_add_u32_e32 v5, v2, v5
	s_addc_u32 s9, s1, s9
	v_ashrrev_i32_e32 v7, 10, v5
	s_mov_b64 s[8:9], s[100:101]
	v_mul_i32_i24_e32 v5, 0x400, v7
	v_sub_u32_e32 v2, v2, v5
	v_lshrrev_b32_e32 v5, 4, v2
	v_bitop3_b32 v2, v5, v2, 32 bitop3:0x6c
	v_ashrrev_i32_e32 v5, 31, v2
	s_waitcnt lgkmcnt(0)
	s_add_u32 s5, s8, s89
	v_lshrrev_b32_e32 v5, 26, v5
	s_addc_u32 s7, s9, 0
	v_add_u32_e32 v5, v2, v5
	v_lshlrev_b32_e32 v10, 3, v7
	s_add_u32 s36, s5, 0x7600000
	v_ashrrev_i32_e32 v8, 6, v5
	v_and_b32_e32 v10, -16, v10
	s_addc_u32 s37, s7, 0
	s_ashr_i32 s7, s6, 31
	v_add_u32_e32 v10, v8, v10
	s_lshl_b64 s[6:7], s[6:7], 3
	v_lshrrev_b32_e32 v11, 2, v10
	v_lshlrev_b32_e32 v12, 1, v10
	v_and_b32_e32 v5, 0xc0, v5
	s_add_u32 s6, s0, s6
	v_and_b32_e32 v9, 3, v8
	v_and_b32_e32 v11, 4, v11
	v_and_b32_e32 v12, 0x1fffd8, v12
	v_sub_u32_e32 v2, v2, v5
	s_addc_u32 s7, s1, s7
	v_or3_b32 v11, v9, v11, v12
	v_lshlrev_b32_e32 v9, 5, v7
	v_ashrrev_i16_sdwa v2, v238, sext(v2) dst_sel:DWORD dst_unused:UNUSED_PAD src0_sel:DWORD src1_sel:BYTE_0
	s_mov_b64 s[6:7], s[100:101]
	v_and_b32_e32 v12, 32, v9
	v_bfe_i32 v9, v2, 0, 16
	v_add_lshl_u32 v5, v12, v9, 1
	v_lshl_add_u32 v2, v11, 11, v5
	v_lshl_add_u32 v202, v10, 11, v5
	v_bfe_i32 v5, v6, 27, 1
	s_mul_i32 s86, s3, 0x280000
	v_lshrrev_b32_e32 v5, 22, v5
	s_lshl_b64 s[8:9], s[86:87], 1
	v_add_u32_e32 v5, v3, v5
	s_waitcnt lgkmcnt(0)
	s_add_u32 s3, s6, s8
	v_and_b32_e32 v5, 0xfffffc00, v5
	s_addc_u32 s5, s7, s9
	v_sub_u32_e32 v3, v3, v5
	s_add_u32 s38, s3, 0x800000
	v_lshrrev_b32_e32 v5, 4, v3
	v_ashrrev_i32_e32 v11, 31, v6
	s_addc_u32 s39, s5, 0
	s_ashr_i32 s3, s2, 31
	v_bitop3_b32 v3, v5, v3, 32 bitop3:0x6c
	v_lshrrev_b32_e32 v11, 26, v11
	s_lshl_b64 s[2:3], s[2:3], 3
	v_ashrrev_i32_e32 v5, 31, v3
	v_add_u32_e32 v11, v6, v11
	s_add_u32 s2, s0, s2
	v_lshrrev_b32_e32 v5, 26, v5
	v_ashrrev_i32_e32 v11, 6, v11
	s_addc_u32 s3, s1, s3
	s_ashr_i32 s5, s4, 31
	v_add_u32_e32 v5, v3, v5
	v_lshlrev_b32_e32 v13, 3, v11
	s_lshl_b64 s[4:5], s[4:5], 3
	v_ashrrev_i32_e32 v10, 6, v5
	v_and_b32_e32 v13, -16, v13
	s_add_u32 s4, s0, s4
	v_add_u32_e32 v13, v10, v13
	s_addc_u32 s5, s1, s5
	s_ashr_i32 s13, s10, 6
	v_lshrrev_b32_e32 v14, 2, v13
	v_lshlrev_b32_e32 v15, 1, v13
	v_and_b32_e32 v5, 0xc0, v5
	s_ashr_i32 s12, s10, 8
	s_lshl_b32 s6, s13, 10
	v_and_b32_e32 v12, 3, v10
	v_and_b32_e32 v14, 4, v14
	v_and_b32_e32 v15, 0x1fffd8, v15
	v_sub_u32_e32 v3, v3, v5
	v_readlane_b32 s8, v253, 19
	v_or3_b32 v14, v12, v14, v15
	v_lshlrev_b32_e32 v12, 5, v11
	v_ashrrev_i16_sdwa v3, v238, sext(v3) dst_sel:DWORD dst_unused:UNUSED_PAD src0_sel:DWORD src1_sel:BYTE_0
	v_readlane_b32 s9, v253, 20
	s_add_u32 s22, s38, s8
	v_and_b32_e32 v15, 32, v12
	v_bfe_i32 v12, v3, 0, 16
	s_addc_u32 s23, s39, s9
	s_add_i32 s40, s6, 0
	v_add_lshl_u32 v3, v15, v12, 1
	s_add_i32 s41, s40, 0x10000
	s_add_i32 s42, s40, 0x12000
	v_lshl_add_u32 v204, v14, 11, v3
	s_mov_b32 m0, s41
	s_add_u32 s6, s22, 0x10000
	global_load_lds_dwordx4 v204, s[22:23]
	s_mov_b32 m0, s42
	s_addc_u32 s7, s23, 0
	s_add_i32 s43, s40, 0x14000
	global_load_lds_dwordx4 v2, s[22:23]
	s_mov_b32 m0, s43
	s_add_i32 s44, s40, 0x16000
	global_load_lds_dwordx4 v204, s[6:7]
	s_mov_b32 m0, s44
	v_lshl_add_u32 v206, v13, 11, v3
	global_load_lds_dwordx4 v2, s[6:7]
	v_readlane_b32 s6, v253, 15
	v_readlane_b32 s7, v253, 16
	s_add_u32 s24, s36, s6
	s_addc_u32 s25, s37, s7
	s_add_i32 s45, s40, 0x2000
	s_mov_b32 m0, s40
	s_add_u32 s6, s24, 0x40000
	global_load_lds_dwordx4 v206, s[24:25]
	s_mov_b32 m0, s45
	s_addc_u32 s7, s25, 0
	s_add_i32 s46, s40, 0x4000
	v_mov_b32_e32 v205, v4
	global_load_lds_dwordx4 v202, s[24:25]
	s_mov_b32 m0, s46
	s_add_i32 s47, s40, 0x6000
	v_lshl_add_u64 v[14:15], s[22:23], 0, v[204:205]
	v_mov_b32_e32 v3, v4
	global_load_lds_dwordx4 v206, s[6:7]
	s_mov_b32 m0, s47
	s_add_i32 s48, s40, 0x18000
	v_lshl_add_u64 v[16:17], s[22:23], 0, v[2:3]
	v_mov_b32_e32 v207, v4
	global_load_lds_dwordx4 v202, s[6:7]
	v_lshl_add_u64 v[14:15], v[14:15], 0, s[68:69]
	s_mov_b32 m0, s48
	s_add_i32 s49, s40, 0x1a000
	v_lshl_add_u64 v[18:19], s[24:25], 0, v[206:207]
	v_mov_b32_e32 v203, v4
	global_load_lds_dwordx4 v[14:15], off
	v_lshl_add_u64 v[14:15], v[16:17], 0, s[68:69]
	s_mov_b32 m0, s49
	s_add_i32 s50, s40, 0x8000
	s_add_i32 s51, s40, 0xa000
	v_lshl_add_u64 v[20:21], s[24:25], 0, v[202:203]
	global_load_lds_dwordx4 v[14:15], off
	v_lshl_add_u64 v[14:15], v[18:19], 0, s[68:69]
	s_mov_b32 m0, s50
	s_add_u32 s6, s22, 0x10080
	global_load_lds_dwordx4 v[14:15], off
	v_lshl_add_u64 v[14:15], v[20:21], 0, s[68:69]
	s_mov_b32 m0, s51
	s_addc_u32 s7, s23, 0
	s_add_i32 s52, s40, 0x1c000
	global_load_lds_dwordx4 v[14:15], off
	s_mov_b32 m0, s52
	s_add_i32 s53, s40, 0x1e000
	global_load_lds_dwordx4 v204, s[6:7]
	s_mov_b32 m0, s53
	s_cmp_eq_u32 s12, 1
	global_load_lds_dwordx4 v2, s[6:7]
	s_mov_b64 s[8:9], s[100:101]
	s_mov_b64 s[6:7], s[100:101]
	s_cselect_b64 s[2:3], -1, 0
	s_cmp_lg_u32 s12, 1
	s_cbranch_scc1 .LBB0_486
	s_barrier

.LBB0_514:
	s_cmp_eq_u32 s46, 0
	s_cselect_b64 s[2:3], -1, 0
	s_cmp_lg_u32 s46, 0
	s_cbranch_scc1 .LBB0_534
	v_readlane_b32 s10, v253, 21
	s_mov_b32 s8, s87
	s_mov_b32 s6, s87
	s_mov_b32 s4, s87
	v_mov_b32_e32 v5, v0
	v_readlane_b32 s11, v253, 22
	s_movk_i32 s12, 0x400
	v_readfirstlane_b32 s20, v5
	s_andn2_b64 vcc, exec, s[10:11]
	s_cbranch_vccnz .LBB0_534
	v_lshlrev_b32_e32 v3, 4, v5
	v_add_u32_e32 v2, 0x2000, v3
	v_ashrrev_i32_e32 v6, 31, v2
	v_lshrrev_b32_e32 v6, 22, v6
	v_add_u32_e32 v6, v2, v6
	v_ashrrev_i32_e32 v134, 10, v6
	v_mul_i32_i24_e32 v6, 0x400, v134
	v_sub_u32_e32 v2, v2, v6
	v_lshrrev_b32_e32 v6, 4, v2
	s_ashr_i32 s9, s8, 31
	v_bitop3_b32 v2, v6, v2, 32 bitop3:0x6c
	s_lshl_b64 s[8:9], s[8:9], 3
	v_ashrrev_i32_e32 v6, 31, v2
	s_add_u32 s8, s0, s8
	v_lshrrev_b32_e32 v6, 26, v6
	s_addc_u32 s9, s1, s9
	v_add_u32_e32 v6, v2, v6
	v_lshlrev_b32_e32 v8, 3, v134
	s_load_dwordx2 s[8:9], s[8:9], 0xd0
	v_ashrrev_i32_e32 v135, 6, v6
	v_and_b32_e32 v8, -16, v8
	v_add_u32_e32 v8, v135, v8
	v_lshrrev_b32_e32 v9, 2, v8
	v_lshlrev_b32_e32 v10, 1, v8
	v_and_b32_e32 v6, 0xc0, v6
	v_and_b32_e32 v7, 3, v135
	v_and_b32_e32 v9, 4, v9
	v_and_b32_e32 v10, 0x1fffd8, v10
	v_sub_u32_e32 v2, v2, v6
	v_or3_b32 v7, v7, v9, v10
	v_lshlrev_b32_e32 v9, 5, v134
	v_ashrrev_i16_sdwa v2, v238, sext(v2) dst_sel:DWORD dst_unused:UNUSED_PAD src0_sel:DWORD src1_sel:BYTE_0
	s_waitcnt lgkmcnt(0)
	s_add_u32 s8, s8, s80
	v_and_b32_e32 v9, 32, v9
	v_bfe_i32 v136, v2, 0, 16
	s_addc_u32 s9, s9, 0
	s_ashr_i32 s7, s6, 31
	v_add_lshl_u32 v6, v9, v136, 1
	s_lshl_b64 s[6:7], s[6:7], 3
	v_lshl_add_u32 v2, v7, 11, v6
	v_lshl_add_u32 v198, v8, 11, v6
	v_bfe_i32 v6, v5, 27, 1
	s_add_u32 s10, s0, s6
	v_lshrrev_b32_e32 v6, 22, v6
	s_addc_u32 s11, s1, s7
	s_ashr_i32 s5, s4, 31
	v_add_u32_e32 v6, v3, v6
	s_lshl_b64 s[4:5], s[4:5], 3
	v_and_b32_e32 v6, 0xfffffc00, v6
	s_add_u32 s4, s0, s4
	v_sub_u32_e32 v3, v3, v6
	s_addc_u32 s5, s1, s5
	v_lshrrev_b32_e32 v6, 4, v3
	v_ashrrev_i32_e32 v8, 31, v5
	s_mov_b64 s[10:11], s[100:101]
	s_nop 0
	s_load_dwordx2 s[4:5], s[4:5], 0xd0
	v_bitop3_b32 v3, v6, v3, 32 bitop3:0x6c
	v_lshrrev_b32_e32 v8, 26, v8
	v_ashrrev_i32_e32 v6, 31, v3
	v_add_u32_e32 v8, v5, v8
	s_ashr_i32 s7, s20, 6
	v_lshrrev_b32_e32 v6, 26, v6
	v_ashrrev_i32_e32 v138, 6, v8
	s_ashr_i32 s6, s20, 8
	s_lshl_b32 s13, s7, 10
	v_add_u32_e32 v6, v3, v6
	v_lshlrev_b32_e32 v8, 3, v138
	v_readlane_b32 s14, v253, 24
	v_ashrrev_i32_e32 v137, 6, v6
	v_and_b32_e32 v8, -16, v8
	v_readlane_b32 s15, v253, 25
	s_waitcnt lgkmcnt(0)
	s_add_u32 s10, s10, s14
	v_add_u32_e32 v8, v137, v8
	s_addc_u32 s11, s11, s15
	v_readlane_b32 s14, v253, 23
	v_lshrrev_b32_e32 v9, 2, v8
	v_lshlrev_b32_e32 v10, 1, v8
	v_and_b32_e32 v6, 0xc0, v6
	s_add_u32 s16, s10, s14
	v_and_b32_e32 v7, 3, v137
	v_and_b32_e32 v9, 4, v9
	v_and_b32_e32 v10, 0x1fffd8, v10
	v_sub_u32_e32 v3, v3, v6
	s_addc_u32 s17, s11, 0
	v_or3_b32 v7, v7, v9, v10
	v_lshlrev_b32_e32 v9, 5, v138
	v_ashrrev_i16_sdwa v3, v238, sext(v3) dst_sel:DWORD dst_unused:UNUSED_PAD src0_sel:DWORD src1_sel:BYTE_0
	s_add_u32 s10, s16, 0x6600000
	v_and_b32_e32 v9, 32, v9
	v_bfe_i32 v139, v3, 0, 16
	s_addc_u32 s11, s17, 0
	s_add_i32 s22, s13, 0
	v_add_lshl_u32 v3, v9, v139, 1
	s_add_i32 s23, s22, 0x10000
	s_add_i32 s24, s22, 0x12000
	v_lshl_add_u32 v200, v7, 11, v3
	s_mov_b32 m0, s23
	s_add_u32 s14, s16, 0x6610000
	global_load_lds_dwordx4 v200, s[10:11]
	s_mov_b32 m0, s24
	s_addc_u32 s15, s17, 0
	s_add_i32 s25, s22, 0x14000
	global_load_lds_dwordx4 v2, s[10:11]
	s_mov_b32 m0, s25
	s_add_i32 s26, s22, 0x16000
	global_load_lds_dwordx4 v200, s[14:15]
	s_mov_b32 m0, s26
	s_add_i32 s27, s22, 0x2000
	v_lshl_add_u32 v202, v8, 11, v3
	global_load_lds_dwordx4 v2, s[14:15]
	s_mov_b32 m0, s22
	s_add_u32 s14, s8, 0x40000
	global_load_lds_dwordx4 v202, s[8:9]
	s_mov_b32 m0, s27
	s_addc_u32 s15, s9, 0
	s_add_i32 s28, s22, 0x4000
	v_mov_b32_e32 v201, v4
	global_load_lds_dwordx4 v198, s[8:9]
	s_mov_b32 m0, s28
	s_add_i32 s29, s22, 0x6000
	v_lshl_add_u64 v[6:7], s[10:11], 0, v[200:201]
	v_mov_b32_e32 v3, v4
	global_load_lds_dwordx4 v202, s[14:15]
	s_mov_b32 m0, s29
	s_add_i32 s30, s22, 0x18000
	v_lshl_add_u64 v[8:9], s[10:11], 0, v[2:3]
	v_mov_b32_e32 v203, v4
	global_load_lds_dwordx4 v198, s[14:15]
	v_lshl_add_u64 v[6:7], v[6:7], 0, s[68:69]
	s_mov_b32 m0, s30
	s_add_i32 s31, s22, 0x1a000
	v_lshl_add_u64 v[10:11], s[8:9], 0, v[202:203]
	v_mov_b32_e32 v199, v4
	global_load_lds_dwordx4 v[6:7], off
	v_lshl_add_u64 v[6:7], v[8:9], 0, s[68:69]
	s_mov_b32 m0, s31
	s_add_i32 s34, s22, 0x8000
	s_add_i32 s35, s22, 0xa000
	v_lshl_add_u64 v[12:13], s[8:9], 0, v[198:199]
	global_load_lds_dwordx4 v[6:7], off
	v_lshl_add_u64 v[6:7], v[10:11], 0, s[68:69]
	s_mov_b32 m0, s34
	s_add_u32 s14, s16, 0x6610080
	global_load_lds_dwordx4 v[6:7], off
	v_lshl_add_u64 v[6:7], v[12:13], 0, s[68:69]
	s_mov_b32 m0, s35
	s_addc_u32 s15, s17, 0
	s_add_i32 s36, s22, 0x1c000
	global_load_lds_dwordx4 v[6:7], off
	s_mov_b32 m0, s36
	s_add_i32 s37, s22, 0x1e000
	global_load_lds_dwordx4 v200, s[14:15]
	s_mov_b32 m0, s37
	s_cmp_lg_u32 s6, 1
	global_load_lds_dwordx4 v2, s[14:15]
	s_cbranch_scc1 .LBB0_518
	s_barrier

.LBB0_583:
	s_xor_b64 s[4:5], s[6:7], -1
	s_mov_b32 s6, s87
	s_ashr_i32 s7, s6, 31
	s_lshl_b64 s[6:7], s[6:7], 3
	s_add_u32 s6, s0, s6
	s_addc_u32 s7, s1, s7
	s_mov_b64 s[6:7], s[100:101]
	s_mov_b32 s8, 7
	s_mov_b32 s12, 8
	s_mov_b32 s16, s87
	s_waitcnt lgkmcnt(0)
	s_add_u32 s6, s6, s81
	s_addc_u32 s7, s7, 0
	s_add_u32 s6, s6, 0x9600000
	s_addc_u32 s7, s7, 0
	s_ashr_i32 s9, s8, 31
	s_lshl_b64 s[8:9], s[8:9], 3
	s_add_u32 s8, s0, s8
	s_addc_u32 s9, s1, s9
	s_load_dwordx2 s[8:9], s[8:9], 0x0
	s_mov_b32 s18, s87
	v_mov_b32_e32 v125, v0
	v_mov_b32_e32 v3, v4
	s_waitcnt lgkmcnt(0)
	s_add_u32 s8, s8, s2
	s_addc_u32 s9, s9, s3
	s_ashr_i32 s13, s12, 31
	s_lshl_b64 s[12:13], s[12:13], 3
	s_add_u32 s12, s0, s12
	s_addc_u32 s13, s1, s13
	s_load_dwordx2 s[12:13], s[12:13], 0x0
	s_waitcnt vmcnt(7)
	v_mov_b64_e32 v[78:79], s[6:7]
	v_mov_b32_e32 v121, v4
	s_waitcnt lgkmcnt(0)
	s_add_u32 s12, s12, s2
	s_addc_u32 s13, s13, s3
	s_ashr_i32 s17, s16, 31
	s_lshl_b64 s[16:17], s[16:17], 3
	s_add_u32 s16, s0, s16
	s_addc_u32 s17, s1, s17
	s_mov_b64 s[16:17], s[100:101]
	s_waitcnt lgkmcnt(0)
	s_add_u32 s16, s16, s81
	s_addc_u32 s17, s17, 0
	s_ashr_i32 s19, s18, 31
	s_lshl_b64 s[18:19], s[18:19], 3
	s_add_u32 s18, s0, s18
	s_addc_u32 s19, s1, s19
	s_mov_b64 s[18:19], s[100:101]
	s_waitcnt lgkmcnt(0)
	s_add_u32 s18, s18, s85
	v_lshlrev_b32_e32 v139, 3, v125
	v_and_b32_e32 v48, 0x78, v139
	v_bfe_u32 v129, v125, 4, 2
	v_lshlrev_b32_e32 v2, 2, v48
	s_addc_u32 s19, s19, 0
	global_load_dwordx4 v[6:9], v2, s[12:13] offset:16
	global_load_dwordx4 v[10:13], v2, s[12:13]
	v_lshlrev_b32_e32 v2, 5, v129
	s_lshl_b32 s12, s14, 1
	global_load_dwordx4 v[14:17], v2, s[8:9]
	global_load_dwordx4 v[18:21], v2, s[8:9] offset:16
	global_load_dwordx4 v[22:25], v2, s[8:9] offset:128
	global_load_dwordx4 v[26:29], v2, s[8:9] offset:144
	global_load_dwordx4 v[30:33], v2, s[8:9] offset:256
	global_load_dwordx4 v[34:37], v2, s[8:9] offset:272
	global_load_dwordx4 v[38:41], v2, s[8:9] offset:384
	global_load_dwordx4 v[42:45], v2, s[8:9] offset:400
	v_sub_co_u32_e64 v2, s[8:9], s55, 1
	s_add_i32 s58, s12, 7
	s_ashr_i32 s10, s11, 2
	v_lshlrev_b32_e32 v2, s58, v2
	s_and_b32 s20, s11, 3
	s_ashr_i32 s11, s10, 31
	v_add_u32_e32 v2, s56, v2
	v_ashrrev_i32_e32 v122, 4, v125
	s_lshl_b64 s[46:47], s[10:11], 12
	v_cndmask_b32_e64 v2, v2, 0, s[8:9]
	v_ashrrev_i32_e32 v123, 31, v122
	v_lshl_add_u64 v[54:55], s[46:47], 0, v[2:3]
	v_lshlrev_b64 v[110:111], s12, v[122:123]
	v_lshl_add_u64 v[2:3], v[110:111], 0, v[54:55]
	v_mad_u64_u32 v[46:47], s[10:11], v2, s77, v[78:79]
	v_mad_i32_i24 v47, v3, s77, v47
	s_lshl_b32 s86, s20, 8
	v_lshl_add_u64 v[46:47], v[46:47], 0, s[86:87]
	v_lshlrev_b32_e32 v2, 1, v48
	v_mov_b32_e32 v3, v4
	v_lshl_add_u64 v[50:51], v[46:47], 0, v[2:3]
	global_load_dwordx4 v[46:49], v[50:51], off offset:1024
	s_nop 0
	global_load_dwordx4 v[50:53], v[50:51], off offset:2048
	v_lshlrev_b32_e32 v132, 1, v122
	v_and_b32_e32 v151, 15, v125
	v_lshlrev_b32_e32 v123, 8, v122
	v_xor_b32_e32 v124, v122, v125
	v_and_b32_e32 v132, 12, v132
	s_lshl_b32 s57, 0x80, s12
	v_lshlrev_b32_e32 v124, 4, v124
	v_and_b32_e32 v124, 0xf0, v124
	v_and_b32_e32 v120, 48, v125
	v_add_u32_e32 v124, 0, v124
	v_ashrrev_i32_e32 v5, 6, v125
	v_lshrrev_b32_e32 v126, 4, v125
	v_cmp_gt_i32_e64 s[22:23], 7, v5
	v_cmp_gt_i32_e64 s[24:25], 6, v5
	v_cmp_gt_i32_e64 s[26:27], 5, v5
	v_cmp_gt_i32_e64 s[28:29], 4, v5
	v_cmp_gt_i32_e64 s[30:31], 3, v5
	v_cmp_gt_i32_e64 s[34:35], 2, v5
	v_cmp_gt_i32_e64 s[36:37], 1, v5
	v_cmp_gt_i32_e64 s[38:39], 0, v5
	s_waitcnt vmcnt(1)
	v_cndmask_b32_e64 v131, v46, 0, s[8:9]
	v_add_u32_e32 v46, 32, v122
	v_cndmask_b32_e64 v128, v47, 0, s[8:9]
	v_ashrrev_i32_e32 v47, 31, v46
	v_lshlrev_b64 v[112:113], s12, v[46:47]
	v_lshl_add_u64 v[46:47], v[112:113], 0, v[54:55]
	v_cndmask_b32_e64 v127, v49, 0, s[8:9]
	v_cndmask_b32_e64 v130, v48, 0, s[8:9]
	v_mad_u64_u32 v[48:49], s[10:11], v46, s77, v[78:79]
	v_mad_i32_i24 v49, v47, s77, v49
	v_lshl_add_u64 v[46:47], v[48:49], 0, s[86:87]
	s_waitcnt vmcnt(0)
	v_cndmask_b32_e64 v103, v51, 0, s[8:9]
	v_cndmask_b32_e64 v102, v50, 0, s[8:9]
	v_lshl_add_u64 v[50:51], v[46:47], 0, v[2:3]
	v_cndmask_b32_e64 v105, v53, 0, s[8:9]
	v_cndmask_b32_e64 v104, v52, 0, s[8:9]
	global_load_dwordx4 v[46:49], v[50:51], off offset:1024
	s_nop 0
	global_load_dwordx4 v[50:53], v[50:51], off offset:2048
	v_and_b32_e32 v135, 0xffff0000, v130
	v_and_b32_e32 v134, 0xffff0000, v131
	v_and_b32_e32 v141, 0xffff0000, v127
	v_and_b32_e32 v140, 0xffff0000, v128
	v_lshlrev_b32_e32 v133, 16, v130
	v_lshlrev_b32_e32 v137, 16, v127
	v_lshlrev_b32_e32 v136, 16, v128
	v_pk_mul_f32 v[142:143], v[140:141], v[140:141]
	s_waitcnt vmcnt(1)
	v_cndmask_b32_e64 v146, v46, 0, s[8:9]
	v_add_u32_e32 v46, 64, v122
	v_cndmask_b32_e64 v144, v47, 0, s[8:9]
	v_ashrrev_i32_e32 v47, 31, v46
	v_lshlrev_b64 v[114:115], s12, v[46:47]
	v_lshl_add_u64 v[46:47], v[114:115], 0, v[54:55]
	v_cndmask_b32_e64 v138, v49, 0, s[8:9]
	v_cndmask_b32_e64 v145, v48, 0, s[8:9]
	v_mad_u64_u32 v[48:49], s[10:11], v46, s77, v[78:79]
	v_mad_i32_i24 v49, v47, s77, v49
	v_lshl_add_u64 v[46:47], v[48:49], 0, s[86:87]
	s_waitcnt vmcnt(0)
	v_cndmask_b32_e64 v99, v51, 0, s[8:9]
	v_cndmask_b32_e64 v98, v50, 0, s[8:9]
	v_lshl_add_u64 v[50:51], v[46:47], 0, v[2:3]
	v_cndmask_b32_e64 v101, v53, 0, s[8:9]
	v_cndmask_b32_e64 v100, v52, 0, s[8:9]
	global_load_dwordx4 v[46:49], v[50:51], off offset:1024
	s_nop 0
	global_load_dwordx4 v[50:53], v[50:51], off offset:2048
	v_pk_fma_f32 v[142:143], v[136:137], v[136:137], v[142:143]
	s_waitcnt vmcnt(1)
	v_cndmask_b32_e64 v150, v46, 0, s[8:9]
	v_add_u32_e32 v46, 0x60, v122
	v_cndmask_b32_e64 v148, v47, 0, s[8:9]
	v_ashrrev_i32_e32 v47, 31, v46
	v_lshlrev_b64 v[116:117], s12, v[46:47]
	v_lshl_add_u64 v[46:47], v[116:117], 0, v[54:55]
	v_cndmask_b32_e64 v147, v49, 0, s[8:9]
	v_cndmask_b32_e64 v149, v48, 0, s[8:9]
	v_mad_u64_u32 v[48:49], s[10:11], v46, s77, v[78:79]
	v_mad_i32_i24 v49, v47, s77, v49
	v_lshl_add_u64 v[46:47], v[48:49], 0, s[86:87]
	s_waitcnt vmcnt(0)
	v_cndmask_b32_e64 v95, v51, 0, s[8:9]
	v_cndmask_b32_e64 v94, v50, 0, s[8:9]
	v_lshl_add_u64 v[50:51], v[46:47], 0, v[2:3]
	v_cndmask_b32_e64 v97, v53, 0, s[8:9]
	v_cndmask_b32_e64 v96, v52, 0, s[8:9]
	global_load_dwordx4 v[46:49], v[50:51], off offset:1024
	s_nop 0
	global_load_dwordx4 v[50:53], v[50:51], off offset:2048
	v_and_b32_e32 v122, 1, v122
	v_bitop3_b32 v122, v132, v151, v122 bitop3:0x36
	v_lshlrev_b32_e32 v132, 16, v131
	v_pk_mul_f32 v[130:131], v[134:135], v[134:135]
	s_waitcnt vmcnt(1)
	v_cndmask_b32_e64 v152, v49, 0, s[8:9]
	v_pk_fma_f32 v[130:131], v[132:133], v[132:133], v[130:131]
	s_waitcnt vmcnt(0)
	v_cndmask_b32_e64 v109, v53, 0, s[8:9]
	v_cndmask_b32_e64 v108, v52, 0, s[8:9]
	v_cndmask_b32_e64 v107, v51, 0, s[8:9]
	v_cndmask_b32_e64 v106, v50, 0, s[8:9]
	v_cndmask_b32_e64 v153, v47, 0, s[8:9]
	v_cndmask_b32_e64 v154, v48, 0, s[8:9]
	v_cndmask_b32_e64 v155, v46, 0, s[8:9]
	s_lshl_b32 s8, s55, s58
	v_pk_add_f32 v[130:131], v[130:131], v[142:143]
	v_ashrrev_i32_e32 v46, 2, v125
	s_add_i32 s8, s8, s56
	v_add_f32_e32 v127, v130, v131
	v_bfi_b32 v46, -16, v46, v125
	s_add_u32 s8, s46, s8
	v_add_f32_dpp v127, v127, v127 row_ror:8 row_mask:0xf bank_mask:0xf bound_ctrl:1
	v_ashrrev_i32_e32 v47, 31, v46
	s_addc_u32 s9, s47, 0
	v_add_f32_dpp v127, v127, v127 row_ror:4 row_mask:0xf bank_mask:0xf bound_ctrl:1
	v_lshlrev_b64 v[118:119], s12, v[46:47]
	v_lshl_add_u64 v[46:47], v[110:111], 0, s[8:9]
	v_add_f32_dpp v127, v127, v127 row_ror:2 row_mask:0xf bank_mask:0xf bound_ctrl:1
	v_mad_u64_u32 v[48:49], s[10:11], v46, s77, v[78:79]
	s_nop 0
	v_add_f32_dpp v127, v127, v127 row_ror:1 row_mask:0xf bank_mask:0xf bound_ctrl:1
	v_mad_i32_i24 v49, v47, s77, v49
	v_fmamk_f32 v127, v127, 0x3c000000, v236
	v_lshl_add_u64 v[46:47], v[48:49], 0, s[86:87]
	v_rsq_f32_e32 v127, v127
	v_lshl_add_u64 v[50:51], v[46:47], 0, v[2:3]
	global_load_dwordx4 v[46:49], v[50:51], off offset:1024
	s_nop 0
	global_load_dwordx4 v[50:53], v[50:51], off offset:2048
	v_lshl_add_u64 v[54:55], v[112:113], 0, s[8:9]
	v_mul_f32_e32 v128, v127, v132
	v_mul_f32_e32 v130, v127, v134
	v_mul_f32_e32 v128, v10, v128
	v_mul_f32_e32 v130, v11, v130
	v_cvt_pk_bf16_f32 v130, v128, v130
	v_mul_f32_e32 v128, v127, v136
	v_mul_f32_e32 v131, v127, v140
	v_mul_f32_e32 v128, v12, v128
	v_mul_f32_e32 v131, v13, v131
	v_lshl_add_u64 v[62:63], v[114:115], 0, s[8:9]
	v_lshl_add_u64 v[70:71], v[116:117], 0, s[8:9]
	v_lshl_add_u64 v[80:81], v[118:119], 0, s[8:9]
	v_cvt_pk_bf16_f32 v131, v128, v131
	v_mul_f32_e32 v128, v127, v133
	v_mul_f32_e32 v132, v127, v135
	v_mad_u64_u32 v[56:57], s[10:11], v54, s77, v[78:79]
	v_mad_u64_u32 v[64:65], s[10:11], v62, s77, v[78:79]
	v_mad_u64_u32 v[72:73], s[10:11], v70, s77, v[78:79]
	v_mad_u64_u32 v[78:79], s[8:9], v80, s77, v[78:79]
	v_mul_f32_e32 v128, v6, v128
	v_mul_f32_e32 v132, v7, v132
	v_mad_i32_i24 v57, v55, s77, v57
	v_mad_i32_i24 v65, v63, s77, v65
	v_mad_i32_i24 v73, v71, s77, v73
	v_mad_i32_i24 v79, v81, s77, v79
	v_cvt_pk_bf16_f32 v132, v128, v132
	v_mul_f32_e32 v128, v127, v137
	v_mul_f32_e32 v127, v127, v141
	v_lshl_add_u64 v[54:55], v[56:57], 0, s[86:87]
	v_lshl_add_u64 v[62:63], v[64:65], 0, s[86:87]
	v_lshl_add_u64 v[70:71], v[72:73], 0, s[86:87]
	v_lshl_add_u64 v[78:79], v[78:79], 0, s[86:87]
	s_add_i32 s54, 0, 0x10000
	v_mul_f32_e32 v127, v9, v127
	v_lshl_add_u64 v[58:59], v[54:55], 0, v[2:3]
	v_lshl_add_u64 v[66:67], v[62:63], 0, v[2:3]
	v_lshl_add_u64 v[74:75], v[70:71], 0, v[2:3]
	v_lshl_add_u64 v[90:91], v[78:79], 0, v[120:121]
	v_lshl_add_u32 v122, v122, 4, s54
	v_mul_f32_e32 v128, v8, v128
	v_cvt_pk_bf16_f32 v133, v128, v127
	v_add_u32_e32 v127, v124, v123
	global_load_dwordx4 v[54:57], v[58:59], off offset:1024
	s_nop 0
	global_load_dwordx4 v[58:61], v[58:59], off offset:2048
	s_nop 0
	global_load_dwordx4 v[62:65], v[66:67], off offset:1024
	s_nop 0
	global_load_dwordx4 v[66:69], v[66:67], off offset:2048
	s_nop 0
	global_load_dwordx4 v[70:73], v[74:75], off offset:1024
	s_nop 0
	global_load_dwordx4 v[74:77], v[74:75], off offset:2048
	s_nop 0
	global_load_dwordx4 v[78:81], v[90:91], off
	global_load_dwordx4 v[82:85], v[90:91], off offset:64
	global_load_dwordx4 v[86:89], v[90:91], off offset:128
	s_nop 0
	global_load_dwordx4 v[90:93], v[90:91], off offset:192
	ds_write_b128 v127, v[130:133] offset:32768
	v_add_u32_e32 v128, v122, v123
	v_and_b32_e32 v131, 0xffff0000, v145
	v_and_b32_e32 v130, 0xffff0000, v146
	v_and_b32_e32 v135, 0xffff0000, v138
	v_and_b32_e32 v134, 0xffff0000, v144
	ds_write_b128 v128, v[102:105] offset:32768
	v_lshlrev_b32_e32 v105, 16, v145
	v_lshlrev_b32_e32 v104, 16, v146
	v_lshlrev_b32_e32 v133, 16, v138
	v_lshlrev_b32_e32 v132, 16, v144
	v_pk_mul_f32 v[102:103], v[130:131], v[130:131]
	v_pk_mul_f32 v[136:137], v[134:135], v[134:135]
	v_pk_fma_f32 v[102:103], v[104:105], v[104:105], v[102:103]
	v_pk_fma_f32 v[136:137], v[132:133], v[132:133], v[136:137]
	s_add_i32 s59, s55, s15
	v_pk_add_f32 v[102:103], v[102:103], v[136:137]
	s_add_u32 s50, s6, s86
	v_add_f32_e32 v102, v102, v103
	s_addc_u32 s51, s7, 0
	s_add_u32 s6, s16, s86
	v_add_f32_dpp v102, v102, v102 row_ror:8 row_mask:0xf bank_mask:0xf bound_ctrl:1
	s_addc_u32 s7, s17, 0
	s_lshl_b32 s10, s14, 18
	v_add_f32_dpp v102, v102, v102 row_ror:4 row_mask:0xf bank_mask:0xf bound_ctrl:1
	s_lshl_b32 s11, s20, 16
	s_lshl_b32 s86, s14, 12
	v_add_f32_dpp v102, v102, v102 row_ror:2 row_mask:0xf bank_mask:0xf bound_ctrl:1
	s_or_b32 s10, s11, s10
	s_add_u32 s10, s18, s10
	v_add_f32_dpp v102, v102, v102 row_ror:1 row_mask:0xf bank_mask:0xf bound_ctrl:1
	v_fmamk_f32 v102, v102, 0x3c000000, v236
	v_rsq_f32_e32 v136, v102
	s_addc_u32 s11, s19, 0
	v_cmp_eq_u32_e64 s[8:9], 0, v129
	s_add_u32 s48, s10, 0x400000
	v_mul_f32_e32 v102, v136, v104
	v_mul_f32_e32 v103, v136, v130
	v_mul_f32_e32 v102, v10, v102
	v_mul_f32_e32 v103, v11, v103
	v_cvt_pk_bf16_f32 v102, v102, v103
	v_mul_f32_e32 v103, v136, v132
	v_mul_f32_e32 v104, v136, v134
	v_mul_f32_e32 v103, v12, v103
	v_mul_f32_e32 v104, v13, v104
	v_cvt_pk_bf16_f32 v103, v103, v104
	v_mul_f32_e32 v104, v136, v105
	v_mul_f32_e32 v105, v136, v131
	v_mul_f32_e32 v104, v6, v104
	v_mul_f32_e32 v105, v7, v105
	v_cvt_pk_bf16_f32 v104, v104, v105
	v_mul_f32_e32 v105, v136, v133
	v_mul_f32_e32 v105, v8, v105
	v_mul_f32_e32 v130, v136, v135
	v_mul_f32_e32 v130, v9, v130
	v_cvt_pk_bf16_f32 v105, v105, v130
	ds_write_b128 v127, v[102:105] offset:40960
	ds_write_b128 v128, v[98:101] offset:40960
	v_and_b32_e32 v103, 0xffff0000, v149
	v_and_b32_e32 v102, 0xffff0000, v150
	v_and_b32_e32 v131, 0xffff0000, v147
	v_and_b32_e32 v130, 0xffff0000, v148
	v_lshlrev_b32_e32 v101, 16, v149
	v_lshlrev_b32_e32 v100, 16, v150
	v_lshlrev_b32_e32 v105, 16, v147
	v_lshlrev_b32_e32 v104, 16, v148
	v_pk_mul_f32 v[98:99], v[102:103], v[102:103]
	v_pk_mul_f32 v[132:133], v[130:131], v[130:131]
	v_pk_fma_f32 v[98:99], v[100:101], v[100:101], v[98:99]
	v_pk_fma_f32 v[132:133], v[104:105], v[104:105], v[132:133]
	s_addc_u32 s49, s11, 0
	v_pk_add_f32 v[98:99], v[98:99], v[132:133]
	s_lshl_b32 s60, s55, 7
	v_add_f32_e32 v98, v98, v99
	v_cmp_gt_i32_e64 s[14:15], 8, v5
	v_and_b32_e32 v138, 8, v139
	v_add_f32_dpp v98, v98, v98 row_ror:8 row_mask:0xf bank_mask:0xf bound_ctrl:1
	v_bitop3_b32 v139, v139, 8, v139 bitop3:0xc
	s_sub_i32 s61, 0, s60
	v_add_f32_dpp v98, v98, v98 row_ror:4 row_mask:0xf bank_mask:0xf bound_ctrl:1
	s_nop 1
	v_add_f32_dpp v98, v98, v98 row_ror:2 row_mask:0xf bank_mask:0xf bound_ctrl:1
	s_nop 1
	v_add_f32_dpp v98, v98, v98 row_ror:1 row_mask:0xf bank_mask:0xf bound_ctrl:1
	v_fmamk_f32 v98, v98, 0x3c000000, v236
	v_rsq_f32_e32 v132, v98
	s_nop 0
	v_mul_f32_e32 v98, v132, v100
	v_mul_f32_e32 v99, v132, v102
	v_mul_f32_e32 v98, v10, v98
	v_mul_f32_e32 v99, v11, v99
	v_cvt_pk_bf16_f32 v98, v98, v99
	v_mul_f32_e32 v99, v132, v104
	v_mul_f32_e32 v100, v132, v130
	v_mul_f32_e32 v99, v12, v99
	v_mul_f32_e32 v100, v13, v100
	v_cvt_pk_bf16_f32 v99, v99, v100
	v_mul_f32_e32 v100, v132, v101
	v_mul_f32_e32 v101, v132, v103
	v_mul_f32_e32 v100, v6, v100
	v_mul_f32_e32 v101, v7, v101
	v_cvt_pk_bf16_f32 v100, v100, v101
	v_mul_f32_e32 v101, v132, v105
	v_mul_f32_e32 v101, v8, v101
	v_mul_f32_e32 v102, v132, v131
	v_mul_f32_e32 v102, v9, v102
	v_cvt_pk_bf16_f32 v101, v101, v102
	ds_write_b128 v127, v[98:101] offset:49152
	ds_write_b128 v128, v[94:97] offset:49152
	v_and_b32_e32 v99, 0xffff0000, v154
	v_and_b32_e32 v98, 0xffff0000, v155
	v_and_b32_e32 v103, 0xffff0000, v152
	v_and_b32_e32 v102, 0xffff0000, v153
	v_lshlrev_b32_e32 v97, 16, v154
	v_lshlrev_b32_e32 v96, 16, v155
	v_lshlrev_b32_e32 v101, 16, v152
	v_lshlrev_b32_e32 v100, 16, v153
	v_pk_mul_f32 v[94:95], v[98:99], v[98:99]
	v_pk_mul_f32 v[104:105], v[102:103], v[102:103]
	v_pk_fma_f32 v[94:95], v[96:97], v[96:97], v[94:95]
	v_pk_fma_f32 v[104:105], v[100:101], v[100:101], v[104:105]
	s_nop 0
	v_pk_add_f32 v[94:95], v[94:95], v[104:105]
	s_nop 0
	v_add_f32_e32 v94, v94, v95
	s_nop 1
	v_add_f32_dpp v94, v94, v94 row_ror:8 row_mask:0xf bank_mask:0xf bound_ctrl:1
	s_nop 1
	v_add_f32_dpp v94, v94, v94 row_ror:4 row_mask:0xf bank_mask:0xf bound_ctrl:1
	s_nop 1
	v_add_f32_dpp v94, v94, v94 row_ror:2 row_mask:0xf bank_mask:0xf bound_ctrl:1
	s_nop 1
	v_add_f32_dpp v94, v94, v94 row_ror:1 row_mask:0xf bank_mask:0xf bound_ctrl:1
	v_fmamk_f32 v94, v94, 0x3c000000, v236
	v_rsq_f32_e32 v104, v94
	s_nop 0
	v_mul_f32_e32 v94, v104, v96
	v_mul_f32_e32 v95, v104, v98
	v_mul_f32_e32 v94, v10, v94
	v_mul_f32_e32 v95, v11, v95
	v_cvt_pk_bf16_f32 v94, v94, v95
	v_mul_f32_e32 v95, v104, v100
	v_mul_f32_e32 v96, v104, v102
	v_mul_f32_e32 v95, v12, v95
	v_mul_f32_e32 v96, v13, v96
	v_cvt_pk_bf16_f32 v95, v95, v96
	v_mul_f32_e32 v96, v104, v97
	v_mul_f32_e32 v97, v104, v99
	v_mul_f32_e32 v96, v6, v96
	v_mul_f32_e32 v97, v7, v97
	v_cvt_pk_bf16_f32 v96, v96, v97
	v_mul_f32_e32 v97, v104, v101
	v_mul_f32_e32 v98, v104, v103
	v_mul_f32_e32 v97, v8, v97
	v_mul_f32_e32 v98, v9, v98
	v_cvt_pk_bf16_f32 v97, v97, v98
	s_waitcnt vmcnt(11)
	v_and_b32_e32 v99, 0xffff0000, v48
	v_and_b32_e32 v98, 0xffff0000, v46
	v_and_b32_e32 v103, 0xffff0000, v49
	v_and_b32_e32 v102, 0xffff0000, v47
	ds_write_b128 v127, v[94:97] offset:57344
	ds_write_b128 v128, v[106:109] offset:57344
	v_lshlrev_b32_e32 v97, 16, v48
	v_lshlrev_b32_e32 v96, 16, v46
	v_lshlrev_b32_e32 v101, 16, v49
	v_lshlrev_b32_e32 v100, 16, v47
	v_pk_mul_f32 v[94:95], v[98:99], v[98:99]
	v_pk_mul_f32 v[104:105], v[102:103], v[102:103]
	v_pk_fma_f32 v[94:95], v[96:97], v[96:97], v[94:95]
	v_pk_fma_f32 v[104:105], v[100:101], v[100:101], v[104:105]
	s_nop 0
	v_pk_add_f32 v[94:95], v[94:95], v[104:105]
	s_nop 0
	v_add_f32_e32 v94, v94, v95
	s_nop 1
	v_add_f32_dpp v94, v94, v94 row_ror:8 row_mask:0xf bank_mask:0xf bound_ctrl:1
	s_nop 1
	v_add_f32_dpp v94, v94, v94 row_ror:4 row_mask:0xf bank_mask:0xf bound_ctrl:1
	s_nop 1
	v_add_f32_dpp v94, v94, v94 row_ror:2 row_mask:0xf bank_mask:0xf bound_ctrl:1
	s_nop 1
	v_add_f32_dpp v94, v94, v94 row_ror:1 row_mask:0xf bank_mask:0xf bound_ctrl:1
	v_fmamk_f32 v94, v94, 0x3c000000, v236
	v_rsq_f32_e32 v104, v94
	s_nop 0
	v_mul_f32_e32 v94, v104, v96
	v_mul_f32_e32 v95, v104, v98
	v_mul_f32_e32 v94, v10, v94
	v_mul_f32_e32 v95, v11, v95
	v_cvt_pk_bf16_f32 v94, v94, v95
	v_mul_f32_e32 v95, v104, v100
	v_mul_f32_e32 v96, v104, v102
	v_mul_f32_e32 v95, v12, v95
	v_mul_f32_e32 v96, v13, v96
	v_cvt_pk_bf16_f32 v95, v95, v96
	v_mul_f32_e32 v96, v104, v97
	v_mul_f32_e32 v97, v104, v99
	v_mul_f32_e32 v96, v6, v96
	v_mul_f32_e32 v97, v7, v97
	v_cvt_pk_bf16_f32 v96, v96, v97
	v_mul_f32_e32 v97, v104, v101
	v_mul_f32_e32 v98, v104, v103
	v_mul_f32_e32 v97, v8, v97
	v_mul_f32_e32 v98, v9, v98
	v_cvt_pk_bf16_f32 v97, v97, v98
	s_waitcnt vmcnt(9)
	v_and_b32_e32 v99, 0xffff0000, v56
	v_and_b32_e32 v98, 0xffff0000, v54
	v_and_b32_e32 v103, 0xffff0000, v57
	v_and_b32_e32 v102, 0xffff0000, v55
	ds_write_b128 v127, v[94:97]
	ds_write_b128 v128, v[50:53]
	v_lshlrev_b32_e32 v97, 16, v56
	v_lshlrev_b32_e32 v96, 16, v54
	v_lshlrev_b32_e32 v101, 16, v57
	v_lshlrev_b32_e32 v100, 16, v55
	v_pk_mul_f32 v[94:95], v[98:99], v[98:99]
	v_pk_mul_f32 v[104:105], v[102:103], v[102:103]
	v_pk_fma_f32 v[94:95], v[96:97], v[96:97], v[94:95]
	v_pk_fma_f32 v[104:105], v[100:101], v[100:101], v[104:105]
	s_nop 0
	v_pk_add_f32 v[94:95], v[94:95], v[104:105]
	s_nop 0
	v_add_f32_e32 v94, v94, v95
	s_nop 1
	v_add_f32_dpp v94, v94, v94 row_ror:8 row_mask:0xf bank_mask:0xf bound_ctrl:1
	s_nop 1
	v_add_f32_dpp v94, v94, v94 row_ror:4 row_mask:0xf bank_mask:0xf bound_ctrl:1
	s_nop 1
	v_add_f32_dpp v94, v94, v94 row_ror:2 row_mask:0xf bank_mask:0xf bound_ctrl:1
	s_nop 1
	v_add_f32_dpp v94, v94, v94 row_ror:1 row_mask:0xf bank_mask:0xf bound_ctrl:1
	v_fmamk_f32 v94, v94, 0x3c000000, v236
	v_rsq_f32_e32 v104, v94
	s_nop 0
	v_mul_f32_e32 v94, v104, v96
	v_mul_f32_e32 v95, v104, v98
	v_mul_f32_e32 v94, v10, v94
	v_mul_f32_e32 v95, v11, v95
	v_cvt_pk_bf16_f32 v94, v94, v95
	v_mul_f32_e32 v95, v104, v100
	v_mul_f32_e32 v96, v104, v102
	v_mul_f32_e32 v95, v12, v95
	v_mul_f32_e32 v96, v13, v96
	v_cvt_pk_bf16_f32 v95, v95, v96
	v_mul_f32_e32 v96, v104, v97
	v_mul_f32_e32 v97, v104, v99
	v_mul_f32_e32 v96, v6, v96
	v_mul_f32_e32 v97, v7, v97
	v_cvt_pk_bf16_f32 v96, v96, v97
	v_mul_f32_e32 v97, v104, v101
	v_mul_f32_e32 v98, v104, v103
	v_mul_f32_e32 v97, v8, v97
	v_mul_f32_e32 v98, v9, v98
	v_cvt_pk_bf16_f32 v97, v97, v98
	s_waitcnt vmcnt(7)
	v_and_b32_e32 v99, 0xffff0000, v64
	v_and_b32_e32 v98, 0xffff0000, v62
	v_and_b32_e32 v103, 0xffff0000, v65
	v_and_b32_e32 v102, 0xffff0000, v63
	ds_write_b128 v127, v[94:97] offset:8192
	ds_write_b128 v128, v[58:61] offset:8192
	v_lshlrev_b32_e32 v97, 16, v64
	v_lshlrev_b32_e32 v96, 16, v62
	v_lshlrev_b32_e32 v101, 16, v65
	v_lshlrev_b32_e32 v100, 16, v63
	v_pk_mul_f32 v[94:95], v[98:99], v[98:99]
	v_pk_mul_f32 v[104:105], v[102:103], v[102:103]
	v_pk_fma_f32 v[94:95], v[96:97], v[96:97], v[94:95]
	v_pk_fma_f32 v[104:105], v[100:101], v[100:101], v[104:105]
	s_nop 0
	v_pk_add_f32 v[94:95], v[94:95], v[104:105]
	s_nop 0
	v_add_f32_e32 v94, v94, v95
	s_nop 1
	v_add_f32_dpp v94, v94, v94 row_ror:8 row_mask:0xf bank_mask:0xf bound_ctrl:1
	s_nop 1
	v_add_f32_dpp v94, v94, v94 row_ror:4 row_mask:0xf bank_mask:0xf bound_ctrl:1
	s_nop 1
	v_add_f32_dpp v94, v94, v94 row_ror:2 row_mask:0xf bank_mask:0xf bound_ctrl:1
	s_nop 1
	v_add_f32_dpp v94, v94, v94 row_ror:1 row_mask:0xf bank_mask:0xf bound_ctrl:1
	v_fmamk_f32 v94, v94, 0x3c000000, v236
	v_rsq_f32_e32 v104, v94
	s_nop 0
	v_mul_f32_e32 v94, v104, v96
	v_mul_f32_e32 v95, v104, v98
	v_mul_f32_e32 v94, v10, v94
	v_mul_f32_e32 v95, v11, v95
	v_cvt_pk_bf16_f32 v94, v94, v95
	v_mul_f32_e32 v95, v104, v100
	v_mul_f32_e32 v96, v104, v102
	v_mul_f32_e32 v95, v12, v95
	v_mul_f32_e32 v96, v13, v96
	v_cvt_pk_bf16_f32 v95, v95, v96
	v_mul_f32_e32 v96, v104, v97
	v_mul_f32_e32 v97, v104, v99
	v_mul_f32_e32 v96, v6, v96
	v_mul_f32_e32 v97, v7, v97
	v_cvt_pk_bf16_f32 v96, v96, v97
	v_mul_f32_e32 v97, v104, v101
	v_mul_f32_e32 v98, v104, v103
	v_mul_f32_e32 v97, v8, v97
	v_mul_f32_e32 v98, v9, v98
	v_cvt_pk_bf16_f32 v97, v97, v98
	s_waitcnt vmcnt(5)
	v_and_b32_e32 v99, 0xffff0000, v72
	v_and_b32_e32 v98, 0xffff0000, v70
	v_and_b32_e32 v103, 0xffff0000, v73
	v_and_b32_e32 v102, 0xffff0000, v71
	ds_write_b128 v127, v[94:97] offset:16384
	ds_write_b128 v128, v[66:69] offset:16384
	v_lshlrev_b32_e32 v97, 16, v72
	v_lshlrev_b32_e32 v96, 16, v70
	v_lshlrev_b32_e32 v101, 16, v73
	v_lshlrev_b32_e32 v100, 16, v71
	v_pk_mul_f32 v[94:95], v[98:99], v[98:99]
	v_pk_mul_f32 v[104:105], v[102:103], v[102:103]
	v_pk_fma_f32 v[94:95], v[96:97], v[96:97], v[94:95]
	v_pk_fma_f32 v[104:105], v[100:101], v[100:101], v[104:105]
	s_nop 0
	v_pk_add_f32 v[94:95], v[94:95], v[104:105]
	s_nop 0
	v_add_f32_e32 v94, v94, v95
	s_nop 1
	v_add_f32_dpp v94, v94, v94 row_ror:8 row_mask:0xf bank_mask:0xf bound_ctrl:1
	s_nop 1
	v_add_f32_dpp v94, v94, v94 row_ror:4 row_mask:0xf bank_mask:0xf bound_ctrl:1
	s_nop 1
	v_add_f32_dpp v94, v94, v94 row_ror:2 row_mask:0xf bank_mask:0xf bound_ctrl:1
	s_nop 1
	v_add_f32_dpp v94, v94, v94 row_ror:1 row_mask:0xf bank_mask:0xf bound_ctrl:1
	v_fmamk_f32 v94, v94, 0x3c000000, v236
	v_rsq_f32_e32 v104, v94
	s_nop 0
	v_mul_f32_e32 v94, v104, v96
	v_mul_f32_e32 v95, v104, v98
	v_mul_f32_e32 v94, v10, v94
	v_mul_f32_e32 v95, v11, v95
	v_cvt_pk_bf16_f32 v94, v94, v95
	v_mul_f32_e32 v95, v104, v100
	v_mul_f32_e32 v96, v104, v102
	v_mul_f32_e32 v95, v12, v95
	v_mul_f32_e32 v96, v13, v96
	v_cvt_pk_bf16_f32 v95, v95, v96
	v_mul_f32_e32 v96, v104, v97
	v_mul_f32_e32 v97, v104, v99
	v_mul_f32_e32 v96, v6, v96
	v_mul_f32_e32 v97, v7, v97
	v_cvt_pk_bf16_f32 v96, v96, v97
	v_mul_f32_e32 v97, v104, v101
	v_mul_f32_e32 v97, v8, v97
	v_mul_f32_e32 v98, v104, v103
	v_mul_f32_e32 v98, v9, v98
	v_cvt_pk_bf16_f32 v97, v97, v98
	ds_write_b128 v127, v[94:97] offset:24576
	s_waitcnt vmcnt(4)
	ds_write_b128 v128, v[74:77] offset:24576
	v_lshlrev_b32_e32 v96, 4, v5
	v_or_b32_e32 v94, v96, v151
	v_ashrrev_i32_e32 v95, 31, v94
	v_lshlrev_b32_e32 v97, 2, v129
	v_lshlrev_b64 v[94:95], s12, v[94:95]
	v_or_b32_e32 v108, 1, v97
	v_lshl_add_u64 v[102:103], v[94:95], 0, s[46:47]
	v_lshlrev_b32_e32 v94, 4, v129
	v_mov_b32_e32 v95, v4
	v_add_u32_e32 v153, 0x80, v96
	v_cmp_lt_u32_e64 s[16:17], v108, v151
	v_or_b32_e32 v108, 2, v97
	v_or_b32_e32 v109, 3, v97
	v_lshl_add_u64 v[94:95], s[6:7], 0, v[94:95]
	s_mov_b64 s[6:7], 0xaa00000
	v_add_u32_e32 v154, 0x70, v96
	v_cmp_lt_u32_e64 s[18:19], v108, v151
	v_cmp_lt_u32_e64 s[20:21], v109, v151
	v_cmp_gt_u32_e64 s[42:43], v108, v151
	v_cmp_gt_u32_e64 s[44:45], v109, v151
	v_lshl_add_u64 v[108:109], s[50:51], 0, v[2:3]
	v_and_b32_e32 v2, 0xffffff80, v153
	v_lshl_add_u64 v[106:107], v[94:95], 0, s[6:7]
	v_and_b32_e32 v94, 16, v125
	v_add_u32_e32 v155, 0x60, v96
	v_and_b32_e32 v137, 0x70, v153
	v_add_u32_e32 v153, 0xffffff80, v2
	v_and_b32_e32 v2, 0xffffff80, v154
	v_cmp_eq_u32_e64 s[6:7], 0, v94
	v_bitop3_b32 v94, v126, v151, 3 bitop3:0x6c
	v_add_u32_e32 v101, 0x50, v96
	v_and_b32_e32 v136, 0x70, v154
	v_add_u32_e32 v154, 0xffffff80, v2
	v_and_b32_e32 v2, 0xffffff80, v155
	v_lshlrev_b32_e32 v126, 4, v94
	v_bitop3_b32 v94, v129, v151, 4 bitop3:0x36
	v_add_u32_e32 v100, 64, v96
	v_and_b32_e32 v135, 0x70, v155
	v_add_u32_e32 v155, 0xffffff80, v2
	v_and_b32_e32 v2, 0xffffff80, v101
	v_lshlrev_b32_e32 v127, 4, v94
	v_bitop3_b32 v94, v129, v151, 8 bitop3:0x36
	v_add_u32_e32 v99, 48, v96
	v_add_u32_e32 v156, 0xffffff80, v2
	v_and_b32_e32 v2, 0xffffff80, v100
	v_lshlrev_b32_e32 v128, 4, v94
	v_bitop3_b32 v94, v129, v151, 12 bitop3:0x36
	v_add_u32_e32 v95, 32, v96
	v_add_u32_e32 v157, 0xffffff80, v2
	v_and_b32_e32 v2, 0xffffff80, v99
	v_lshlrev_b32_e32 v129, 4, v94
	v_add_u32_e32 v94, 16, v96
	v_add_u32_e32 v158, 0xffffff80, v2
	v_and_b32_e32 v2, 0xffffff80, v95
	v_add_u32_e32 v159, 0xffffff80, v2
	v_and_b32_e32 v2, 0xffffff80, v94
	v_lshl_add_u64 v[104:105], s[50:51], 0, v[120:121]
	v_bfe_u32 v98, v125, 2, 2
	v_and_b32_e32 v120, 3, v125
	v_and_b32_e32 v125, 0x70, v96
	v_and_b32_e32 v130, 0x70, v94
	v_and_b32_e32 v131, 0x70, v95
	v_and_b32_e32 v132, 0x70, v99
	v_and_b32_e32 v133, 0x70, v100
	v_and_b32_e32 v134, 0x70, v101
	v_add_u32_e32 v160, 0xffffff80, v2
	v_and_b32_e32 v2, 0xffffff80, v96
	s_lshl_b32 s50, s55, 15
	v_bfe_u32 v121, v151, 2, 1
	v_cmp_gt_u32_e64 s[10:11], v97, v151
	v_cmp_lt_u32_e64 s[12:13], v97, v151
	v_cmp_ge_u32_e64 s[40:41], v97, v151
	v_or_b32_e32 v140, 4, v120
	v_or_b32_e32 v141, 8, v120
	v_or_b32_e32 v142, 12, v120
	v_or_b32_e32 v143, v125, v151
	v_or_b32_e32 v144, v130, v151
	v_or_b32_e32 v145, v131, v151
	v_or_b32_e32 v146, v151, v132
	v_or_b32_e32 v147, v133, v151
	v_or_b32_e32 v148, v151, v134
	v_or_b32_e32 v149, v135, v151
	v_or_b32_e32 v150, v151, v136
	v_or_b32_e32 v151, v137, v151
	v_or_b32_e32 v152, v97, v98
	v_add_u32_e32 v161, 0xffffff80, v2
	s_add_i32 s62, s50, 0x8000
	s_branch .LBB0_585

.LBB0_594:
	s_lshl_b32 s2, s37, 14
	s_and_b32 s2, s2, 0xc000
	s_or_b32 s8, s2, s36
	s_lshl_b32 s2, s37, 7
	s_ashr_i32 s14, s37, 7
	s_and_b32 s40, s2, 0x180
	s_mov_b32 s2, 0
	s_ashr_i32 s15, s14, 31
	s_bfe_u32 s39, s37, 0x50002
	s_ashr_i32 s3, s2, 31
	s_lshl_b32 s38, s39, 7
	s_lshl_b64 s[12:13], s[14:15], 12
	s_lshl_b64 s[2:3], s[2:3], 3
	s_add_u32 s2, s0, s2
	s_addc_u32 s3, s1, s3
	s_mov_b64 s[2:3], s[100:101]
	s_mov_b32 s6, 10
	s_mov_b32 s16, 14
	s_mov_b32 s18, 0
	s_mov_b32 s20, 0
	s_waitcnt lgkmcnt(0)
	s_add_u32 s2, s2, s81
	s_addc_u32 s3, s3, 0
	s_add_u32 s30, s2, 0x9600000
	s_mov_b32 s2, 9
	s_addc_u32 s31, s3, 0
	s_ashr_i32 s3, s2, 31
	s_lshl_b64 s[2:3], s[2:3], 3
	s_add_u32 s2, s0, s2
	s_addc_u32 s3, s1, s3
	s_load_dwordx2 s[2:3], s[2:3], 0x0
	s_mov_b32 s22, 0
	s_waitcnt vmcnt(13)
	v_mov_b32_e32 v56, v0
	v_mov_b32_e32 v7, v4
	s_waitcnt lgkmcnt(0)
	s_add_u32 s2, s2, s4
	s_addc_u32 s3, s3, s5
	s_ashr_i32 s7, s6, 31
	s_lshl_b64 s[6:7], s[6:7], 3
	s_add_u32 s6, s0, s6
	s_addc_u32 s7, s1, s7
	s_load_dwordx2 s[6:7], s[6:7], 0x0
	v_mov_b64_e32 v[46:47], s[30:31]
	v_mov_b32_e32 v49, v4
	v_mov_b32_e32 v19, v4
	v_mov_b32_e32 v21, v4
	s_waitcnt lgkmcnt(0)
	s_add_u32 s34, s6, s10
	s_mov_b32 s6, 0
	s_addc_u32 s35, s7, s11
	s_ashr_i32 s7, s6, 31
	s_lshl_b64 s[6:7], s[6:7], 3
	s_add_u32 s6, s0, s6
	s_addc_u32 s7, s1, s7
	s_mov_b64 s[6:7], s[100:101]
	s_lshl_b32 s15, s8, 1
	s_mov_b32 s8, 0
	v_mov_b32_e32 v23, v4
	s_waitcnt lgkmcnt(0)
	s_add_u32 s6, s6, s15
	s_addc_u32 s7, s7, 0
	s_ashr_i32 s9, s8, 31
	s_lshl_b64 s[8:9], s[8:9], 3
	s_add_u32 s8, s0, s8
	s_addc_u32 s9, s1, s9
	s_mov_b64 s[8:9], s[100:101]
	v_mov_b32_e32 v111, 1.0
	v_mov_b32_e32 v109, 0
	s_waitcnt lgkmcnt(0)
	s_add_u32 s24, s8, s15
	s_mov_b32 s8, 12
	s_addc_u32 s25, s9, 0
	s_ashr_i32 s9, s8, 31
	s_lshl_b64 s[8:9], s[8:9], 3
	s_add_u32 s8, s0, s8
	s_addc_u32 s9, s1, s9
	s_load_dwordx2 s[8:9], s[8:9], 0x0
	s_mov_b32 s15, 0
	s_waitcnt lgkmcnt(0)
	s_add_u32 s8, s8, s10
	s_addc_u32 s9, s9, s11
	s_ashr_i32 s17, s16, 31
	s_lshl_b64 s[16:17], s[16:17], 3
	s_add_u32 s16, s0, s16
	s_addc_u32 s17, s1, s17
	s_load_dwordx2 s[16:17], s[16:17], 0x0
	s_waitcnt lgkmcnt(0)
	s_add_u32 s26, s16, s10
	s_mov_b32 s16, 15
	s_addc_u32 s27, s17, s11
	s_ashr_i32 s17, s16, 31
	s_lshl_b64 s[16:17], s[16:17], 3
	s_add_u32 s16, s0, s16
	s_addc_u32 s17, s1, s17
	s_load_dwordx2 s[16:17], s[16:17], 0x0
	s_waitcnt lgkmcnt(0)
	s_add_u32 s28, s16, s10
	s_mov_b32 s16, 0
	s_addc_u32 s29, s17, s11
	s_ashr_i32 s17, s16, 31
	s_lshl_b64 s[16:17], s[16:17], 3
	s_add_u32 s16, s0, s16
	s_addc_u32 s17, s1, s17
	s_load_dwordx2 s[16:17], s[16:17], 0xd0
	s_ashr_i32 s19, s18, 31
	s_lshl_b64 s[18:19], s[18:19], 3
	s_add_u32 s18, s0, s18
	s_addc_u32 s19, s1, s19
	s_load_dwordx2 s[18:19], s[18:19], 0xd0
	s_ashr_i32 s21, s20, 31
	s_lshl_b64 s[20:21], s[20:21], 3
	s_add_u32 s20, s0, s20
	s_addc_u32 s21, s1, s21
	s_mov_b64 s[20:21], s[100:101]
	s_ashr_i32 s23, s22, 31
	s_lshl_b64 s[22:23], s[22:23], 3
	s_add_u32 s22, s0, s22
	s_addc_u32 s23, s1, s23
	s_mov_b64 s[22:23], s[100:101]
	s_waitcnt vmcnt(9)
	v_ashrrev_i32_e32 v70, 4, v56
	v_add_u32_e32 v54, s38, v70
	v_max_i32_e32 v3, 3, v54
	v_lshlrev_b32_e32 v2, 3, v56
	v_add_u32_e32 v6, -3, v3
	v_and_b32_e32 v2, 0x78, v2
	v_lshl_add_u64 v[6:7], s[12:13], 0, v[6:7]
	v_or_b32_e32 v2, s40, v2
	v_mad_u64_u32 v[8:9], s[30:31], v6, s77, v[46:47]
	v_mad_i32_i24 v9, v7, s77, v9
	v_lshlrev_b32_e32 v48, 1, v2
	v_lshlrev_b32_e32 v18, 2, v2
	v_lshl_add_u64 v[6:7], v[8:9], 0, v[48:49]
	v_max_i32_e32 v3, 2, v54
	global_load_dwordx4 v[34:37], v18, s[2:3]
	global_load_dwordx4 v[14:17], v18, s[2:3] offset:2048
	global_load_dwordx4 v[58:61], v[6:7], off offset:3072
	v_add_u32_e32 v6, -2, v3
	v_mov_b32_e32 v7, v4
	v_lshl_add_u64 v[6:7], s[12:13], 0, v[6:7]
	v_mad_u64_u32 v[8:9], s[30:31], v6, s77, v[46:47]
	v_mad_i32_i24 v9, v7, s77, v9
	v_lshl_add_u64 v[6:7], v[8:9], 0, v[48:49]
	global_load_dwordx4 v[62:65], v[6:7], off offset:3072
	global_load_dwordx4 v[26:29], v18, s[34:35]
	global_load_dwordx4 v[42:45], v18, s[2:3] offset:16
	s_nop 0
	global_load_dwordx4 v[6:9], v18, s[2:3] offset:2064
	global_load_dwordx4 v[10:13], v18, s[34:35] offset:16
	v_max_i32_e32 v5, 1, v54
	v_max_i32_e32 v22, 0, v54
	v_add_u32_e32 v20, -1, v5
	v_lshl_add_u64 v[18:19], s[2:3], 0, v[18:19]
	s_mov_b64 s[2:3], 0x1000
	v_lshl_add_u64 v[52:53], s[12:13], 0, v[22:23]
	v_lshl_add_u64 v[50:51], s[12:13], 0, v[20:21]
	v_lshl_add_u64 v[20:21], v[18:19], 0, s[2:3]
	v_add_co_u32_e32 v22, vcc, s88, v18
	s_mov_b64 s[2:3], 0x1800
	s_nop 0
	v_addc_co_u32_e32 v23, vcc, 0, v19, vcc
	v_lshl_add_u64 v[18:19], v[18:19], 0, s[2:3]
	v_mad_u64_u32 v[66:67], s[2:3], v50, s77, v[46:47]
	v_mad_i32_i24 v67, v51, s77, v67
	v_lshl_add_u64 v[50:51], v[66:67], 0, v[48:49]
	global_load_dwordx4 v[38:41], v[22:23], off
	global_load_dwordx4 v[30:33], v[20:21], off offset:16
	s_nop 0
	global_load_dwordx4 v[22:25], v[22:23], off offset:2048
	s_nop 0
	global_load_dwordx4 v[18:21], v[18:19], off offset:16
	v_cmp_lt_i32_e32 vcc, 2, v54
	global_load_dwordx4 v[66:69], v[50:51], off offset:3072
	v_xor_b32_e32 v3, v70, v56
	v_lshlrev_b32_e32 v3, 4, v3
	v_and_b32_e32 v3, 0xf0, v3
	v_add_u32_e32 v57, 0, v3
	s_waitcnt vmcnt(12)
	v_mov_b32_e32 v50, v34
	s_waitcnt vmcnt(11)
	v_mov_b32_e32 v51, v14
	s_waitcnt vmcnt(10)
	v_cndmask_b32_e32 v5, 0, v61, vcc
	v_cndmask_b32_e32 v55, 0, v60, vcc
	v_cndmask_b32_e32 v71, 0, v59, vcc
	v_cndmask_b32_e32 v58, 0, v58, vcc
	v_cmp_lt_i32_e32 vcc, 1, v54
	v_mov_b32_e32 v14, v35
	v_lshlrev_b32_e32 v34, 16, v58
	s_waitcnt vmcnt(9)
	v_cndmask_b32_e32 v59, 0, v62, vcc
	v_lshlrev_b32_e32 v35, 16, v59
	v_pk_mul_f32 v[34:35], v[50:51], v[34:35]
	v_cndmask_b32_e32 v72, 0, v63, vcc
	s_waitcnt vmcnt(8)
	v_add_f32_e32 v34, v26, v34
	v_add_f32_e32 v73, v34, v35
	v_mad_u64_u32 v[34:35], s[2:3], v52, s77, v[46:47]
	v_mad_i32_i24 v35, v53, s77, v35
	v_and_b32_e32 v63, 0xffff0000, v59
	v_and_b32_e32 v62, 0xffff0000, v58
	v_lshl_add_u64 v[34:35], v[34:35], 0, v[48:49]
	global_load_dwordx4 v[58:61], v[34:35], off offset:3072
	v_pk_mul_f32 v[34:35], v[14:15], v[62:63]
	v_mov_b32_e32 v52, v36
	v_add_f32_e32 v34, v27, v34
	v_add_f32_e32 v78, v34, v35
	v_lshlrev_b32_e32 v35, 16, v72
	v_lshlrev_b32_e32 v34, 16, v71
	v_mov_b32_e32 v53, v16
	v_pk_mul_f32 v[34:35], v[52:53], v[34:35]
	v_cndmask_b32_e32 v64, 0, v64, vcc
	v_add_f32_e32 v16, v28, v34
	v_add_f32_e32 v79, v16, v35
	v_and_b32_e32 v35, 0xffff0000, v72
	v_and_b32_e32 v34, 0xffff0000, v71
	v_mov_b32_e32 v16, v37
	v_pk_mul_f32 v[34:35], v[16:17], v[34:35]
	s_waitcnt vmcnt(8)
	v_mov_b32_e32 v36, v42
	v_add_f32_e32 v34, v29, v34
	v_add_f32_e32 v71, v34, v35
	v_lshlrev_b32_e32 v35, 16, v64
	v_lshlrev_b32_e32 v34, 16, v55
	s_waitcnt vmcnt(7)
	v_mov_b32_e32 v37, v6
	v_pk_mul_f32 v[34:35], v[36:37], v[34:35]
	v_cndmask_b32_e32 v65, 0, v65, vcc
	s_waitcnt vmcnt(6)
	v_add_f32_e32 v6, v10, v34
	v_add_f32_e32 v80, v6, v35
	v_and_b32_e32 v35, 0xffff0000, v64
	v_and_b32_e32 v34, 0xffff0000, v55
	v_mov_b32_e32 v6, v43
	v_pk_mul_f32 v[34:35], v[6:7], v[34:35]
	v_lshlrev_b32_e32 v43, 16, v65
	v_add_f32_e32 v34, v11, v34
	v_add_f32_e32 v81, v34, v35
	v_lshlrev_b32_e32 v42, 16, v5
	v_mov_b32_e32 v34, v44
	v_mov_b32_e32 v35, v8
	v_pk_mul_f32 v[42:43], v[34:35], v[42:43]
	v_ashrrev_i32_e32 v55, 31, v54
	v_add_f32_e32 v8, v12, v42
	v_add_f32_e32 v82, v8, v43
	v_and_b32_e32 v43, 0xffff0000, v65
	v_and_b32_e32 v42, 0xffff0000, v5
	v_mov_b32_e32 v8, v45
	v_pk_mul_f32 v[42:43], v[8:9], v[42:43]
	v_add_u32_e32 v72, 32, v70
	v_add_f32_e32 v5, v13, v42
	v_add_f32_e32 v5, v5, v43
	v_lshl_add_u64 v[42:43], s[12:13], 0, v[54:55]
	v_mad_u64_u32 v[44:45], s[2:3], v42, s77, v[46:47]
	v_mad_i32_i24 v45, v43, s77, v45
	v_lshl_add_u64 v[42:43], v[44:45], 0, v[48:49]
	v_add_u32_e32 v44, s38, v72
	v_max_i32_e32 v45, 3, v44
	v_add_u32_e32 v62, -3, v45
	v_mov_b32_e32 v63, v4
	v_lshl_add_u64 v[62:63], s[12:13], 0, v[62:63]
	v_mad_u64_u32 v[64:65], s[2:3], v62, s77, v[46:47]
	v_add_co_u32_e32 v42, vcc, s88, v42
	v_mad_i32_i24 v65, v63, s77, v65
	s_nop 0
	v_addc_co_u32_e32 v43, vcc, 0, v43, vcc
	v_lshl_add_u64 v[74:75], v[64:65], 0, v[48:49]
	global_load_dwordx4 v[62:65], v[42:43], off
	s_nop 0
	global_load_dwordx4 v[74:77], v[74:75], off offset:3072
	v_max_i32_e32 v42, 2, v44
	v_add_u32_e32 v42, -2, v42
	v_mov_b32_e32 v43, v4
	v_cmp_lt_i32_e32 vcc, 0, v54
	v_lshl_add_u64 v[42:43], s[12:13], 0, v[42:43]
	s_waitcnt vmcnt(3)
	v_cndmask_b32_e32 v84, 0, v67, vcc
	v_cndmask_b32_e32 v85, 0, v66, vcc
	v_mad_u64_u32 v[66:67], s[2:3], v42, s77, v[46:47]
	v_mad_i32_i24 v67, v43, s77, v67
	v_lshl_add_u64 v[42:43], v[66:67], 0, v[48:49]
	v_cndmask_b32_e32 v45, 0, v69, vcc
	v_cndmask_b32_e32 v83, 0, v68, vcc
	global_load_dwordx4 v[66:69], v[42:43], off offset:3072
	v_cmp_lt_i32_e32 vcc, -1, v54
	v_lshlrev_b32_e32 v54, 16, v85
	v_mov_b32_e32 v42, v38
	s_waitcnt vmcnt(3)
	v_cndmask_b32_e32 v58, 0, v58, vcc
	v_lshlrev_b32_e32 v55, 16, v58
	v_mov_b32_e32 v43, v22
	v_pk_mul_f32 v[54:55], v[42:43], v[54:55]
	v_cndmask_b32_e32 v59, 0, v59, vcc
	v_add_f32_e32 v22, v73, v54
	v_add_f32_e32 v73, v22, v55
	v_and_b32_e32 v55, 0xffff0000, v58
	v_and_b32_e32 v54, 0xffff0000, v85
	v_mov_b32_e32 v22, v39
	v_pk_mul_f32 v[38:39], v[22:23], v[54:55]
	v_lshlrev_b32_e32 v55, 16, v59
	v_add_f32_e32 v38, v78, v38
	v_add_f32_e32 v58, v38, v39
	v_lshlrev_b32_e32 v54, 16, v84
	v_mov_b32_e32 v38, v40
	v_mov_b32_e32 v39, v24
	v_pk_mul_f32 v[54:55], v[38:39], v[54:55]
	v_cndmask_b32_e32 v60, 0, v60, vcc
	v_add_f32_e32 v24, v79, v54
	v_add_f32_e32 v78, v24, v55
	v_and_b32_e32 v55, 0xffff0000, v59
	v_and_b32_e32 v54, 0xffff0000, v84
	v_mov_b32_e32 v24, v41
	v_pk_mul_f32 v[40:41], v[24:25], v[54:55]
	v_lshlrev_b32_e32 v55, 16, v60
	v_add_f32_e32 v40, v71, v40
	v_add_f32_e32 v59, v40, v41
	v_lshlrev_b32_e32 v54, 16, v83
	v_mov_b32_e32 v40, v30
	v_mov_b32_e32 v41, v18
	v_pk_mul_f32 v[54:55], v[40:41], v[54:55]
	v_cndmask_b32_e32 v61, 0, v61, vcc
	v_add_f32_e32 v18, v80, v54
	v_add_f32_e32 v71, v18, v55
	v_and_b32_e32 v55, 0xffff0000, v60
	v_and_b32_e32 v54, 0xffff0000, v83
	v_mov_b32_e32 v18, v31
	v_pk_mul_f32 v[30:31], v[18:19], v[54:55]
	v_lshlrev_b32_e32 v55, 16, v61
	v_add_f32_e32 v30, v81, v30
	v_add_f32_e32 v60, v30, v31
	v_lshlrev_b32_e32 v54, 16, v45
	v_mov_b32_e32 v30, v32
	v_mov_b32_e32 v31, v20
	v_pk_mul_f32 v[54:55], v[30:31], v[54:55]
	v_cvt_pk_bf16_f32 v58, v73, v58
	v_cvt_pk_bf16_f32 v59, v78, v59
	v_cvt_pk_bf16_f32 v60, v71, v60
	v_cmp_lt_i32_e32 vcc, 2, v44
	v_add_f32_e32 v20, v82, v54
	v_add_f32_e32 v79, v20, v55
	v_and_b32_e32 v55, 0xffff0000, v61
	v_and_b32_e32 v54, 0xffff0000, v45
	v_mov_b32_e32 v20, v33
	v_pk_mul_f32 v[32:33], v[20:21], v[54:55]
	s_waitcnt vmcnt(1)
	v_cndmask_b32_e32 v71, 0, v77, vcc
	v_add_f32_e32 v5, v5, v32
	v_add_f32_e32 v5, v5, v33
	v_cvt_pk_bf16_f32 v61, v79, v5
	v_lshlrev_b32_e32 v5, 8, v70
	v_add_u32_e32 v32, v57, v5
	ds_write_b128 v32, v[58:61]
	ds_write_b128 v32, v[62:65] offset:32768
	v_max_i32_e32 v32, 1, v44
	v_add_u32_e32 v32, -1, v32
	v_mov_b32_e32 v33, v4
	v_lshl_add_u64 v[32:33], s[12:13], 0, v[32:33]
	v_mad_u64_u32 v[54:55], s[2:3], v32, s77, v[46:47]
	v_mad_i32_i24 v55, v33, s77, v55
	v_lshl_add_u64 v[32:33], v[54:55], 0, v[48:49]
	global_load_dwordx4 v[58:61], v[32:33], off offset:3072
	v_max_i32_e32 v32, 0, v44
	v_mov_b32_e32 v33, v4
	v_lshl_add_u64 v[32:33], s[12:13], 0, v[32:33]
	v_mad_u64_u32 v[54:55], s[2:3], v32, s77, v[46:47]
	v_mad_i32_i24 v55, v33, s77, v55
	v_lshl_add_u64 v[32:33], v[54:55], 0, v[48:49]
	global_load_dwordx4 v[62:65], v[32:33], off offset:3072
	v_cndmask_b32_e32 v45, 0, v76, vcc
	v_cndmask_b32_e32 v73, 0, v75, vcc
	v_cndmask_b32_e32 v74, 0, v74, vcc
	v_cmp_lt_i32_e32 vcc, 1, v44
	v_lshlrev_b32_e32 v32, 16, v74
	s_waitcnt vmcnt(2)
	v_cndmask_b32_e32 v55, 0, v66, vcc
	v_lshlrev_b32_e32 v33, 16, v55
	v_pk_mul_f32 v[32:33], v[50:51], v[32:33]
	v_cndmask_b32_e32 v54, 0, v67, vcc
	v_add_f32_e32 v32, v26, v32
	v_add_f32_e32 v84, v32, v33
	v_and_b32_e32 v33, 0xffff0000, v55
	v_and_b32_e32 v32, 0xffff0000, v74
	v_pk_mul_f32 v[32:33], v[14:15], v[32:33]
	v_cndmask_b32_e32 v68, 0, v68, vcc
	v_add_f32_e32 v32, v27, v32
	v_add_f32_e32 v85, v32, v33
	v_lshlrev_b32_e32 v33, 16, v54
	v_lshlrev_b32_e32 v32, 16, v73
	v_pk_mul_f32 v[32:33], v[52:53], v[32:33]
	v_cndmask_b32_e32 v75, 0, v69, vcc
	v_add_f32_e32 v32, v28, v32
	v_add_f32_e32 v86, v32, v33
	v_and_b32_e32 v33, 0xffff0000, v54
	v_and_b32_e32 v32, 0xffff0000, v73
	v_pk_mul_f32 v[32:33], v[16:17], v[32:33]
	v_add_u32_e32 v74, 64, v70
	v_add_f32_e32 v32, v29, v32
	v_add_f32_e32 v73, v32, v33
	v_lshlrev_b32_e32 v33, 16, v68
	v_lshlrev_b32_e32 v32, 16, v45
	v_pk_mul_f32 v[32:33], v[36:37], v[32:33]
	s_nop 0
	v_add_f32_e32 v32, v10, v32
	v_add_f32_e32 v87, v32, v33
	v_and_b32_e32 v32, 0xffff0000, v45
	v_ashrrev_i32_e32 v45, 31, v44
	v_lshl_add_u64 v[54:55], s[12:13], 0, v[44:45]
	v_mad_u64_u32 v[66:67], s[2:3], v54, s77, v[46:47]
	v_mad_i32_i24 v67, v55, s77, v67
	v_lshl_add_u64 v[54:55], v[66:67], 0, v[48:49]
	v_add_co_u32_e32 v54, vcc, s88, v54
	v_and_b32_e32 v33, 0xffff0000, v68
	s_nop 0
	v_addc_co_u32_e32 v55, vcc, 0, v55, vcc
	global_load_dwordx4 v[66:69], v[54:55], off
	v_pk_mul_f32 v[32:33], v[6:7], v[32:33]
	v_mov_b32_e32 v55, v4
	v_add_f32_e32 v32, v11, v32
	v_add_f32_e32 v88, v32, v33
	v_lshlrev_b32_e32 v33, 16, v75
	v_lshlrev_b32_e32 v32, 16, v71
	v_pk_mul_f32 v[32:33], v[34:35], v[32:33]
	v_cmp_lt_i32_e32 vcc, 0, v44
	v_add_f32_e32 v89, v12, v32
	v_add_u32_e32 v32, s38, v74
	v_max_i32_e32 v45, 3, v32
	v_add_u32_e32 v54, -3, v45
	v_lshl_add_u64 v[54:55], s[12:13], 0, v[54:55]
	v_mad_u64_u32 v[76:77], s[2:3], v54, s77, v[46:47]
	v_mad_i32_i24 v77, v55, s77, v77
	v_lshl_add_u64 v[54:55], v[76:77], 0, v[48:49]
	v_max_i32_e32 v45, 2, v32
	global_load_dwordx4 v[76:79], v[54:55], off offset:3072
	v_add_u32_e32 v54, -2, v45
	v_mov_b32_e32 v55, v4
	v_lshl_add_u64 v[54:55], s[12:13], 0, v[54:55]
	v_mad_u64_u32 v[80:81], s[2:3], v54, s77, v[46:47]
	v_mad_i32_i24 v81, v55, s77, v81
	v_lshl_add_u64 v[54:55], v[80:81], 0, v[48:49]
	global_load_dwordx4 v[80:83], v[54:55], off offset:3072
	v_and_b32_e32 v55, 0xffff0000, v75
	v_and_b32_e32 v54, 0xffff0000, v71
	v_pk_mul_f32 v[54:55], v[8:9], v[54:55]
	s_waitcnt vmcnt(4)
	v_cndmask_b32_e32 v75, 0, v61, vcc
	v_add_f32_e32 v45, v13, v54
	v_add_f32_e32 v71, v45, v55
	v_cndmask_b32_e32 v54, 0, v60, vcc
	v_cndmask_b32_e32 v55, 0, v59, vcc
	v_cndmask_b32_e32 v58, 0, v58, vcc
	v_cmp_lt_i32_e32 vcc, -1, v44
	v_lshlrev_b32_e32 v44, 16, v58
	v_add_f32_e32 v33, v89, v33
	s_waitcnt vmcnt(3)
	v_cndmask_b32_e32 v61, 0, v62, vcc
	v_lshlrev_b32_e32 v45, 16, v61
	v_pk_mul_f32 v[44:45], v[42:43], v[44:45]
	v_cndmask_b32_e32 v60, 0, v63, vcc
	v_add_f32_e32 v44, v84, v44
	v_add_f32_e32 v62, v44, v45
	v_and_b32_e32 v45, 0xffff0000, v61
	v_and_b32_e32 v44, 0xffff0000, v58
	v_pk_mul_f32 v[44:45], v[22:23], v[44:45]
	v_cndmask_b32_e32 v59, 0, v64, vcc
	v_add_f32_e32 v44, v85, v44
	v_add_f32_e32 v63, v44, v45
	v_lshlrev_b32_e32 v45, 16, v60
	v_lshlrev_b32_e32 v44, 16, v55
	v_pk_mul_f32 v[44:45], v[38:39], v[44:45]
	v_cndmask_b32_e32 v65, 0, v65, vcc
	v_add_f32_e32 v44, v86, v44
	v_add_f32_e32 v64, v44, v45
	v_and_b32_e32 v45, 0xffff0000, v60
	v_and_b32_e32 v44, 0xffff0000, v55
	v_pk_mul_f32 v[44:45], v[24:25], v[44:45]
	v_mov_b32_e32 v55, v4
	v_add_f32_e32 v44, v73, v44
	v_add_f32_e32 v73, v44, v45
	v_lshlrev_b32_e32 v45, 16, v59
	v_lshlrev_b32_e32 v44, 16, v54
	v_pk_mul_f32 v[44:45], v[40:41], v[44:45]
	v_cvt_pk_bf16_f32 v62, v62, v63
	v_cvt_pk_bf16_f32 v63, v64, v73
	v_lshlrev_b32_e32 v73, 8, v72
	v_add_f32_e32 v44, v87, v44
	v_add_f32_e32 v84, v44, v45
	v_and_b32_e32 v44, 0xffff0000, v54
	v_max_i32_e32 v54, 1, v32
	v_add_u32_e32 v54, -1, v54
	v_lshl_add_u64 v[54:55], s[12:13], 0, v[54:55]
	v_and_b32_e32 v45, 0xffff0000, v59
	v_mad_u64_u32 v[58:59], s[2:3], v54, s77, v[46:47]
	v_pk_mul_f32 v[44:45], v[18:19], v[44:45]
	v_mad_i32_i24 v59, v55, s77, v59
	v_lshl_add_u64 v[54:55], v[58:59], 0, v[48:49]
	v_add_f32_e32 v44, v88, v44
	global_load_dwordx4 v[58:61], v[54:55], off offset:3072
	v_add_f32_e32 v54, v44, v45
	v_lshlrev_b32_e32 v45, 16, v65
	v_lshlrev_b32_e32 v44, 16, v75
	v_pk_mul_f32 v[44:45], v[30:31], v[44:45]
	v_cvt_pk_bf16_f32 v64, v84, v54
	v_cmp_lt_i32_e32 vcc, 2, v32
	v_add_f32_e32 v33, v33, v44
	v_add_f32_e32 v33, v33, v45
	v_and_b32_e32 v45, 0xffff0000, v65
	v_and_b32_e32 v44, 0xffff0000, v75
	v_pk_mul_f32 v[44:45], v[20:21], v[44:45]
	s_nop 0
	v_add_f32_e32 v44, v71, v44
	v_add_f32_e32 v44, v44, v45
	v_cvt_pk_bf16_f32 v65, v33, v44
	v_max_i32_e32 v44, 0, v32
	v_mov_b32_e32 v45, v4
	v_lshl_add_u64 v[44:45], s[12:13], 0, v[44:45]
	v_mad_u64_u32 v[54:55], s[2:3], v44, s77, v[46:47]
	v_add_u32_e32 v33, v57, v73
	v_mad_i32_i24 v55, v45, s77, v55
	ds_write_b128 v33, v[62:65]
	s_waitcnt vmcnt(3)
	ds_write_b128 v33, v[66:69] offset:32768
	v_lshl_add_u64 v[44:45], v[54:55], 0, v[48:49]
	global_load_dwordx4 v[62:65], v[44:45], off offset:3072
	s_waitcnt vmcnt(3)
	v_cndmask_b32_e32 v33, 0, v79, vcc
	v_cndmask_b32_e32 v66, 0, v78, vcc
	v_cndmask_b32_e32 v67, 0, v77, vcc
	v_cndmask_b32_e32 v68, 0, v76, vcc
	v_cmp_lt_i32_e32 vcc, 1, v32
	v_lshlrev_b32_e32 v44, 16, v68
	v_add_u32_e32 v76, 0x60, v70
	s_waitcnt vmcnt(2)
	v_cndmask_b32_e32 v55, 0, v80, vcc
	v_lshlrev_b32_e32 v45, 16, v55
	v_pk_mul_f32 v[44:45], v[50:51], v[44:45]
	v_cndmask_b32_e32 v54, 0, v81, vcc
	v_add_f32_e32 v44, v26, v44
	v_add_f32_e32 v75, v44, v45
	v_and_b32_e32 v45, 0xffff0000, v55
	v_and_b32_e32 v44, 0xffff0000, v68
	v_pk_mul_f32 v[44:45], v[14:15], v[44:45]
	v_cndmask_b32_e32 v71, 0, v82, vcc
	v_add_f32_e32 v44, v27, v44
	v_add_f32_e32 v77, v44, v45
	v_lshlrev_b32_e32 v45, 16, v54
	v_lshlrev_b32_e32 v44, 16, v67
	v_pk_mul_f32 v[44:45], v[52:53], v[44:45]
	v_cndmask_b32_e32 v69, 0, v83, vcc
	v_add_f32_e32 v44, v28, v44
	v_add_f32_e32 v86, v44, v45
	v_and_b32_e32 v45, 0xffff0000, v54
	v_and_b32_e32 v44, 0xffff0000, v67
	v_pk_mul_f32 v[44:45], v[16:17], v[44:45]
	v_mov_b32_e32 v67, v4
	v_add_f32_e32 v44, v29, v44
	v_add_f32_e32 v87, v44, v45
	v_lshlrev_b32_e32 v45, 16, v71
	v_lshlrev_b32_e32 v44, 16, v66
	v_pk_mul_f32 v[44:45], v[36:37], v[44:45]
	v_cmp_lt_i32_e32 vcc, 0, v32
	v_add_f32_e32 v44, v10, v44
	v_add_f32_e32 v88, v44, v45
	v_and_b32_e32 v45, 0xffff0000, v71
	v_and_b32_e32 v44, 0xffff0000, v66
	v_pk_mul_f32 v[44:45], v[6:7], v[44:45]
	s_waitcnt vmcnt(1)
	v_cndmask_b32_e32 v91, 0, v61, vcc
	v_add_f32_e32 v44, v11, v44
	v_add_f32_e32 v71, v44, v45
	v_lshlrev_b32_e32 v45, 16, v69
	v_lshlrev_b32_e32 v44, 16, v33
	v_pk_mul_f32 v[44:45], v[34:35], v[44:45]
	s_nop 0
	v_add_f32_e32 v44, v12, v44
	v_add_f32_e32 v89, v44, v45
	v_and_b32_e32 v45, 0xffff0000, v69
	v_and_b32_e32 v44, 0xffff0000, v33
	v_pk_mul_f32 v[44:45], v[8:9], v[44:45]
	s_nop 0
	v_add_f32_e32 v33, v13, v44
	v_add_f32_e32 v90, v33, v45
	v_ashrrev_i32_e32 v33, 31, v32
	v_lshl_add_u64 v[44:45], s[12:13], 0, v[32:33]
	v_mad_u64_u32 v[54:55], s[2:3], v44, s77, v[46:47]
	v_mad_i32_i24 v55, v45, s77, v55
	v_lshl_add_u64 v[44:45], v[54:55], 0, v[48:49]
	v_add_co_u32_e64 v54, s[2:3], s88, v44
	v_add_u32_e32 v44, s38, v76
	v_max_i32_e32 v33, 3, v44
	v_add_u32_e32 v66, -3, v33
	v_lshl_add_u64 v[66:67], s[12:13], 0, v[66:67]
	v_addc_co_u32_e64 v55, s[2:3], 0, v45, s[2:3]
	v_mad_u64_u32 v[68:69], s[2:3], v66, s77, v[46:47]
	v_mad_i32_i24 v69, v67, s77, v69
	v_lshl_add_u64 v[78:79], v[68:69], 0, v[48:49]
	v_max_i32_e32 v33, 2, v44
	global_load_dwordx4 v[66:69], v[54:55], off
	s_nop 0
	global_load_dwordx4 v[78:81], v[78:79], off offset:3072
	v_add_u32_e32 v54, -2, v33
	v_mov_b32_e32 v55, v4
	v_lshl_add_u64 v[54:55], s[12:13], 0, v[54:55]
	v_mad_u64_u32 v[82:83], s[2:3], v54, s77, v[46:47]
	v_mad_i32_i24 v83, v55, s77, v83
	v_lshl_add_u64 v[54:55], v[82:83], 0, v[48:49]
	global_load_dwordx4 v[82:85], v[54:55], off offset:3072
	v_cndmask_b32_e32 v45, 0, v60, vcc
	v_cndmask_b32_e32 v54, 0, v59, vcc
	v_cndmask_b32_e32 v55, 0, v58, vcc
	v_cmp_lt_i32_e32 vcc, -1, v32
	v_lshlrev_b32_e32 v32, 16, v55
	s_waitcnt vmcnt(3)
	v_cndmask_b32_e32 v61, 0, v62, vcc
	v_lshlrev_b32_e32 v33, 16, v61
	v_pk_mul_f32 v[32:33], v[42:43], v[32:33]
	v_cndmask_b32_e32 v60, 0, v63, vcc
	v_add_f32_e32 v32, v75, v32
	v_add_f32_e32 v75, v32, v33
	v_and_b32_e32 v33, 0xffff0000, v61
	v_and_b32_e32 v32, 0xffff0000, v55
	v_pk_mul_f32 v[32:33], v[22:23], v[32:33]
	v_cndmask_b32_e32 v59, 0, v64, vcc
	v_add_f32_e32 v32, v77, v32
	v_add_f32_e32 v77, v32, v33
	v_lshlrev_b32_e32 v33, 16, v60
	v_lshlrev_b32_e32 v32, 16, v54
	v_pk_mul_f32 v[32:33], v[38:39], v[32:33]
	v_cndmask_b32_e32 v58, 0, v65, vcc
	v_add_f32_e32 v32, v86, v32
	v_add_f32_e32 v92, v32, v33
	v_and_b32_e32 v33, 0xffff0000, v60
	v_and_b32_e32 v32, 0xffff0000, v54
	v_pk_mul_f32 v[32:33], v[24:25], v[32:33]
	v_mov_b32_e32 v55, v4
	v_add_f32_e32 v32, v87, v32
	v_add_f32_e32 v87, v32, v33
	v_lshlrev_b32_e32 v33, 16, v59
	v_lshlrev_b32_e32 v32, 16, v45
	v_pk_mul_f32 v[32:33], v[40:41], v[32:33]
	v_cvt_pk_bf16_f32 v86, v75, v77
	v_lshlrev_b32_e32 v75, 8, v74
	v_add_f32_e32 v32, v88, v32
	v_add_f32_e32 v88, v32, v33
	v_and_b32_e32 v33, 0xffff0000, v59
	v_and_b32_e32 v32, 0xffff0000, v45
	v_pk_mul_f32 v[32:33], v[18:19], v[32:33]
	v_cvt_pk_bf16_f32 v87, v92, v87
	v_cmp_lt_i32_e32 vcc, 2, v44
	v_add_f32_e32 v32, v71, v32
	v_add_f32_e32 v45, v32, v33
	v_lshlrev_b32_e32 v33, 16, v58
	v_lshlrev_b32_e32 v32, 16, v91
	v_pk_mul_f32 v[32:33], v[30:31], v[32:33]
	v_cvt_pk_bf16_f32 v88, v88, v45
	v_lshlrev_b32_e32 v77, 8, v76
	v_add_f32_e32 v32, v89, v32
	v_add_f32_e32 v71, v32, v33
	v_max_i32_e32 v32, 1, v44
	v_add_u32_e32 v54, -1, v32
	v_lshl_add_u64 v[54:55], s[12:13], 0, v[54:55]
	v_and_b32_e32 v33, 0xffff0000, v58
	v_mad_u64_u32 v[58:59], s[2:3], v54, s77, v[46:47]
	v_mad_i32_i24 v59, v55, s77, v59
	v_lshl_add_u64 v[54:55], v[58:59], 0, v[48:49]
	global_load_dwordx4 v[58:61], v[54:55], off offset:3072
	v_max_i32_e32 v54, 0, v44
	v_mov_b32_e32 v55, v4
	v_lshl_add_u64 v[54:55], s[12:13], 0, v[54:55]
	v_mad_u64_u32 v[62:63], s[2:3], v54, s77, v[46:47]
	v_mad_i32_i24 v63, v55, s77, v63
	v_lshl_add_u64 v[54:55], v[62:63], 0, v[48:49]
	v_and_b32_e32 v32, 0xffff0000, v91
	global_load_dwordx4 v[62:65], v[54:55], off offset:3072
	v_pk_mul_f32 v[32:33], v[20:21], v[32:33]
	s_waitcnt vmcnt(3)
	v_cndmask_b32_e32 v54, 0, v81, vcc
	v_add_f32_e32 v32, v90, v32
	v_add_f32_e32 v32, v32, v33
	v_cvt_pk_bf16_f32 v89, v71, v32
	v_add_u32_e32 v32, v57, v75
	ds_write_b128 v32, v[86:89]
	ds_write_b128 v32, v[66:69] offset:32768
	v_cndmask_b32_e32 v55, 0, v80, vcc
	v_cndmask_b32_e32 v45, 0, v79, vcc
	v_cndmask_b32_e32 v66, 0, v78, vcc
	v_cmp_lt_i32_e32 vcc, 1, v44
	v_lshlrev_b32_e32 v32, 16, v66
	s_waitcnt vmcnt(2)
	v_cndmask_b32_e32 v71, 0, v82, vcc
	v_lshlrev_b32_e32 v33, 16, v71
	v_pk_mul_f32 v[32:33], v[50:51], v[32:33]
	v_cndmask_b32_e32 v69, 0, v83, vcc
	v_add_f32_e32 v26, v26, v32
	v_add_f32_e32 v50, v26, v33
	v_and_b32_e32 v33, 0xffff0000, v71
	v_and_b32_e32 v32, 0xffff0000, v66
	v_pk_mul_f32 v[14:15], v[14:15], v[32:33]
	v_cndmask_b32_e32 v68, 0, v84, vcc
	v_add_f32_e32 v14, v27, v14
	v_add_f32_e32 v32, v14, v15
	v_lshlrev_b32_e32 v15, 16, v69
	v_lshlrev_b32_e32 v14, 16, v45
	v_pk_mul_f32 v[14:15], v[52:53], v[14:15]
	v_cndmask_b32_e32 v67, 0, v85, vcc
	v_add_f32_e32 v14, v28, v14
	v_add_f32_e32 v28, v14, v15
	v_and_b32_e32 v15, 0xffff0000, v69
	v_and_b32_e32 v14, 0xffff0000, v45
	v_pk_mul_f32 v[14:15], v[16:17], v[14:15]
	v_ashrrev_i32_e32 v45, 31, v44
	v_add_f32_e32 v14, v29, v14
	v_add_f32_e32 v29, v14, v15
	v_lshlrev_b32_e32 v15, 16, v68
	v_lshlrev_b32_e32 v14, 16, v55
	v_pk_mul_f32 v[14:15], v[36:37], v[14:15]
	v_and_b32_e32 v27, 0xffff0000, v68
	v_add_f32_e32 v10, v10, v14
	v_add_f32_e32 v10, v10, v15
	v_lshl_add_u64 v[14:15], s[12:13], 0, v[44:45]
	v_mad_u64_u32 v[16:17], s[2:3], v14, s77, v[46:47]
	v_mad_i32_i24 v17, v15, s77, v17
	v_lshl_add_u64 v[14:15], v[16:17], 0, v[48:49]
	v_add_co_u32_e32 v14, vcc, s88, v14
	v_and_b32_e32 v26, 0xffff0000, v55
	s_nop 0
	v_addc_co_u32_e32 v15, vcc, 0, v15, vcc
	v_pk_mul_f32 v[6:7], v[6:7], v[26:27]
	global_load_dwordx4 v[14:17], v[14:15], off
	v_add_f32_e32 v6, v11, v6
	v_add_f32_e32 v11, v6, v7
	v_lshlrev_b32_e32 v7, 16, v67
	v_lshlrev_b32_e32 v6, 16, v54
	v_pk_mul_f32 v[6:7], v[34:35], v[6:7]
	v_cmp_lt_i32_e32 vcc, 0, v44
	v_add_f32_e32 v6, v12, v6
	v_add_f32_e32 v12, v6, v7
	v_and_b32_e32 v7, 0xffff0000, v67
	v_and_b32_e32 v6, 0xffff0000, v54
	v_pk_mul_f32 v[6:7], v[8:9], v[6:7]
	v_bfe_u32 v54, v56, 4, 2
	v_add_f32_e32 v6, v13, v6
	v_add_f32_e32 v13, v6, v7
	v_ashrrev_i32_e32 v6, 2, v56
	v_bfi_b32 v47, -16, v6, v56
	v_add_u32_e32 v78, s40, v47
	v_ashrrev_i32_e32 v79, 31, v78
	s_waitcnt vmcnt(2)
	v_cndmask_b32_e32 v26, 0, v61, vcc
	v_cndmask_b32_e32 v27, 0, v60, vcc
	v_cndmask_b32_e32 v33, 0, v59, vcc
	v_cndmask_b32_e32 v34, 0, v58, vcc
	v_cmp_lt_i32_e32 vcc, -1, v44
	v_lshlrev_b64 v[44:45], 2, v[78:79]
	v_lshl_add_u64 v[8:9], s[28:29], 0, v[44:45]
	global_load_dword v48, v[8:9], off
	s_waitcnt vmcnt(2)
	v_cndmask_b32_e32 v46, 0, v62, vcc
	v_lshlrev_b32_e32 v7, 16, v46
	v_lshlrev_b32_e32 v6, 16, v34
	v_pk_mul_f32 v[6:7], v[42:43], v[6:7]
	v_cndmask_b32_e32 v37, 0, v63, vcc
	v_add_f32_e32 v6, v50, v6
	v_add_f32_e32 v8, v6, v7
	v_and_b32_e32 v7, 0xffff0000, v46
	v_and_b32_e32 v6, 0xffff0000, v34
	v_pk_mul_f32 v[6:7], v[22:23], v[6:7]
	v_cndmask_b32_e32 v36, 0, v64, vcc
	v_add_f32_e32 v6, v32, v6
	v_add_f32_e32 v9, v6, v7
	v_lshlrev_b32_e32 v7, 16, v37
	v_lshlrev_b32_e32 v6, 16, v33
	v_pk_mul_f32 v[6:7], v[38:39], v[6:7]
	v_cndmask_b32_e32 v35, 0, v65, vcc
	v_add_f32_e32 v6, v28, v6
	v_add_f32_e32 v22, v6, v7
	v_and_b32_e32 v7, 0xffff0000, v37
	v_and_b32_e32 v6, 0xffff0000, v33
	v_pk_mul_f32 v[6:7], v[24:25], v[6:7]
	s_mov_b64 s[2:3], 0x600000
	v_add_f32_e32 v6, v29, v6
	v_add_f32_e32 v23, v6, v7
	v_lshlrev_b32_e32 v7, 16, v36
	v_lshlrev_b32_e32 v6, 16, v27
	v_pk_mul_f32 v[6:7], v[40:41], v[6:7]
	v_lshl_add_u64 v[38:39], s[8:9], 0, v[44:45]
	v_add_f32_e32 v6, v10, v6
	v_add_f32_e32 v10, v6, v7
	v_and_b32_e32 v7, 0xffff0000, v36
	v_and_b32_e32 v6, 0xffff0000, v27
	v_pk_mul_f32 v[6:7], v[18:19], v[6:7]
	v_lshlrev_b32_e32 v63, 10, v54
	v_add_f32_e32 v6, v11, v6
	v_add_f32_e32 v11, v6, v7
	v_lshlrev_b32_e32 v7, 16, v35
	v_lshlrev_b32_e32 v6, 16, v26
	v_pk_mul_f32 v[6:7], v[30:31], v[6:7]
	v_lshlrev_b32_e32 v64, 6, v54
	v_add_f32_e32 v6, v12, v6
	v_add_f32_e32 v12, v6, v7
	v_and_b32_e32 v7, 0xffff0000, v35
	v_and_b32_e32 v6, 0xffff0000, v26
	v_pk_mul_f32 v[6:7], v[20:21], v[6:7]
	v_and_b32_e32 v46, 15, v56
	v_add_f32_e32 v6, v13, v6
	v_add_f32_e32 v13, v6, v7
	v_cvt_pk_bf16_f32 v6, v8, v9
	v_cvt_pk_bf16_f32 v7, v22, v23
	v_cvt_pk_bf16_f32 v8, v10, v11
	v_cvt_pk_bf16_f32 v9, v12, v13
	v_add_u32_e32 v10, v57, v77
	ds_write_b128 v10, v[6:9]
	s_waitcnt vmcnt(1)
	ds_write_b128 v10, v[14:17] offset:32768
	v_lshlrev_b32_e32 v6, 7, v47
	v_ashrrev_i32_e32 v7, 31, v6
	v_lshlrev_b64 v[6:7], 1, v[6:7]
	v_lshl_add_u64 v[8:9], s[6:7], 0, v[6:7]
	v_lshlrev_b32_e32 v10, 4, v54
	v_mov_b32_e32 v11, v4
	v_lshl_add_u64 v[8:9], v[8:9], 0, v[10:11]
	v_lshl_add_u64 v[6:7], s[24:25], 0, v[6:7]
	v_lshl_add_u64 v[30:31], v[8:9], 0, s[2:3]
	v_lshl_add_u64 v[10:11], v[6:7], 0, v[10:11]
	s_mov_b64 s[2:3], 0x620000
	v_lshl_add_u64 v[34:35], v[10:11], 0, s[2:3]
	s_mov_b32 s2, 0x600000
	v_add_co_u32_e32 v6, vcc, s2, v8
	s_mov_b32 s2, 0x620000
	s_nop 0
	v_addc_co_u32_e32 v7, vcc, 0, v9, vcc
	v_add_co_u32_e32 v10, vcc, s2, v10
	global_load_dwordx4 v[6:9], v[6:7], off
	s_nop 0
	v_addc_co_u32_e32 v11, vcc, 0, v11, vcc
	global_load_dwordx4 v[10:13], v[10:11], off
	s_nop 0
	global_load_dwordx4 v[14:17], v[30:31], off offset:64
	global_load_dwordx4 v[18:21], v[30:31], off offset:128
	global_load_dwordx4 v[22:25], v[34:35], off offset:64
	global_load_dwordx4 v[26:29], v[34:35], off offset:128
	s_nop 0
	global_load_dwordx4 v[30:33], v[30:31], off offset:192
	s_nop 0
	global_load_dwordx4 v[34:37], v[34:35], off offset:192
	v_lshlrev_b32_e32 v47, 1, v47
	global_load_dword v71, v[38:39], off
	s_waitcnt vmcnt(9)
	v_mul_f32_e32 v38, 0xbfb8aa3b, v48
	v_exp_f32_e32 v41, v38
	v_lshl_add_u64 v[38:39], s[26:27], 0, v[44:45]
	global_load_dword v96, v[38:39], off
	v_lshlrev_b32_e32 v48, 1, v56
	v_and_b32_e32 v97, -16, v47
	v_and_b32_e32 v61, 14, v48
	v_xad_u32 v47, v97, v64, v63
	v_lshrrev_b32_e32 v40, 4, v56
	v_lshlrev_b32_e32 v62, 2, v54
	v_or_b32_e32 v47, v47, v61
	v_bitop3_b32 v38, v40, v46, 3 bitop3:0x6c
	v_add_u32_e32 v98, 0, v47
	v_or_b32_e32 v47, 1, v62
	v_lshlrev_b32_e32 v56, 8, v46
	v_lshlrev_b32_e32 v57, 4, v38
	v_bitop3_b32 v38, v54, v46, 4 bitop3:0x36
	v_bitop3_b32 v39, v54, v46, 8 bitop3:0x36
	v_lshlrev_b32_e32 v48, 8, v47
	v_lshlrev_b32_e32 v47, 4, v47
	v_add_u32_e32 v49, 0, v56
	v_lshlrev_b32_e32 v58, 4, v38
	v_lshlrev_b32_e32 v59, 4, v39
	v_xad_u32 v47, v47, v97, v48
	v_add_u32_e32 v38, v49, v58
	v_add_u32_e32 v42, v49, v59
	v_or_b32_e32 v47, v47, v61
	v_add_f32_e32 v55, 1.0, v41
	s_waitcnt lgkmcnt(0)
	s_barrier
	ds_read_b128 v[38:41], v38
	ds_read_b128 v[42:45], v42
	v_add_u32_e32 v51, 0, v47
	ds_read_u16 v65, v98
	ds_read_u16 v52, v51
	v_or_b32_e32 v47, 2, v62
	v_or_b32_e32 v62, 3, v62
	v_bitop3_b32 v46, v54, v46, 12 bitop3:0x36
	s_waitcnt lgkmcnt(1)
	v_lshlrev_b32_e32 v90, 16, v65
	v_lshlrev_b32_e32 v65, 8, v62
	v_lshlrev_b32_e32 v62, 4, v62
	v_lshlrev_b32_e32 v48, 8, v47
	v_lshlrev_b32_e32 v47, 4, v47
	v_xad_u32 v62, v62, v97, v65
	v_lshlrev_b32_e32 v60, 4, v46
	v_xad_u32 v47, v47, v97, v48
	v_or_b32_e32 v62, v62, v61
	v_add_u32_e32 v50, v49, v57
	v_add_u32_e32 v46, v49, v60
	v_or_b32_e32 v47, v47, v61
	v_add_u32_e32 v62, 0, v62
	v_add_u32_e32 v66, 0, v47
	ds_read_b128 v[46:49], v46
	ds_read_u16 v67, v66 offset:32768
	ds_read_u16 v68, v51 offset:32768
	s_waitcnt lgkmcnt(3)
	v_lshlrev_b32_e32 v91, 16, v52
	ds_read_b128 v[50:53], v50
	ds_read_u16 v69, v98 offset:32768
	ds_read_u16 v65, v62
	v_cmp_gt_f32_e32 vcc, s45, v55
	ds_read_u16 v66, v66
	ds_read_u16 v62, v62 offset:32768
	s_mov_b32 s2, 0x3f317217
	v_cmp_eq_u32_e64 s[6:7], 2, v54
	s_waitcnt lgkmcnt(2)
	v_lshlrev_b32_e32 v89, 16, v65
	v_cndmask_b32_e64 v65, 0, 32, vcc
	v_ldexp_f32 v55, v55, v65
	v_log_f32_e32 v55, v55
	s_waitcnt lgkmcnt(0)
	v_lshlrev_b32_e32 v81, 16, v62
	v_cmp_lt_u32_e64 s[8:9], 1, v54
	v_lshlrev_b32_e32 v83, 16, v68
	v_mul_f32_e32 v62, 0x3f317217, v55
	v_fma_f32 v62, v55, s2, -v62
	v_fmac_f32_e32 v62, 0x3377d1cf, v55
	s_mov_b32 s2, 0x7f800000
	v_fmac_f32_e32 v62, 0x3f317217, v55
	v_cmp_lt_f32_e64 s[2:3], |v55|, s2
	v_lshlrev_b32_e32 v82, 16, v69
	v_lshlrev_b32_e32 v88, 16, v66
	v_cndmask_b32_e64 v55, v55, v62, s[2:3]
	v_cndmask_b32_e32 v62, 0, v241, vcc
	v_cmp_eq_u32_e32 vcc, 0, v54
	v_or_b32_e32 v54, v56, v60
	s_add_i32 s2, 0, 0x1000
	v_add_u32_e32 v100, s2, v54
	v_or_b32_e32 v54, v56, v59
	v_add_u32_e32 v101, s2, v54
	v_or_b32_e32 v54, v56, v58
	v_add_u32_e32 v102, s2, v54
	v_or_b32_e32 v54, v56, v57
	v_sub_f32_e32 v55, v55, v62
	v_add_u32_e32 v103, s2, v54
	v_or_b32_e32 v54, v63, v61
	v_lshlrev_b32_e32 v80, 16, v67
	v_mul_f32_e32 v99, 0xc1000000, v55
	v_add_u32_e32 v104, 0, v54
	v_or_b32_e32 v105, 0x120, v64
	s_branch .LBB0_596

.LBB0_637:
	s_or_b64 exec, exec, s[2:3]
	s_mov_b32 s2, s87
	s_waitcnt lgkmcnt(0)
	s_barrier
	s_ashr_i32 s3, s2, 31
	s_lshl_b64 s[2:3], s[2:3], 3
	s_add_u32 s2, s0, s2
	s_addc_u32 s3, s1, s3
	s_mov_b64 s[2:3], s[100:101]
	s_mov_b32 s4, s87
	s_mov_b32 s6, s87
	s_mov_b32 s8, s87
	s_waitcnt lgkmcnt(0)
	s_add_u32 s2, s2, s81
	s_addc_u32 s3, s3, 0
	s_add_u32 s2, s2, 0xaa00000
	s_addc_u32 s3, s3, 0
	s_ashr_i32 s5, s4, 31
	s_lshl_b64 s[4:5], s[4:5], 3
	s_add_u32 s4, s0, s4
	s_addc_u32 s5, s1, s5
	s_mov_b64 s[4:5], s[100:101]
	s_waitcnt vmcnt(7)
	v_mov_b32_e32 v78, v0
	v_mov_b32_e32 v9, v4
	v_mov_b32_e32 v7, v4
	s_waitcnt lgkmcnt(0)
	s_add_u32 s10, s4, s85
	s_addc_u32 s11, s5, 0
	s_ashr_i32 s7, s6, 31
	s_lshl_b64 s[4:5], s[6:7], 3
	s_add_u32 s4, s0, s4
	s_addc_u32 s5, s1, s5
	s_load_dwordx2 s[4:5], s[4:5], 0xd0
	s_mov_b32 s6, s87
	s_mov_b32 s9, 0x400000
	s_waitcnt lgkmcnt(0)
	s_add_u32 s12, s4, s80
	s_addc_u32 s13, s5, 0
	s_ashr_i32 s7, s6, 31
	s_lshl_b64 s[4:5], s[6:7], 3
	s_add_u32 s4, s0, s4
	s_addc_u32 s5, s1, s5
	s_load_dwordx2 s[4:5], s[4:5], 0xd0
	s_mov_b32 s6, s87
	v_readlane_b32 s7, v253, 34
	s_waitcnt lgkmcnt(0)
	s_add_u32 s14, s4, s80
	s_mov_b32 s4, s87
	s_addc_u32 s15, s5, 0
	s_ashr_i32 s5, s4, 31
	s_lshl_b64 s[4:5], s[4:5], 3
	s_add_u32 s4, s0, s4
	s_addc_u32 s5, s1, s5
	s_mov_b64 s[4:5], s[100:101]
	s_nop 0
	v_lshlrev_b32_e32 v8, 12, v78
	v_ashrrev_i32_e32 v2, 6, v78
	v_and_b32_e32 v8, 0x30000, v8
	v_and_b32_e32 v5, 63, v78
	v_add_u32_e32 v104, s7, v2
	v_lshl_add_u64 v[8:9], s[10:11], 0, v[8:9]
	s_mov_b64 s[10:11], 0x440000
	v_lshlrev_b32_e32 v6, 4, v5
	v_lshl_add_u64 v[102:103], v[8:9], 0, s[10:11]
	s_mov_b64 s[10:11], 0x480000
	v_ashrrev_i32_e32 v105, 31, v104
	v_lshl_add_u64 v[94:95], s[12:13], 0, v[6:7]
	v_lshl_add_u64 v[2:3], s[14:15], 0, v[6:7]
	v_lshl_add_u64 v[100:101], v[8:9], 0, s[48:49]
	v_lshl_add_u64 v[98:99], v[8:9], 0, s[10:11]
	v_lshlrev_b64 v[8:9], 10, v[104:105]
	v_lshl_add_u64 v[96:97], v[2:3], 0, s[48:49]
	v_lshl_add_u64 v[10:11], v[94:95], 0, v[8:9]
	v_lshl_add_u64 v[2:3], s[2:3], 0, v[6:7]
	global_load_dwordx4 v[86:89], v[10:11], off nt
	v_lshl_add_u64 v[10:11], v[96:97], 0, v[8:9]
	global_load_dwordx4 v[90:93], v[10:11], off nt
	v_lshl_add_u64 v[10:11], v[2:3], 0, v[8:9]
	v_lshl_add_u64 v[8:9], s[2:3], 0, v[8:9]
	v_lshl_add_u64 v[8:9], v[8:9], 0, v[6:7]
	v_add_co_u32_e32 v12, vcc, s9, v8
	v_add_u32_e32 v110, 8, v104
	s_nop 0
	v_addc_co_u32_e32 v13, vcc, 0, v9, vcc
	v_add_co_u32_e32 v8, vcc, s45, v8
	global_load_dwordx4 v[66:69], v[10:11], off nt
	global_load_dwordx4 v[70:73], v[12:13], off nt
	v_addc_co_u32_e32 v9, vcc, 0, v9, vcc
	global_load_dwordx4 v[74:77], v[8:9], off nt
	v_lshlrev_b64 v[8:9], 2, v[104:105]
	v_ashrrev_i32_e32 v111, 31, v110
	v_lshl_add_u64 v[80:81], v[100:101], 0, v[8:9]
	s_waitcnt vmcnt(11)
	v_lshl_add_u64 v[82:83], v[102:103], 0, v[8:9]
	v_lshl_add_u64 v[84:85], v[98:99], 0, v[8:9]
	v_lshlrev_b64 v[8:9], 10, v[110:111]
	v_lshl_add_u64 v[10:11], v[94:95], 0, v[8:9]
	global_load_dwordx4 v[58:61], v[10:11], off nt
	v_lshl_add_u64 v[10:11], v[96:97], 0, v[8:9]
	global_load_dwordx4 v[62:65], v[10:11], off nt
	v_lshl_add_u64 v[10:11], v[2:3], 0, v[8:9]
	v_lshl_add_u64 v[8:9], s[2:3], 0, v[8:9]
	v_lshl_add_u64 v[8:9], v[8:9], 0, v[6:7]
	v_add_co_u32_e32 v12, vcc, s9, v8
	v_add_u32_e32 v108, 16, v104
	s_nop 0
	v_addc_co_u32_e32 v13, vcc, 0, v9, vcc
	v_add_co_u32_e32 v8, vcc, s45, v8
	v_ashrrev_i32_e32 v109, 31, v108
	s_nop 0
	v_addc_co_u32_e32 v9, vcc, 0, v9, vcc
	global_load_dwordx4 v[46:49], v[10:11], off nt
	global_load_dwordx4 v[50:53], v[12:13], off nt
	global_load_dwordx4 v[54:57], v[8:9], off nt
	v_lshlrev_b64 v[8:9], 10, v[108:109]
	v_lshl_add_u64 v[10:11], v[94:95], 0, v[8:9]
	global_load_dwordx4 v[38:41], v[10:11], off nt
	v_lshl_add_u64 v[10:11], v[96:97], 0, v[8:9]
	global_load_dwordx4 v[42:45], v[10:11], off nt
	v_lshl_add_u64 v[10:11], v[2:3], 0, v[8:9]
	v_lshl_add_u64 v[8:9], s[2:3], 0, v[8:9]
	v_lshl_add_u64 v[8:9], v[8:9], 0, v[6:7]
	v_add_co_u32_e32 v12, vcc, s9, v8
	v_add_u32_e32 v106, 24, v104
	s_nop 0
	v_addc_co_u32_e32 v13, vcc, 0, v9, vcc
	v_add_co_u32_e32 v8, vcc, s45, v8
	v_ashrrev_i32_e32 v107, 31, v106
	s_nop 0
	v_addc_co_u32_e32 v9, vcc, 0, v9, vcc
	global_load_dwordx4 v[26:29], v[10:11], off nt
	global_load_dwordx4 v[30:33], v[12:13], off nt
	global_load_dwordx4 v[34:37], v[8:9], off nt
	v_lshlrev_b64 v[8:9], 10, v[106:107]
	v_lshl_add_u64 v[10:11], v[94:95], 0, v[8:9]
	global_load_dwordx4 v[18:21], v[10:11], off nt
	v_lshl_add_u64 v[10:11], v[96:97], 0, v[8:9]
	global_load_dwordx4 v[22:25], v[10:11], off nt
	v_lshl_add_u64 v[10:11], v[2:3], 0, v[8:9]
	v_lshl_add_u64 v[8:9], s[2:3], 0, v[8:9]
	v_lshl_add_u64 v[14:15], v[8:9], 0, v[6:7]
	v_add_co_u32_e32 v12, vcc, s9, v14
	s_bfe_u32 s10, s7, 0x50007
	s_nop 0
	v_addc_co_u32_e32 v13, vcc, 0, v15, vcc
	v_add_co_u32_e32 v14, vcc, 0x800000, v14
	global_load_dwordx4 v[6:9], v[10:11], off nt
	s_nop 0
	global_load_dwordx4 v[10:13], v[12:13], off nt
	v_addc_co_u32_e32 v15, vcc, 0, v15, vcc
	global_load_dwordx4 v[14:17], v[14:15], off nt
	s_nop 0
	global_load_dword v114, v[80:81], off
	global_load_dword v116, v[82:83], off
	global_load_dword v117, v[80:81], off offset:32
	global_load_dword v118, v[82:83], off offset:32
	global_load_dword v119, v[80:81], off offset:64
	global_load_dword v120, v[82:83], off offset:64
	global_load_dword v122, v[82:83], off offset:96
	global_load_dword v124, v[80:81], off offset:96
	global_load_dword v115, v[84:85], off
	global_load_dword v121, v[84:85], off offset:32
	global_load_dword v123, v[84:85], off offset:64
	global_load_dword v125, v[84:85], off offset:96
	s_cmp_eq_u32 s10, 0
	s_cbranch_scc1 .LBB0_641
	s_ashr_i32 s9, s8, 31
	s_lshl_b64 s[8:9], s[8:9], 3
	s_add_u32 s8, s0, s8
	s_addc_u32 s9, s1, s9
	s_mov_b64 s[8:9], s[100:101]
	s_lshl_b32 s11, s85, 2
	v_readlane_b32 s16, v253, 46
	v_ashrrev_i32_e32 v79, 31, v78
	v_readlane_b32 s17, v253, 47
	s_waitcnt lgkmcnt(0)
	s_add_u32 s12, s8, s11
	s_addc_u32 s9, s9, 0
	s_ashr_i32 s7, s6, 31
	s_lshl_b64 s[6:7], s[6:7], 3
	s_add_u32 s6, s0, s6
	s_addc_u32 s7, s1, s7
	s_mov_b64 s[6:7], s[100:101]
	v_lshlrev_b64 v[82:83], 2, v[78:79]
	s_mov_b32 s8, 0
	v_mov_b32_e32 v126, 0
	s_waitcnt lgkmcnt(0)
	s_add_u32 s11, s6, s11
	s_addc_u32 s14, s7, 0
	s_add_u32 s6, s12, s16
	s_addc_u32 s7, s9, s17
	v_lshl_add_u64 v[80:81], s[6:7], 0, v[82:83]
	s_add_u32 s6, s11, s16
	s_addc_u32 s7, s14, s17
	s_mov_b64 s[12:13], 0x500000
	v_lshl_add_u64 v[82:83], s[6:7], 0, v[82:83]
	s_mov_b64 s[6:7], 0x540000
	v_lshl_add_u64 v[80:81], v[80:81], 0, s[12:13]
	v_lshl_add_u64 v[82:83], v[82:83], 0, s[6:7]
	v_mov_b64_e32 v[84:85], v[82:83]
	v_mov_b64_e32 v[112:113], v[80:81]
	s_mov_b64 s[12:13], 0x8000

.LBB0_679:
	s_or_b64 exec, exec, s[2:3]
	s_mov_b32 s8, s87
	s_mov_b32 s6, s87
	s_mov_b32 s4, s87
	s_mov_b32 s2, s87
	v_mov_b32_e32 v6, v0
	s_waitcnt lgkmcnt(0)
	s_barrier
	s_movk_i32 s11, 0x400
	v_readfirstlane_b32 s10, v6
	s_and_b64 vcc, exec, s[50:51]
	s_cbranch_vccnz .LBB0_722
	v_lshlrev_b32_e32 v3, 4, v6
	v_add_u32_e32 v2, 0x2000, v3
	v_ashrrev_i32_e32 v5, 31, v2
	v_lshrrev_b32_e32 v5, 22, v5
	v_add_u32_e32 v5, v2, v5
	v_ashrrev_i32_e32 v7, 10, v5
	v_mul_i32_i24_e32 v5, 0x400, v7
	v_sub_u32_e32 v2, v2, v5
	v_lshrrev_b32_e32 v5, 4, v2
	v_bitop3_b32 v2, v5, v2, 32 bitop3:0x6c
	s_ashr_i32 s9, s8, 31
	v_ashrrev_i32_e32 v5, 31, v2
	s_lshl_b64 s[8:9], s[8:9], 3
	v_lshrrev_b32_e32 v5, 26, v5
	s_add_u32 s8, s0, s8
	v_add_u32_e32 v5, v2, v5
	v_lshlrev_b32_e32 v10, 3, v7
	s_addc_u32 s9, s1, s9
	s_ashr_i32 s7, s6, 31
	v_ashrrev_i32_e32 v8, 6, v5
	v_and_b32_e32 v10, -16, v10
	s_lshl_b64 s[6:7], s[6:7], 3
	v_add_u32_e32 v10, v8, v10
	s_add_u32 s6, s0, s6
	v_lshrrev_b32_e32 v11, 2, v10
	v_lshlrev_b32_e32 v12, 1, v10
	v_and_b32_e32 v5, 0xc0, v5
	s_addc_u32 s7, s1, s7
	s_ashr_i32 s5, s4, 31
	v_and_b32_e32 v9, 3, v8
	v_and_b32_e32 v11, 4, v11
	v_and_b32_e32 v12, 0x1fffd8, v12
	v_sub_u32_e32 v2, v2, v5
	s_lshl_b64 s[4:5], s[4:5], 3
	v_or3_b32 v11, v9, v11, v12
	v_lshlrev_b32_e32 v9, 5, v7
	v_ashrrev_i16_sdwa v2, v238, sext(v2) dst_sel:DWORD dst_unused:UNUSED_PAD src0_sel:DWORD src1_sel:BYTE_0
	s_add_u32 s4, s0, s4
	v_and_b32_e32 v12, 32, v9
	v_bfe_i32 v9, v2, 0, 16
	s_addc_u32 s5, s1, s5
	s_ashr_i32 s3, s2, 31
	v_add_lshl_u32 v5, v12, v9, 1
	s_lshl_b64 s[2:3], s[2:3], 3
	v_lshl_add_u32 v2, v11, 11, v5
	v_lshl_add_u32 v202, v10, 11, v5
	v_bfe_i32 v5, v6, 27, 1
	s_add_u32 s2, s0, s2
	v_lshrrev_b32_e32 v5, 22, v5
	s_addc_u32 s3, s1, s3
	v_add_u32_e32 v5, v3, v5
	s_mov_b64 s[12:13], s[100:101]
	s_nop 0
	s_mov_b64 s[4:5], s[100:101]
	s_nop 0
	s_mov_b64 s[6:7], s[100:101]
	s_nop 0
	s_mov_b64 s[2:3], s[100:101]
	v_and_b32_e32 v5, 0xfffffc00, v5
	s_lshl_b32 s8, s46, 20
	v_sub_u32_e32 v3, v3, v5
	s_waitcnt lgkmcnt(0)
	s_add_u32 s8, s12, s8
	v_lshrrev_b32_e32 v5, 4, v3
	v_ashrrev_i32_e32 v11, 31, v6
	s_addc_u32 s9, s13, 0
	v_bitop3_b32 v3, v5, v3, 32 bitop3:0x6c
	v_lshrrev_b32_e32 v11, 26, v11
	s_add_u32 s36, s8, 0x1200000
	v_ashrrev_i32_e32 v5, 31, v3
	v_add_u32_e32 v11, v6, v11
	s_addc_u32 s37, s9, 0
	v_lshrrev_b32_e32 v5, 26, v5
	v_ashrrev_i32_e32 v11, 6, v11
	s_add_u32 s2, s2, s81
	v_add_u32_e32 v5, v3, v5
	v_lshlrev_b32_e32 v13, 3, v11
	s_addc_u32 s3, s3, 0
	v_ashrrev_i32_e32 v10, 6, v5
	v_and_b32_e32 v13, -16, v13
	s_add_u32 s38, s2, 0x9600000
	v_add_u32_e32 v13, v10, v13
	s_addc_u32 s39, s3, 0
	s_ashr_i32 s9, s10, 6
	v_lshrrev_b32_e32 v14, 2, v13
	v_lshlrev_b32_e32 v15, 1, v13
	v_and_b32_e32 v5, 0xc0, v5
	s_ashr_i32 s8, s10, 8
	s_lshl_b32 s2, s9, 10
	v_and_b32_e32 v12, 3, v10
	v_and_b32_e32 v14, 4, v14
	v_and_b32_e32 v15, 0x1fffd8, v15
	v_sub_u32_e32 v3, v3, v5
	v_readlane_b32 s12, v253, 60
	v_or3_b32 v14, v12, v14, v15
	v_lshlrev_b32_e32 v12, 5, v11
	v_ashrrev_i16_sdwa v3, v238, sext(v3) dst_sel:DWORD dst_unused:UNUSED_PAD src0_sel:DWORD src1_sel:BYTE_0
	v_readlane_b32 s13, v253, 61
	s_add_u32 s22, s36, s12
	v_and_b32_e32 v15, 32, v12
	v_bfe_i32 v12, v3, 0, 16
	s_addc_u32 s23, s37, s13
	s_add_i32 s40, s2, 0
	v_add_lshl_u32 v3, v15, v12, 1
	s_add_i32 s41, s40, 0x10000
	s_add_i32 s42, s40, 0x12000
	v_lshl_add_u32 v204, v14, 11, v3
	s_mov_b32 m0, s41
	s_add_u32 s2, s22, 0x10000
	global_load_lds_dwordx4 v204, s[22:23]
	s_mov_b32 m0, s42
	s_addc_u32 s3, s23, 0
	s_add_i32 s43, s40, 0x14000
	global_load_lds_dwordx4 v2, s[22:23]
	s_mov_b32 m0, s43
	s_add_i32 s44, s40, 0x16000
	global_load_lds_dwordx4 v204, s[2:3]
	s_mov_b32 m0, s44
	v_lshl_add_u32 v206, v13, 11, v3
	global_load_lds_dwordx4 v2, s[2:3]
	v_readlane_b32 s2, v253, 58
	v_readlane_b32 s3, v253, 59
	s_add_u32 s24, s38, s2
	s_addc_u32 s25, s39, s3
	s_add_i32 s45, s40, 0x2000
	s_mov_b32 m0, s40
	s_add_u32 s2, s24, 0x40000
	global_load_lds_dwordx4 v206, s[24:25]
	s_mov_b32 m0, s45
	s_addc_u32 s3, s25, 0
	s_add_i32 s46, s40, 0x4000
	v_mov_b32_e32 v205, v4
	global_load_lds_dwordx4 v202, s[24:25]
	s_mov_b32 m0, s46
	s_add_i32 s47, s40, 0x6000
	v_lshl_add_u64 v[14:15], s[22:23], 0, v[204:205]
	v_mov_b32_e32 v3, v4
	global_load_lds_dwordx4 v206, s[2:3]
	s_mov_b32 m0, s47
	s_add_i32 s48, s40, 0x18000
	v_lshl_add_u64 v[16:17], s[22:23], 0, v[2:3]
	v_mov_b32_e32 v207, v4
	global_load_lds_dwordx4 v202, s[2:3]
	v_lshl_add_u64 v[14:15], v[14:15], 0, s[68:69]
	s_mov_b32 m0, s48
	s_add_i32 s49, s40, 0x1a000
	v_lshl_add_u64 v[18:19], s[24:25], 0, v[206:207]
	v_mov_b32_e32 v203, v4
	global_load_lds_dwordx4 v[14:15], off
	v_lshl_add_u64 v[14:15], v[16:17], 0, s[68:69]
	s_mov_b32 m0, s49
	s_add_i32 s50, s40, 0x8000
	s_add_i32 s51, s40, 0xa000
	v_lshl_add_u64 v[20:21], s[24:25], 0, v[202:203]
	global_load_lds_dwordx4 v[14:15], off
	v_lshl_add_u64 v[14:15], v[18:19], 0, s[68:69]
	s_mov_b32 m0, s50
	s_add_u32 s2, s22, 0x10080
	global_load_lds_dwordx4 v[14:15], off
	v_lshl_add_u64 v[14:15], v[20:21], 0, s[68:69]
	s_mov_b32 m0, s51
	s_addc_u32 s3, s23, 0
	s_add_i32 s52, s40, 0x1c000
	global_load_lds_dwordx4 v[14:15], off
	s_mov_b32 m0, s52
	s_add_i32 s53, s40, 0x1e000
	global_load_lds_dwordx4 v204, s[2:3]
	s_mov_b32 m0, s53
	s_cmp_eq_u32 s8, 1
	global_load_lds_dwordx4 v2, s[2:3]
	s_cselect_b64 s[2:3], -1, 0
	s_cmp_lg_u32 s8, 1
	s_cbranch_scc1 .LBB0_682
	s_barrier

.LBB0_760:
	s_mov_b32 s2, s87
	s_ashr_i32 s3, s2, 31
	s_lshl_b64 s[2:3], s[2:3], 3
	s_add_u32 s2, s0, s2
	s_addc_u32 s3, s1, s3
	s_mov_b64 s[10:11], s[100:101]
	s_mov_b32 s2, s87
	s_ashr_i32 s3, s2, 31
	s_lshl_b64 s[2:3], s[2:3], 3
	s_add_u32 s2, s0, s2
	s_addc_u32 s3, s1, s3
	s_mov_b64 s[12:13], s[100:101]
	s_mov_b32 s2, s87
	s_ashr_i32 s3, s2, 31
	s_lshl_b64 s[2:3], s[2:3], 3
	s_add_u32 s2, s0, s2
	s_addc_u32 s3, s1, s3
	s_mov_b64 s[6:7], s[100:101]
	v_readlane_b32 s2, v254, 28
	v_readlane_b32 s3, v254, 29
	s_andn2_b64 vcc, exec, s[2:3]
	s_mov_b64 s[4:5], -1
	s_cbranch_vccnz .LBB0_762
	s_mov_b32 s2, s87
	s_mov_b64 s[4:5], 0

.LBB0_764:
	s_mov_b32 s8, s87
	v_mov_b32_e32 v6, v0
	s_lshl_b32 s38, s46, 20
	s_movk_i32 s15, 0x400
	v_readfirstlane_b32 s14, v6
	s_and_b64 vcc, exec, s[50:51]
	s_cbranch_vccnz .LBB0_808
	v_lshlrev_b32_e32 v3, 4, v6
	v_add_u32_e32 v2, 0x2000, v3
	v_ashrrev_i32_e32 v5, 31, v2
	v_lshrrev_b32_e32 v5, 22, v5
	v_add_u32_e32 v5, v2, v5
	v_ashrrev_i32_e32 v7, 10, v5
	v_mul_i32_i24_e32 v5, 0x400, v7
	v_sub_u32_e32 v2, v2, v5
	v_lshrrev_b32_e32 v5, 4, v2
	v_bitop3_b32 v2, v5, v2, 32 bitop3:0x6c
	v_ashrrev_i32_e32 v5, 31, v2
	v_lshrrev_b32_e32 v5, 26, v5
	v_add_u32_e32 v5, v2, v5
	v_lshlrev_b32_e32 v10, 3, v7
	v_ashrrev_i32_e32 v8, 6, v5
	v_and_b32_e32 v10, -16, v10
	v_add_u32_e32 v10, v8, v10
	v_lshrrev_b32_e32 v11, 2, v10
	v_lshlrev_b32_e32 v12, 1, v10
	v_and_b32_e32 v5, 0xc0, v5
	v_and_b32_e32 v9, 3, v8
	v_and_b32_e32 v11, 4, v11
	v_and_b32_e32 v12, 0x1fffd8, v12
	v_sub_u32_e32 v2, v2, v5
	v_or3_b32 v11, v9, v11, v12
	v_lshlrev_b32_e32 v9, 5, v7
	v_ashrrev_i16_sdwa v2, v238, sext(v2) dst_sel:DWORD dst_unused:UNUSED_PAD src0_sel:DWORD src1_sel:BYTE_0
	s_ashr_i32 s3, s2, 31
	v_and_b32_e32 v12, 32, v9
	v_bfe_i32 v9, v2, 0, 16
	s_lshl_b64 s[2:3], s[2:3], 3
	v_add_lshl_u32 v5, v12, v9, 1
	s_add_u32 s2, s0, s2
	v_lshl_add_u32 v2, v11, 11, v5
	v_lshl_add_u32 v198, v10, 11, v5
	v_bfe_i32 v5, v6, 27, 1
	s_addc_u32 s3, s1, s3
	s_ashr_i32 s9, s8, 31
	v_lshrrev_b32_e32 v5, 22, v5
	s_lshl_b64 s[8:9], s[8:9], 3
	v_add_u32_e32 v5, v3, v5
	s_add_u32 s8, s0, s8
	v_and_b32_e32 v5, 0xfffffc00, v5
	s_addc_u32 s9, s1, s9
	s_ashr_i32 s17, s14, 6
	v_sub_u32_e32 v3, v3, v5
	s_ashr_i32 s16, s14, 8
	s_lshl_b32 s18, s17, 10
	v_lshrrev_b32_e32 v5, 4, v3
	v_ashrrev_i32_e32 v11, 31, v6
	s_waitcnt lgkmcnt(0)
	s_add_u32 s10, s10, s89
	v_bitop3_b32 v3, v5, v3, 32 bitop3:0x6c
	v_lshrrev_b32_e32 v11, 26, v11
	s_addc_u32 s11, s11, 0
	v_ashrrev_i32_e32 v5, 31, v3
	v_add_u32_e32 v11, v6, v11
	s_add_u32 s39, s10, 0x7600000
	v_lshrrev_b32_e32 v5, 26, v5
	v_ashrrev_i32_e32 v11, 6, v11
	s_addc_u32 s40, s11, 0
	s_lshl_b32 s10, s38, 1
	v_add_u32_e32 v5, v3, v5
	v_lshlrev_b32_e32 v13, 3, v11
	s_add_u32 s10, s12, s10
	v_ashrrev_i32_e32 v10, 6, v5
	v_and_b32_e32 v13, -16, v13
	s_addc_u32 s11, s13, 0
	v_add_u32_e32 v13, v10, v13
	s_add_u32 s41, s10, 0x1600000
	v_lshrrev_b32_e32 v14, 2, v13
	v_lshlrev_b32_e32 v15, 1, v13
	v_and_b32_e32 v5, 0xc0, v5
	s_addc_u32 s42, s11, 0
	v_and_b32_e32 v12, 3, v10
	v_and_b32_e32 v14, 4, v14
	v_and_b32_e32 v15, 0x1fffd8, v15
	v_sub_u32_e32 v3, v3, v5
	v_readlane_b32 s10, v253, 60
	v_or3_b32 v14, v12, v14, v15
	v_lshlrev_b32_e32 v12, 5, v11
	v_ashrrev_i16_sdwa v3, v238, sext(v3) dst_sel:DWORD dst_unused:UNUSED_PAD src0_sel:DWORD src1_sel:BYTE_0
	v_readlane_b32 s11, v253, 61
	s_add_u32 s24, s41, s10
	v_and_b32_e32 v15, 32, v12
	v_bfe_i32 v12, v3, 0, 16
	s_addc_u32 s25, s42, s11
	s_add_i32 s43, s18, 0
	v_add_lshl_u32 v3, v15, v12, 1
	s_add_i32 s44, s43, 0x10000
	s_add_i32 s45, s43, 0x12000
	v_lshl_add_u32 v200, v14, 11, v3
	s_mov_b32 m0, s44
	s_add_u32 s10, s24, 0x10000
	global_load_lds_dwordx4 v200, s[24:25]
	s_mov_b32 m0, s45
	s_addc_u32 s11, s25, 0
	s_add_i32 s46, s43, 0x14000
	global_load_lds_dwordx4 v2, s[24:25]
	s_mov_b32 m0, s46
	s_add_i32 s47, s43, 0x16000
	global_load_lds_dwordx4 v200, s[10:11]
	s_mov_b32 m0, s47
	v_lshl_add_u32 v202, v13, 11, v3
	global_load_lds_dwordx4 v2, s[10:11]
	v_readlane_b32 s10, v253, 58
	v_readlane_b32 s11, v253, 59
	s_add_u32 s26, s39, s10
	s_addc_u32 s27, s40, s11
	s_add_i32 s48, s43, 0x2000
	s_mov_b32 m0, s43
	s_add_u32 s10, s26, 0x40000
	global_load_lds_dwordx4 v202, s[26:27]
	s_mov_b32 m0, s48
	s_addc_u32 s11, s27, 0
	s_add_i32 s49, s43, 0x4000
	v_mov_b32_e32 v201, v4
	global_load_lds_dwordx4 v198, s[26:27]
	s_mov_b32 m0, s49
	s_add_i32 s50, s43, 0x6000
	v_lshl_add_u64 v[14:15], s[24:25], 0, v[200:201]
	v_mov_b32_e32 v3, v4
	global_load_lds_dwordx4 v202, s[10:11]
	s_mov_b32 m0, s50
	s_add_i32 s51, s43, 0x18000
	v_lshl_add_u64 v[16:17], s[24:25], 0, v[2:3]
	v_mov_b32_e32 v203, v4
	global_load_lds_dwordx4 v198, s[10:11]
	v_lshl_add_u64 v[14:15], v[14:15], 0, s[68:69]
	s_mov_b32 m0, s51
	s_add_i32 s52, s43, 0x1a000
	v_lshl_add_u64 v[18:19], s[26:27], 0, v[202:203]
	v_mov_b32_e32 v199, v4
	global_load_lds_dwordx4 v[14:15], off
	v_lshl_add_u64 v[14:15], v[16:17], 0, s[68:69]
	s_mov_b32 m0, s52
	s_add_i32 s53, s43, 0x8000
	s_add_i32 s54, s43, 0xa000
	v_lshl_add_u64 v[20:21], s[26:27], 0, v[198:199]
	global_load_lds_dwordx4 v[14:15], off
	v_lshl_add_u64 v[14:15], v[18:19], 0, s[68:69]
	s_mov_b32 m0, s53
	s_add_u32 s10, s24, 0x10080
	global_load_lds_dwordx4 v[14:15], off
	v_lshl_add_u64 v[14:15], v[20:21], 0, s[68:69]
	s_mov_b32 m0, s54
	s_addc_u32 s11, s25, 0
	s_add_i32 s55, s43, 0x1c000
	global_load_lds_dwordx4 v[14:15], off
	s_mov_b32 m0, s55
	s_add_i32 s56, s43, 0x1e000
	global_load_lds_dwordx4 v200, s[10:11]
	s_mov_b32 m0, s56
	s_cmp_eq_u32 s16, 1
	global_load_lds_dwordx4 v2, s[10:11]
	s_mov_b64 s[10:11], s[100:101]
	s_nop 0
	s_mov_b64 s[8:9], s[100:101]
	s_cselect_b64 s[2:3], -1, 0
	s_cmp_lg_u32 s16, 1
	s_cbranch_scc1 .LBB0_767
	s_barrier

.LBB0_812:
	s_or_b64 exec, exec, s[2:3]
	s_and_b64 vcc, exec, s[50:51]
	s_barrier
	s_cbranch_vccnz .LBB0_814
	s_mov_b32 s2, s87
	s_ashr_i32 s3, s2, 31
	s_lshl_b64 s[2:3], s[2:3], 3
	s_add_u32 s2, s0, s2
	s_addc_u32 s3, s1, s3
	s_mov_b64 s[2:3], s[100:101]
	s_mov_b32 s4, s87
	s_mov_b32 s6, s87
	v_mov_b32_e32 v145, v0
	s_waitcnt lgkmcnt(0)
	s_add_u32 s8, s2, s81
	s_addc_u32 s16, s3, 0
	s_ashr_i32 s5, s4, 31
	s_lshl_b64 s[2:3], s[4:5], 3
	s_add_u32 s2, s0, s2
	s_addc_u32 s3, s1, s3
	s_mov_b64 s[2:3], s[100:101]
	s_mov_b32 s5, s87
	s_mov_b32 s4, s87
	s_waitcnt lgkmcnt(0)
	s_add_u32 s2, s2, s84
	s_addc_u32 s3, s3, 0
	s_add_u32 s17, s2, 0x200000
	s_addc_u32 s18, s3, 0
	s_ashr_i32 s5, s4, 31
	s_lshl_b64 s[2:3], s[4:5], 3
	s_add_u32 s2, s0, s2
	s_addc_u32 s3, s1, s3
	s_load_dwordx2 s[2:3], s[2:3], 0xd0
	v_mov_b32_e32 v143, v4
	s_waitcnt lgkmcnt(0)
	s_add_u32 s2, s2, s80
	s_addc_u32 s3, s3, 0
	s_lshl_b32 s4, s46, 19
	s_add_u32 s2, s2, s4
	s_addc_u32 s3, s3, 0
	v_readlane_b32 s4, v253, 62
	v_readlane_b32 s5, v253, 63
	s_add_u32 s2, s2, s4
	s_addc_u32 s3, s3, s5
	s_add_u32 s4, s2, 0xe00000
	s_addc_u32 s5, s3, 0
	s_ashr_i32 s7, s6, 31
	s_lshl_b64 s[2:3], s[6:7], 3
	s_add_u32 s2, s0, s2
	s_addc_u32 s3, s1, s3
	s_mov_b64 s[2:3], s[100:101]
	s_waitcnt lgkmcnt(0)
	s_add_u32 s2, s2, s81
	v_readfirstlane_b32 s6, v145
	s_addc_u32 s3, s3, 0
	s_ashr_i32 s9, s6, 6
	s_lshl_b32 s10, s9, 5
	s_lshl_b64 s[6:7], s[74:75], 8
	s_ashr_i32 s11, s10, 31
	s_add_u32 s19, s6, s10
	s_addc_u32 s20, s7, s11
	s_lshl_b32 s6, s78, 2
	s_ashr_i32 s7, s6, 31
	s_lshl_b64 s[10:11], s[6:7], 14
	s_add_u32 s10, s17, s10
	s_addc_u32 s11, s18, s11
	s_or_b32 s12, s6, 1
	s_ashr_i32 s13, s12, 31
	s_lshl_b64 s[12:13], s[12:13], 14
	s_add_u32 s12, s17, s12
	s_addc_u32 s13, s18, s13
	s_or_b32 s14, s6, 2
	s_ashr_i32 s15, s14, 31
	s_lshl_b64 s[14:15], s[14:15], 14
	s_add_u32 s14, s17, s14
	s_addc_u32 s15, s18, s15
	s_or_b32 s6, s6, 3
	v_and_b32_e32 v144, 15, v145
	s_ashr_i32 s7, s6, 31
	s_lshl_b64 s[6:7], s[6:7], 14
	v_or_b32_e32 v6, s19, v144
	s_add_u32 s6, s17, s6
	v_mov_b32_e32 v5, v6
	s_addc_u32 s7, s18, s7
	v_ashrrev_i64 v[2:3], 30, v[4:5]
	v_mov_b32_e32 v7, s20
	v_lshl_add_u64 v[8:9], s[10:11], 0, v[2:3]
	v_lshl_add_u64 v[10:11], s[12:13], 0, v[2:3]
	v_lshl_add_u64 v[12:13], s[14:15], 0, v[2:3]
	v_lshl_add_u64 v[2:3], s[6:7], 0, v[2:3]
	global_load_dword v14, v[8:9], off
	global_load_dword v16, v[10:11], off
	global_load_dword v15, v[12:13], off
	global_load_dword v17, v[2:3], off
	v_lshlrev_b64 v[2:3], 11, v[6:7]
	v_or_b32_e32 v6, 16, v6
	v_mov_b32_e32 v5, v6
	v_ashrrev_i64 v[8:9], 30, v[4:5]
	v_lshl_add_u64 v[10:11], s[10:11], 0, v[8:9]
	v_lshl_add_u64 v[12:13], s[12:13], 0, v[8:9]
	v_lshl_add_u64 v[18:19], s[14:15], 0, v[8:9]
	v_lshl_add_u64 v[8:9], s[6:7], 0, v[8:9]
	s_lshl_b32 s6, s78, 8
	s_ashr_i32 s7, s6, 31
	s_lshl_b64 s[6:7], s[6:7], 1
	s_add_u32 s10, s8, s6
	s_addc_u32 s11, s16, s7
	v_and_b32_e32 v142, 48, v145
	global_load_dword v20, v[10:11], off
	global_load_dword v22, v[12:13], off
	global_load_dword v21, v[18:19], off
	global_load_dword v23, v[8:9], off
	v_lshl_add_u64 v[8:9], s[10:11], 0, v[142:143]
	s_mov_b64 s[10:11], 0x9e00000
	v_lshl_add_u64 v[8:9], v[8:9], 0, s[10:11]
	v_lshlrev_b64 v[6:7], 11, v[6:7]
	v_lshl_add_u64 v[10:11], v[8:9], 0, v[2:3]
	v_lshl_add_u64 v[6:7], v[8:9], 0, v[6:7]
	global_load_dwordx4 v[66:69], v[10:11], off
	global_load_dwordx4 v[62:65], v[10:11], off offset:64
	global_load_dwordx4 v[58:61], v[10:11], off offset:128
	global_load_dwordx4 v[54:57], v[10:11], off offset:192
	global_load_dwordx4 v[50:53], v[10:11], off offset:256
	global_load_dwordx4 v[46:49], v[10:11], off offset:320
	global_load_dwordx4 v[42:45], v[10:11], off offset:384
	global_load_dwordx4 v[38:41], v[10:11], off offset:448
	global_load_dwordx4 v[98:101], v[6:7], off
	global_load_dwordx4 v[94:97], v[6:7], off offset:64
	global_load_dwordx4 v[90:93], v[6:7], off offset:128
	global_load_dwordx4 v[86:89], v[6:7], off offset:192
	global_load_dwordx4 v[82:85], v[6:7], off offset:256
	global_load_dwordx4 v[78:81], v[6:7], off offset:320
	global_load_dwordx4 v[74:77], v[6:7], off offset:384
	global_load_dwordx4 v[70:73], v[6:7], off offset:448
	v_bfe_u32 v5, v145, 4, 2
	v_bitop3_b32 v6, v5, v145, 15 bitop3:0x78
	v_bitop3_b32 v8, v5, v144, 8 bitop3:0x36
	v_bitop3_b32 v30, v5, v144, 24 bitop3:0x36
	v_lshl_add_u32 v134, v144, 9, 0
	v_bitop3_b32 v7, v5, v144, 4 bitop3:0x36
	v_bitop3_b32 v9, v5, v144, 12 bitop3:0x36
	v_lshlrev_b32_e32 v149, 4, v6
	v_lshlrev_b32_e32 v136, 4, v8
	v_lshlrev_b32_e32 v152, 4, v30
	v_lshlrev_b32_e32 v137, 4, v7
	v_lshlrev_b32_e32 v135, 4, v9
	v_add_u32_e32 v170, v134, v149
	v_add_u32_e32 v172, v134, v136
	v_add_u32_e32 v176, v134, v152
	v_add_u32_e32 v171, v134, v137
	v_add_u32_e32 v173, v134, v135
	s_waitcnt vmcnt(0)
	s_barrier
	ds_read_b128 v[6:9], v170
	ds_read_b128 v[10:13], v171
	v_lshrrev_b32_e32 v146, 1, v145
	s_lshl_b32 s8, s9, 3
	s_waitcnt vmcnt(20)
	v_pk_add_f32 v[14:15], v[14:15], v[16:17]
	s_nop 0
	v_add_f32_e32 v14, v14, v15
	v_fmamk_f32 v14, v14, 0x3b800000, v236
	v_rsq_f32_e32 v148, v14
	s_waitcnt vmcnt(16)
	v_pk_add_f32 v[16:17], v[20:21], v[22:23]
	v_bitop3_b32 v22, v5, v144, 16 bitop3:0x36
	v_lshlrev_b32_e32 v150, 4, v22
	v_bitop3_b32 v22, v5, v144, 20 bitop3:0x36
	v_bitop3_b32 v5, v5, v144, 28 bitop3:0x36
	v_add_f32_e32 v15, v16, v17
	v_add_u32_e32 v174, v134, v150
	v_lshlrev_b32_e32 v151, 4, v22
	v_lshlrev_b32_e32 v153, 4, v5
	v_fmamk_f32 v102, v15, 0x3b800000, v236
	ds_read_b128 v[14:17], v172
	ds_read_b128 v[18:21], v173
	v_add_u32_e32 v175, v134, v151
	ds_read_b128 v[22:25], v174
	ds_read_b128 v[26:29], v175
	v_add_u32_e32 v177, v134, v153
	ds_read_b128 v[30:33], v176
	ds_read_b128 v[34:37], v177
	v_rsq_f32_e32 v147, v102
	v_and_b32_e32 v5, 63, v145
	s_setprio 1
	s_waitcnt vmcnt(15) lgkmcnt(7)
	v_mfma_f32_16x16x32_bf16 v[102:105], v[6:9], v[66:69], 0
	s_waitcnt vmcnt(7)
	v_mfma_f32_16x16x32_bf16 v[6:9], v[6:9], v[98:101], 0
	s_waitcnt lgkmcnt(6)
	v_mfma_f32_16x16x32_bf16 v[102:105], v[10:13], v[62:65], v[102:105]
	s_waitcnt vmcnt(6)
	v_mfma_f32_16x16x32_bf16 v[6:9], v[10:13], v[94:97], v[6:9]
	s_waitcnt lgkmcnt(5)
	v_mfma_f32_16x16x32_bf16 v[10:13], v[14:17], v[58:61], v[102:105]
	s_waitcnt vmcnt(5)
	v_mfma_f32_16x16x32_bf16 v[6:9], v[14:17], v[90:93], v[6:9]
	s_waitcnt lgkmcnt(4)
	v_mfma_f32_16x16x32_bf16 v[10:13], v[18:21], v[54:57], v[10:13]
	s_waitcnt vmcnt(4)
	v_mfma_f32_16x16x32_bf16 v[6:9], v[18:21], v[86:89], v[6:9]
	s_setprio 0
	ds_read_b128 v[14:17], v170 offset:8192
	ds_read_b128 v[18:21], v171 offset:8192
	ds_read_b128 v[102:105], v172 offset:8192
	ds_read_b128 v[106:109], v173 offset:8192
	s_setprio 1
	s_waitcnt lgkmcnt(7)
	v_mfma_f32_16x16x32_bf16 v[10:13], v[22:25], v[50:53], v[10:13]
	s_waitcnt vmcnt(3)
	v_mfma_f32_16x16x32_bf16 v[6:9], v[22:25], v[82:85], v[6:9]
	s_waitcnt lgkmcnt(6)
	v_mfma_f32_16x16x32_bf16 v[10:13], v[26:29], v[46:49], v[10:13]
	s_waitcnt vmcnt(2)
	v_mfma_f32_16x16x32_bf16 v[6:9], v[26:29], v[78:81], v[6:9]
	s_waitcnt lgkmcnt(5)
	v_mfma_f32_16x16x32_bf16 v[10:13], v[30:33], v[42:45], v[10:13]
	s_waitcnt vmcnt(1)
	v_mfma_f32_16x16x32_bf16 v[6:9], v[30:33], v[74:77], v[6:9]
	s_waitcnt lgkmcnt(4)
	v_mfma_f32_16x16x32_bf16 v[10:13], v[34:37], v[38:41], v[10:13]
	s_waitcnt vmcnt(0)
	v_mfma_f32_16x16x32_bf16 v[22:25], v[34:37], v[70:73], v[6:9]
	s_setprio 0
	s_nop 2
	ds_read_b128 v[6:9], v174 offset:8192
	ds_read_b128 v[26:29], v175 offset:8192
	ds_read_b128 v[30:33], v176 offset:8192
	ds_read_b128 v[34:37], v177 offset:8192
	s_setprio 1
	s_waitcnt lgkmcnt(7)
	v_mfma_f32_16x16x32_bf16 v[110:113], v[14:17], v[66:69], 0
	v_mfma_f32_16x16x32_bf16 v[14:17], v[14:17], v[98:101], 0
	s_waitcnt lgkmcnt(6)
	v_mfma_f32_16x16x32_bf16 v[110:113], v[18:21], v[62:65], v[110:113]
	v_mfma_f32_16x16x32_bf16 v[14:17], v[18:21], v[94:97], v[14:17]
	s_waitcnt lgkmcnt(5)
	v_mfma_f32_16x16x32_bf16 v[18:21], v[102:105], v[58:61], v[110:113]
	v_mfma_f32_16x16x32_bf16 v[14:17], v[102:105], v[90:93], v[14:17]
	s_waitcnt lgkmcnt(4)
	v_mfma_f32_16x16x32_bf16 v[18:21], v[106:109], v[54:57], v[18:21]
	v_mfma_f32_16x16x32_bf16 v[14:17], v[106:109], v[86:89], v[14:17]
	s_setprio 0
	ds_read_b128 v[102:105], v170 offset:16384
	ds_read_b128 v[106:109], v171 offset:16384
	ds_read_b128 v[110:113], v172 offset:16384
	ds_read_b128 v[114:117], v173 offset:16384
	s_setprio 1
	s_waitcnt lgkmcnt(7)
	v_mfma_f32_16x16x32_bf16 v[18:21], v[6:9], v[50:53], v[18:21]
	v_mfma_f32_16x16x32_bf16 v[6:9], v[6:9], v[82:85], v[14:17]
	s_waitcnt lgkmcnt(6)
	v_mfma_f32_16x16x32_bf16 v[14:17], v[26:29], v[46:49], v[18:21]
	v_mfma_f32_16x16x32_bf16 v[6:9], v[26:29], v[78:81], v[6:9]
	s_waitcnt lgkmcnt(5)
	v_mfma_f32_16x16x32_bf16 v[14:17], v[30:33], v[42:45], v[14:17]
	v_mfma_f32_16x16x32_bf16 v[6:9], v[30:33], v[74:77], v[6:9]
	s_waitcnt lgkmcnt(4)
	v_mfma_f32_16x16x32_bf16 v[14:17], v[34:37], v[38:41], v[14:17]
	v_mfma_f32_16x16x32_bf16 v[26:29], v[34:37], v[70:73], v[6:9]
	s_setprio 0
	s_nop 3
	ds_read_b128 v[6:9], v174 offset:16384
	ds_read_b128 v[18:21], v175 offset:16384
	ds_read_b128 v[30:33], v176 offset:16384
	ds_read_b128 v[34:37], v177 offset:16384
	s_setprio 1
	s_waitcnt lgkmcnt(7)
	v_mfma_f32_16x16x32_bf16 v[118:121], v[102:105], v[66:69], 0
	v_mfma_f32_16x16x32_bf16 v[102:105], v[102:105], v[98:101], 0
	s_waitcnt lgkmcnt(6)
	v_mfma_f32_16x16x32_bf16 v[118:121], v[106:109], v[62:65], v[118:121]
	v_mfma_f32_16x16x32_bf16 v[102:105], v[106:109], v[94:97], v[102:105]
	s_waitcnt lgkmcnt(5)
	v_mfma_f32_16x16x32_bf16 v[106:109], v[110:113], v[58:61], v[118:121]
	v_mfma_f32_16x16x32_bf16 v[102:105], v[110:113], v[90:93], v[102:105]
	s_waitcnt lgkmcnt(4)
	v_mfma_f32_16x16x32_bf16 v[106:109], v[114:117], v[54:57], v[106:109]
	v_mfma_f32_16x16x32_bf16 v[102:105], v[114:117], v[86:89], v[102:105]
	s_setprio 0
	ds_read_b128 v[110:113], v170 offset:24576
	ds_read_b128 v[114:117], v171 offset:24576
	ds_read_b128 v[118:121], v172 offset:24576
	ds_read_b128 v[122:125], v173 offset:24576
	s_setprio 1
	s_waitcnt lgkmcnt(7)
	v_mfma_f32_16x16x32_bf16 v[106:109], v[6:9], v[50:53], v[106:109]
	v_mfma_f32_16x16x32_bf16 v[6:9], v[6:9], v[82:85], v[102:105]
	s_waitcnt lgkmcnt(6)
	v_mfma_f32_16x16x32_bf16 v[102:105], v[18:21], v[46:49], v[106:109]
	v_mfma_f32_16x16x32_bf16 v[6:9], v[18:21], v[78:81], v[6:9]
	s_waitcnt lgkmcnt(5)
	v_mfma_f32_16x16x32_bf16 v[18:21], v[30:33], v[42:45], v[102:105]
	v_mfma_f32_16x16x32_bf16 v[6:9], v[30:33], v[74:77], v[6:9]
	s_waitcnt lgkmcnt(4)
	v_mfma_f32_16x16x32_bf16 v[18:21], v[34:37], v[38:41], v[18:21]
	v_mfma_f32_16x16x32_bf16 v[30:33], v[34:37], v[70:73], v[6:9]
	s_setprio 0
	s_nop 3
	ds_read_b128 v[6:9], v174 offset:24576
	ds_read_b128 v[34:37], v175 offset:24576
	ds_read_b128 v[102:105], v176 offset:24576
	ds_read_b128 v[106:109], v177 offset:24576
	s_setprio 1
	s_waitcnt lgkmcnt(7)
	v_mfma_f32_16x16x32_bf16 v[126:129], v[110:113], v[66:69], 0
	v_mfma_f32_16x16x32_bf16 v[110:113], v[110:113], v[98:101], 0
	s_waitcnt lgkmcnt(6)
	v_mfma_f32_16x16x32_bf16 v[126:129], v[114:117], v[62:65], v[126:129]
	v_mfma_f32_16x16x32_bf16 v[110:113], v[114:117], v[94:97], v[110:113]
	s_waitcnt lgkmcnt(5)
	v_mfma_f32_16x16x32_bf16 v[114:117], v[118:121], v[58:61], v[126:129]
	v_mfma_f32_16x16x32_bf16 v[110:113], v[118:121], v[90:93], v[110:113]
	s_waitcnt lgkmcnt(4)
	v_mfma_f32_16x16x32_bf16 v[114:117], v[122:125], v[54:57], v[114:117]
	v_mfma_f32_16x16x32_bf16 v[110:113], v[122:125], v[86:89], v[110:113]
	s_setprio 0
	ds_read_b128 v[118:121], v170 offset:32768
	ds_read_b128 v[122:125], v171 offset:32768
	ds_read_b128 v[126:129], v172 offset:32768
	ds_read_b128 v[130:133], v173 offset:32768
	s_setprio 1
	s_waitcnt lgkmcnt(7)
	v_mfma_f32_16x16x32_bf16 v[114:117], v[6:9], v[50:53], v[114:117]
	v_mfma_f32_16x16x32_bf16 v[6:9], v[6:9], v[82:85], v[110:113]
	s_waitcnt lgkmcnt(6)
	v_mfma_f32_16x16x32_bf16 v[110:113], v[34:37], v[46:49], v[114:117]
	v_mfma_f32_16x16x32_bf16 v[6:9], v[34:37], v[78:81], v[6:9]
	s_waitcnt lgkmcnt(5)
	v_mfma_f32_16x16x32_bf16 v[34:37], v[102:105], v[42:45], v[110:113]
	v_mfma_f32_16x16x32_bf16 v[6:9], v[102:105], v[74:77], v[6:9]
	s_waitcnt lgkmcnt(4)
	v_mfma_f32_16x16x32_bf16 v[114:117], v[106:109], v[38:41], v[34:37]
	v_mfma_f32_16x16x32_bf16 v[34:37], v[106:109], v[70:73], v[6:9]
	s_setprio 0
	s_nop 3
	ds_read_b128 v[6:9], v174 offset:32768
	ds_read_b128 v[102:105], v175 offset:32768
	ds_read_b128 v[106:109], v176 offset:32768
	ds_read_b128 v[110:113], v177 offset:32768
	s_setprio 1
	s_waitcnt lgkmcnt(7)
	v_mfma_f32_16x16x32_bf16 v[138:141], v[118:121], v[66:69], 0
	v_mfma_f32_16x16x32_bf16 v[118:121], v[118:121], v[98:101], 0
	s_waitcnt lgkmcnt(6)
	v_mfma_f32_16x16x32_bf16 v[138:141], v[122:125], v[62:65], v[138:141]
	v_mfma_f32_16x16x32_bf16 v[118:121], v[122:125], v[94:97], v[118:121]
	s_waitcnt lgkmcnt(5)
	v_mfma_f32_16x16x32_bf16 v[122:125], v[126:129], v[58:61], v[138:141]
	v_mfma_f32_16x16x32_bf16 v[118:121], v[126:129], v[90:93], v[118:121]
	s_waitcnt lgkmcnt(4)
	v_mfma_f32_16x16x32_bf16 v[122:125], v[130:133], v[54:57], v[122:125]
	v_mfma_f32_16x16x32_bf16 v[118:121], v[130:133], v[86:89], v[118:121]
	s_setprio 0
	ds_read_b128 v[126:129], v170 offset:40960
	ds_read_b128 v[130:133], v171 offset:40960
	ds_read_b128 v[138:141], v172 offset:40960
	ds_read_b128 v[154:157], v173 offset:40960
	s_setprio 1
	s_waitcnt lgkmcnt(7)
	v_mfma_f32_16x16x32_bf16 v[122:125], v[6:9], v[50:53], v[122:125]
	v_mfma_f32_16x16x32_bf16 v[6:9], v[6:9], v[82:85], v[118:121]
	s_waitcnt lgkmcnt(6)
	v_mfma_f32_16x16x32_bf16 v[118:121], v[102:105], v[46:49], v[122:125]
	v_mfma_f32_16x16x32_bf16 v[6:9], v[102:105], v[78:81], v[6:9]
	s_waitcnt lgkmcnt(5)
	v_mfma_f32_16x16x32_bf16 v[102:105], v[106:109], v[42:45], v[118:121]
	v_mfma_f32_16x16x32_bf16 v[6:9], v[106:109], v[74:77], v[6:9]
	s_waitcnt lgkmcnt(4)
	v_mfma_f32_16x16x32_bf16 v[118:121], v[110:113], v[38:41], v[102:105]
	v_mfma_f32_16x16x32_bf16 v[102:105], v[110:113], v[70:73], v[6:9]
	s_setprio 0
	s_nop 3
	ds_read_b128 v[6:9], v174 offset:40960
	ds_read_b128 v[106:109], v175 offset:40960
	ds_read_b128 v[110:113], v176 offset:40960
	ds_read_b128 v[122:125], v177 offset:40960
	s_setprio 1
	s_waitcnt lgkmcnt(7)
	v_mfma_f32_16x16x32_bf16 v[158:161], v[126:129], v[66:69], 0
	v_mfma_f32_16x16x32_bf16 v[126:129], v[126:129], v[98:101], 0
	s_waitcnt lgkmcnt(6)
	v_mfma_f32_16x16x32_bf16 v[158:161], v[130:133], v[62:65], v[158:161]
	v_mfma_f32_16x16x32_bf16 v[126:129], v[130:133], v[94:97], v[126:129]
	s_waitcnt lgkmcnt(5)
	v_mfma_f32_16x16x32_bf16 v[130:133], v[138:141], v[58:61], v[158:161]
	v_mfma_f32_16x16x32_bf16 v[126:129], v[138:141], v[90:93], v[126:129]
	s_waitcnt lgkmcnt(4)
	v_mfma_f32_16x16x32_bf16 v[130:133], v[154:157], v[54:57], v[130:133]
	v_mfma_f32_16x16x32_bf16 v[126:129], v[154:157], v[86:89], v[126:129]
	s_setprio 0
	ds_read_b128 v[138:141], v170 offset:49152
	ds_read_b128 v[154:157], v171 offset:49152
	ds_read_b128 v[158:161], v172 offset:49152
	ds_read_b128 v[162:165], v173 offset:49152
	s_setprio 1
	s_waitcnt lgkmcnt(7)
	v_mfma_f32_16x16x32_bf16 v[130:133], v[6:9], v[50:53], v[130:133]
	v_mfma_f32_16x16x32_bf16 v[6:9], v[6:9], v[82:85], v[126:129]
	s_waitcnt lgkmcnt(6)
	v_mfma_f32_16x16x32_bf16 v[126:129], v[106:109], v[46:49], v[130:133]
	v_mfma_f32_16x16x32_bf16 v[6:9], v[106:109], v[78:81], v[6:9]
	s_waitcnt lgkmcnt(5)
	v_mfma_f32_16x16x32_bf16 v[106:109], v[110:113], v[42:45], v[126:129]
	v_mfma_f32_16x16x32_bf16 v[6:9], v[110:113], v[74:77], v[6:9]
	s_waitcnt lgkmcnt(4)
	v_mfma_f32_16x16x32_bf16 v[126:129], v[122:125], v[38:41], v[106:109]
	v_mfma_f32_16x16x32_bf16 v[106:109], v[122:125], v[70:73], v[6:9]
	s_setprio 0
	s_nop 3
	ds_read_b128 v[6:9], v174 offset:49152
	ds_read_b128 v[110:113], v175 offset:49152
	ds_read_b128 v[122:125], v176 offset:49152
	ds_read_b128 v[130:133], v177 offset:49152
	s_setprio 1
	s_waitcnt lgkmcnt(7)
	v_mfma_f32_16x16x32_bf16 v[166:169], v[138:141], v[66:69], 0
	v_mfma_f32_16x16x32_bf16 v[138:141], v[138:141], v[98:101], 0
	s_waitcnt lgkmcnt(6)
	v_mfma_f32_16x16x32_bf16 v[166:169], v[154:157], v[62:65], v[166:169]
	v_mfma_f32_16x16x32_bf16 v[138:141], v[154:157], v[94:97], v[138:141]
	s_waitcnt lgkmcnt(5)
	v_mfma_f32_16x16x32_bf16 v[154:157], v[158:161], v[58:61], v[166:169]
	v_mfma_f32_16x16x32_bf16 v[138:141], v[158:161], v[90:93], v[138:141]
	s_waitcnt lgkmcnt(4)
	v_mfma_f32_16x16x32_bf16 v[154:157], v[162:165], v[54:57], v[154:157]
	v_mfma_f32_16x16x32_bf16 v[138:141], v[162:165], v[86:89], v[138:141]
	s_setprio 0
	ds_read_b128 v[158:161], v170 offset:57344
	ds_read_b128 v[162:165], v171 offset:57344
	ds_read_b128 v[166:169], v172 offset:57344
	ds_read_b128 v[170:173], v173 offset:57344
	s_setprio 1
	s_waitcnt lgkmcnt(7)
	v_mfma_f32_16x16x32_bf16 v[154:157], v[6:9], v[50:53], v[154:157]
	v_mfma_f32_16x16x32_bf16 v[6:9], v[6:9], v[82:85], v[138:141]
	s_waitcnt lgkmcnt(6)
	v_mfma_f32_16x16x32_bf16 v[138:141], v[110:113], v[46:49], v[154:157]
	v_mfma_f32_16x16x32_bf16 v[6:9], v[110:113], v[78:81], v[6:9]
	s_waitcnt lgkmcnt(5)
	v_mfma_f32_16x16x32_bf16 v[110:113], v[122:125], v[42:45], v[138:141]
	v_mfma_f32_16x16x32_bf16 v[6:9], v[122:125], v[74:77], v[6:9]
	s_waitcnt lgkmcnt(4)
	v_mfma_f32_16x16x32_bf16 v[122:125], v[130:133], v[38:41], v[110:113]
	v_mfma_f32_16x16x32_bf16 v[110:113], v[130:133], v[70:73], v[6:9]
	s_setprio 0
	s_nop 3
	ds_read_b128 v[6:9], v174 offset:57344
	ds_read_b128 v[130:133], v175 offset:57344
	ds_read_b128 v[138:141], v176 offset:57344
	ds_read_b128 v[154:157], v177 offset:57344
	s_setprio 1
	s_waitcnt lgkmcnt(7)
	v_mfma_f32_16x16x32_bf16 v[174:177], v[158:161], v[66:69], 0
	v_mfma_f32_16x16x32_bf16 v[158:161], v[158:161], v[98:101], 0
	s_waitcnt lgkmcnt(6)
	v_mfma_f32_16x16x32_bf16 v[174:177], v[162:165], v[62:65], v[174:177]
	v_mfma_f32_16x16x32_bf16 v[158:161], v[162:165], v[94:97], v[158:161]
	s_waitcnt lgkmcnt(5)
	v_mfma_f32_16x16x32_bf16 v[162:165], v[166:169], v[58:61], v[174:177]
	v_mfma_f32_16x16x32_bf16 v[158:161], v[166:169], v[90:93], v[158:161]
	s_waitcnt lgkmcnt(4)
	v_mfma_f32_16x16x32_bf16 v[162:165], v[170:173], v[54:57], v[162:165]
	v_mfma_f32_16x16x32_bf16 v[158:161], v[170:173], v[86:89], v[158:161]
	s_setprio 0
	s_setprio 1
	s_waitcnt lgkmcnt(3)
	v_mfma_f32_16x16x32_bf16 v[162:165], v[6:9], v[50:53], v[162:165]
	v_mfma_f32_16x16x32_bf16 v[6:9], v[6:9], v[82:85], v[158:161]
	s_waitcnt lgkmcnt(2)
	v_mfma_f32_16x16x32_bf16 v[158:161], v[130:133], v[46:49], v[162:165]
	v_mfma_f32_16x16x32_bf16 v[6:9], v[130:133], v[78:81], v[6:9]
	s_waitcnt lgkmcnt(1)
	v_mfma_f32_16x16x32_bf16 v[130:133], v[138:141], v[42:45], v[158:161]
	v_mfma_f32_16x16x32_bf16 v[6:9], v[138:141], v[74:77], v[6:9]
	s_waitcnt lgkmcnt(0)
	v_mfma_f32_16x16x32_bf16 v[130:133], v[154:157], v[38:41], v[130:133]
	v_mfma_f32_16x16x32_bf16 v[138:141], v[154:157], v[70:73], v[6:9]
	s_setprio 0
	s_nop 3
	v_mul_f32_e32 v7, v148, v14
	v_mul_f32_e32 v6, v148, v10
	v_exp_f32_e32 v8, v7
	v_mul_f32_e32 v7, v148, v11
	v_mul_f32_e32 v10, v148, v12
	v_mul_f32_e32 v12, v148, v13
	v_exp_f32_e32 v6, v6
	v_exp_f32_e32 v7, v7
	v_mul_f32_e32 v9, v148, v15
	v_exp_f32_e32 v10, v10
	v_mul_f32_e32 v11, v148, v16
	v_exp_f32_e32 v12, v12
	v_mul_f32_e32 v13, v148, v17
	v_exp_f32_e32 v9, v9
	v_exp_f32_e32 v11, v11
	v_exp_f32_e32 v13, v13
	v_add_f32_e32 v14, v6, v7
	v_add_f32_e32 v15, v10, v12
	v_add_f32_e32 v14, v14, v15
	v_add_f32_e32 v15, v8, v9
	v_add_f32_e32 v16, v11, v13
	v_add_f32_e32 v15, v15, v16
	v_cvt_pk_bf16_f32 v8, v8, v9
	v_cvt_pk_bf16_f32 v9, v11, v13
	v_mul_f32_e32 v11, v148, v114
	v_add_f32_e32 v14, v14, v15
	v_cvt_pk_bf16_f32 v6, v6, v7
	v_cvt_pk_bf16_f32 v7, v10, v12
	v_mul_f32_e32 v10, v148, v18
	v_exp_f32_e32 v12, v11
	v_mul_f32_e32 v11, v148, v19
	v_mul_f32_e32 v15, v148, v20
	v_mul_f32_e32 v17, v148, v21
	v_exp_f32_e32 v10, v10
	v_exp_f32_e32 v11, v11
	v_mul_f32_e32 v13, v148, v115
	v_exp_f32_e32 v15, v15
	v_mul_f32_e32 v16, v148, v116
	v_exp_f32_e32 v17, v17
	v_mul_f32_e32 v18, v148, v117
	v_exp_f32_e32 v13, v13
	v_exp_f32_e32 v16, v16
	v_exp_f32_e32 v18, v18
	v_add_f32_e32 v19, v10, v11
	v_add_f32_e32 v20, v15, v17
	v_add_f32_e32 v19, v19, v20
	v_add_f32_e32 v20, v12, v13
	v_add_f32_e32 v21, v16, v18
	v_add_f32_e32 v20, v20, v21
	v_add_f32_e32 v14, 0, v14
	v_add_f32_e32 v19, v19, v20
	v_add_f32_e32 v14, v14, v19
	v_cvt_pk_bf16_f32 v10, v10, v11
	v_cvt_pk_bf16_f32 v11, v15, v17
	v_mul_f32_e32 v15, v148, v118
	v_mul_f32_e32 v17, v148, v119
	v_mul_f32_e32 v19, v148, v120
	v_mul_f32_e32 v21, v148, v121
	v_cvt_pk_bf16_f32 v12, v12, v13
	v_cvt_pk_bf16_f32 v13, v16, v18
	v_exp_f32_e32 v15, v15
	v_mul_f32_e32 v16, v148, v126
	v_exp_f32_e32 v17, v17
	v_mul_f32_e32 v18, v148, v127
	v_exp_f32_e32 v19, v19
	v_mul_f32_e32 v20, v148, v128
	v_exp_f32_e32 v21, v21
	v_mul_f32_e32 v114, v148, v129
	v_exp_f32_e32 v16, v16
	v_exp_f32_e32 v18, v18
	v_exp_f32_e32 v20, v20
	v_exp_f32_e32 v114, v114
	v_add_f32_e32 v115, v15, v17
	v_add_f32_e32 v116, v19, v21
	v_add_f32_e32 v115, v115, v116
	v_add_f32_e32 v116, v16, v18
	v_add_f32_e32 v117, v20, v114
	v_add_f32_e32 v116, v116, v117
	v_add_f32_e32 v115, v115, v116
	v_add_f32_e32 v115, v14, v115
	v_cvt_pk_bf16_f32 v14, v15, v17
	v_cvt_pk_bf16_f32 v15, v19, v21
	v_mul_f32_e32 v19, v148, v130
	v_cvt_pk_bf16_f32 v16, v16, v18
	v_cvt_pk_bf16_f32 v17, v20, v114
	v_mul_f32_e32 v18, v148, v122
	v_exp_f32_e32 v20, v19
	v_mul_f32_e32 v19, v148, v123
	v_mul_f32_e32 v114, v148, v124
	v_mul_f32_e32 v117, v148, v125
	v_exp_f32_e32 v18, v18
	v_exp_f32_e32 v19, v19
	v_mul_f32_e32 v21, v148, v131
	v_exp_f32_e32 v114, v114
	v_mul_f32_e32 v116, v148, v132
	v_exp_f32_e32 v117, v117
	v_mul_f32_e32 v118, v148, v133
	v_exp_f32_e32 v21, v21
	v_exp_f32_e32 v116, v116
	v_exp_f32_e32 v118, v118
	v_mul_f32_e32 v22, v147, v22
	v_mul_f32_e32 v23, v147, v23
	v_mul_f32_e32 v24, v147, v24
	v_mul_f32_e32 v25, v147, v25
	v_add_f32_e32 v119, v18, v19
	v_add_f32_e32 v120, v114, v117
	v_exp_f32_e32 v22, v22
	v_mul_f32_e32 v26, v147, v26
	v_exp_f32_e32 v23, v23
	v_mul_f32_e32 v27, v147, v27
	v_exp_f32_e32 v24, v24
	v_exp_f32_e32 v25, v25
	v_add_f32_e32 v119, v119, v120
	v_add_f32_e32 v120, v20, v21
	v_add_f32_e32 v121, v116, v118
	v_exp_f32_e32 v26, v26
	v_exp_f32_e32 v27, v27
	v_mul_f32_e32 v28, v147, v28
	v_mul_f32_e32 v29, v147, v29
	v_add_f32_e32 v120, v120, v121
	v_exp_f32_e32 v28, v28
	v_exp_f32_e32 v29, v29
	v_add_f32_e32 v119, v119, v120
	v_add_f32_e32 v155, v115, v119
	v_cvt_pk_bf16_f32 v18, v18, v19
	v_cvt_pk_bf16_f32 v19, v114, v117
	v_add_f32_e32 v114, v22, v23
	v_add_f32_e32 v115, v24, v25
	v_add_f32_e32 v114, v114, v115
	v_add_f32_e32 v115, v26, v27
	v_cvt_pk_bf16_f32 v22, v22, v23
	v_cvt_pk_bf16_f32 v23, v24, v25
	v_cvt_pk_bf16_f32 v24, v26, v27
	v_mul_f32_e32 v27, v147, v34
	v_cvt_pk_bf16_f32 v20, v20, v21
	v_cvt_pk_bf16_f32 v21, v116, v118
	v_add_f32_e32 v116, v28, v29
	v_cvt_pk_bf16_f32 v25, v28, v29
	v_mul_f32_e32 v26, v147, v30
	v_exp_f32_e32 v28, v27
	v_mul_f32_e32 v27, v147, v31
	v_mul_f32_e32 v30, v147, v32
	v_mul_f32_e32 v32, v147, v33
	v_exp_f32_e32 v26, v26
	v_exp_f32_e32 v27, v27
	v_mul_f32_e32 v29, v147, v35
	v_exp_f32_e32 v30, v30
	v_mul_f32_e32 v31, v147, v36
	v_exp_f32_e32 v32, v32
	v_mul_f32_e32 v33, v147, v37
	v_exp_f32_e32 v29, v29
	v_exp_f32_e32 v31, v31
	v_exp_f32_e32 v33, v33
	v_add_f32_e32 v34, v26, v27
	v_add_f32_e32 v35, v30, v32
	v_add_f32_e32 v34, v34, v35
	v_add_f32_e32 v35, v28, v29
	v_add_f32_e32 v36, v31, v33
	v_add_f32_e32 v35, v35, v36
	v_cvt_pk_bf16_f32 v28, v28, v29
	v_cvt_pk_bf16_f32 v29, v31, v33
	v_mul_f32_e32 v31, v147, v106
	v_add_f32_e32 v34, v34, v35
	v_cvt_pk_bf16_f32 v26, v26, v27
	v_cvt_pk_bf16_f32 v27, v30, v32
	v_mul_f32_e32 v30, v147, v102
	v_exp_f32_e32 v32, v31
	v_mul_f32_e32 v31, v147, v103
	v_mul_f32_e32 v35, v147, v104
	v_mul_f32_e32 v37, v147, v105
	v_exp_f32_e32 v30, v30
	v_exp_f32_e32 v31, v31
	v_mul_f32_e32 v33, v147, v107
	v_exp_f32_e32 v35, v35
	v_mul_f32_e32 v36, v147, v108
	v_exp_f32_e32 v37, v37
	v_mul_f32_e32 v102, v147, v109
	v_exp_f32_e32 v33, v33
	v_exp_f32_e32 v36, v36
	v_exp_f32_e32 v102, v102
	v_add_f32_e32 v115, v115, v116
	v_add_f32_e32 v103, v30, v31
	v_add_f32_e32 v104, v35, v37
	v_add_f32_e32 v114, v114, v115
	v_add_f32_e32 v103, v103, v104
	v_add_f32_e32 v104, v32, v33
	v_add_f32_e32 v105, v36, v102
	v_add_f32_e32 v114, 0, v114
	v_add_f32_e32 v104, v104, v105
	v_add_f32_e32 v34, v114, v34
	v_add_f32_e32 v103, v103, v104
	v_add_f32_e32 v34, v34, v103
	v_cvt_pk_bf16_f32 v30, v30, v31
	v_cvt_pk_bf16_f32 v31, v35, v37
	v_mul_f32_e32 v35, v147, v110
	v_mul_f32_e32 v37, v147, v111
	v_mul_f32_e32 v103, v147, v112
	v_mul_f32_e32 v105, v147, v113
	v_cvt_pk_bf16_f32 v32, v32, v33
	v_cvt_pk_bf16_f32 v33, v36, v102
	v_exp_f32_e32 v35, v35
	v_mul_f32_e32 v36, v147, v138
	v_exp_f32_e32 v37, v37
	v_mul_f32_e32 v102, v147, v139
	v_exp_f32_e32 v103, v103
	v_mul_f32_e32 v104, v147, v140
	v_exp_f32_e32 v105, v105
	v_mul_f32_e32 v106, v147, v141
	v_exp_f32_e32 v36, v36
	v_exp_f32_e32 v102, v102
	v_exp_f32_e32 v104, v104
	v_exp_f32_e32 v106, v106
	v_add_f32_e32 v107, v35, v37
	v_add_f32_e32 v108, v103, v105
	v_add_f32_e32 v107, v107, v108
	v_add_f32_e32 v108, v36, v102
	v_add_f32_e32 v109, v104, v106
	v_add_f32_e32 v108, v108, v109
	v_add_f32_e32 v107, v107, v108
	v_cvt_pk_bf16_f32 v36, v36, v102
	v_mov_b32_e32 v102, v5
	v_add_f32_e32 v154, v34, v107
	v_cvt_pk_bf16_f32 v34, v35, v37
	v_cvt_pk_bf16_f32 v37, v104, v106
	s_barrier
	v_cvt_pk_bf16_f32 v35, v103, v105
	v_mov_b32_e32 v105, v4
	v_ashrrev_i32_e32 v106, 5, v102
	v_and_b32_e32 v107, 31, v102
	v_lshl_add_u32 v102, s9, 4, v106
	v_lshrrev_b32_e32 v103, 1, v102
	v_and_b32_e32 v103, 12, v103
	v_and_b32_e32 v108, 3, v106
	v_bitop3_b32 v104, v103, v107, v108 bitop3:0x36
	v_ashrrev_i32_e32 v103, 31, v102
	v_lshlrev_b64 v[102:103], 9, v[102:103]
	v_lshl_add_u64 v[102:103], s[4:5], 0, v[102:103]
	v_lshlrev_b32_e32 v104, 4, v104
	s_lshl_b32 s9, s9, 13
	v_lshl_add_u64 v[102:103], v[102:103], 0, v[104:105]
	s_add_i32 m0, s9, 0
	s_or_b32 s9, s8, 1
	global_load_lds_dwordx4 v[102:103], off
	v_lshl_add_u32 v102, s9, 1, v106
	v_lshrrev_b32_e32 v103, 1, v102
	v_and_b32_e32 v103, 12, v103
	v_and_b32_e32 v104, 3, v102
	v_bitop3_b32 v104, v103, v107, v104 bitop3:0x36
	v_ashrrev_i32_e32 v103, 31, v102
	v_lshlrev_b64 v[102:103], 9, v[102:103]
	v_lshl_add_u64 v[102:103], s[4:5], 0, v[102:103]
	v_lshlrev_b32_e32 v104, 4, v104
	s_lshl_b32 s9, s9, 10
	v_lshl_add_u64 v[102:103], v[102:103], 0, v[104:105]
	s_add_i32 m0, s9, 0
	s_or_b32 s9, s8, 2
	global_load_lds_dwordx4 v[102:103], off
	v_lshl_add_u32 v102, s9, 1, v106
	v_lshrrev_b32_e32 v103, 1, v102
	v_and_b32_e32 v103, 12, v103
	v_bitop3_b32 v104, v103, v107, v108 bitop3:0x36
	v_ashrrev_i32_e32 v103, 31, v102
	v_lshlrev_b64 v[102:103], 9, v[102:103]
	v_lshl_add_u64 v[102:103], s[4:5], 0, v[102:103]
	v_lshlrev_b32_e32 v104, 4, v104
	s_lshl_b32 s9, s9, 10
	v_lshl_add_u64 v[102:103], v[102:103], 0, v[104:105]
	s_add_i32 m0, s9, 0
	s_or_b32 s9, s8, 3
	global_load_lds_dwordx4 v[102:103], off
	v_lshl_add_u32 v102, s9, 1, v106
	v_lshrrev_b32_e32 v103, 1, v102
	v_and_b32_e32 v103, 12, v103
	v_and_b32_e32 v104, 3, v102
	v_bitop3_b32 v104, v103, v107, v104 bitop3:0x36
	v_ashrrev_i32_e32 v103, 31, v102
	v_lshlrev_b64 v[102:103], 9, v[102:103]
	v_lshl_add_u64 v[102:103], s[4:5], 0, v[102:103]
	v_lshlrev_b32_e32 v104, 4, v104
	s_lshl_b32 s9, s9, 10
	v_lshl_add_u64 v[102:103], v[102:103], 0, v[104:105]
	s_add_i32 m0, s9, 0
	s_or_b32 s9, s8, 4
	global_load_lds_dwordx4 v[102:103], off
	v_lshl_add_u32 v102, s9, 1, v106
	v_lshrrev_b32_e32 v103, 1, v102
	v_and_b32_e32 v103, 12, v103
	v_bitop3_b32 v104, v103, v107, v108 bitop3:0x36
	v_ashrrev_i32_e32 v103, 31, v102
	v_lshlrev_b64 v[102:103], 9, v[102:103]
	v_lshl_add_u64 v[102:103], s[4:5], 0, v[102:103]
	v_lshlrev_b32_e32 v104, 4, v104
	s_lshl_b32 s9, s9, 10
	v_lshl_add_u64 v[102:103], v[102:103], 0, v[104:105]
	s_add_i32 m0, s9, 0
	s_or_b32 s9, s8, 5
	global_load_lds_dwordx4 v[102:103], off
	v_lshl_add_u32 v102, s9, 1, v106
	v_lshrrev_b32_e32 v103, 1, v102
	v_and_b32_e32 v103, 12, v103
	v_and_b32_e32 v104, 3, v102
	v_bitop3_b32 v104, v103, v107, v104 bitop3:0x36
	v_ashrrev_i32_e32 v103, 31, v102
	v_lshlrev_b64 v[102:103], 9, v[102:103]
	v_lshl_add_u64 v[102:103], s[4:5], 0, v[102:103]
	v_lshlrev_b32_e32 v104, 4, v104
	s_lshl_b32 s9, s9, 10
	v_lshl_add_u64 v[102:103], v[102:103], 0, v[104:105]
	s_add_i32 m0, s9, 0
	s_or_b32 s9, s8, 6
	global_load_lds_dwordx4 v[102:103], off
	v_lshl_add_u32 v102, s9, 1, v106
	v_lshrrev_b32_e32 v103, 1, v102
	v_and_b32_e32 v103, 12, v103
	v_bitop3_b32 v104, v103, v107, v108 bitop3:0x36
	v_ashrrev_i32_e32 v103, 31, v102
	v_lshlrev_b64 v[102:103], 9, v[102:103]
	v_lshl_add_u64 v[102:103], s[4:5], 0, v[102:103]
	v_lshlrev_b32_e32 v104, 4, v104
	s_lshl_b32 s9, s9, 10
	v_lshl_add_u64 v[102:103], v[102:103], 0, v[104:105]
	s_add_i32 m0, s9, 0
	s_or_b32 s9, s8, 7
	global_load_lds_dwordx4 v[102:103], off
	v_lshl_add_u32 v102, s9, 1, v106
	v_lshrrev_b32_e32 v103, 1, v102
	v_and_b32_e32 v103, 12, v103
	v_and_b32_e32 v104, 3, v102
	v_bitop3_b32 v104, v103, v107, v104 bitop3:0x36
	v_ashrrev_i32_e32 v103, 31, v102
	v_lshlrev_b64 v[102:103], 9, v[102:103]
	v_lshl_add_u64 v[102:103], s[4:5], 0, v[102:103]
	v_lshlrev_b32_e32 v104, 4, v104
	s_lshl_b32 s9, s9, 10
	v_lshl_add_u64 v[102:103], v[102:103], 0, v[104:105]
	s_add_i32 m0, s9, 0
	v_add_u32_e32 v130, 0x10000, v134
	global_load_lds_dwordx4 v[102:103], off
	v_add_u32_e32 v102, v130, v149
	v_add_u32_e32 v106, v130, v137
	v_add_u32_e32 v110, v130, v136
	v_add_u32_e32 v114, v130, v135
	v_add_u32_e32 v118, v130, v150
	v_add_u32_e32 v122, v130, v151
	v_add_u32_e32 v126, v130, v152
	v_add_u32_e32 v130, v130, v153
	ds_read_b128 v[102:105], v102
	ds_read_b128 v[106:109], v106
	ds_read_b128 v[110:113], v110
	ds_read_b128 v[114:117], v114
	ds_read_b128 v[118:121], v118
	ds_read_b128 v[122:125], v122
	ds_read_b128 v[126:129], v126
	ds_read_b128 v[130:133], v130
	s_setprio 1
	s_waitcnt lgkmcnt(0)
	v_mfma_f32_16x16x32_bf16 v[138:141], v[102:105], v[66:69], 0
	v_mfma_f32_16x16x32_bf16 v[102:105], v[102:105], v[98:101], 0
	v_mfma_f32_16x16x32_bf16 v[138:141], v[106:109], v[62:65], v[138:141]
	v_mfma_f32_16x16x32_bf16 v[102:105], v[106:109], v[94:97], v[102:105]
	v_mfma_f32_16x16x32_bf16 v[106:109], v[110:113], v[58:61], v[138:141]
	v_mfma_f32_16x16x32_bf16 v[102:105], v[110:113], v[90:93], v[102:105]
	v_mfma_f32_16x16x32_bf16 v[106:109], v[114:117], v[54:57], v[106:109]
	v_mfma_f32_16x16x32_bf16 v[102:105], v[114:117], v[86:89], v[102:105]
	s_setprio 0
	v_add_u32_e32 v160, 0x12000, v134
	v_add_u32_e32 v110, v160, v149
	v_add_u32_e32 v114, v160, v137
	v_add_u32_e32 v138, v160, v136
	v_add_u32_e32 v156, v160, v135
	ds_read_b128 v[110:113], v110
	ds_read_b128 v[114:117], v114
	ds_read_b128 v[138:141], v138
	ds_read_b128 v[156:159], v156
	s_setprio 1
	v_mfma_f32_16x16x32_bf16 v[106:109], v[118:121], v[50:53], v[106:109]
	v_mfma_f32_16x16x32_bf16 v[102:105], v[118:121], v[82:85], v[102:105]
	v_mfma_f32_16x16x32_bf16 v[106:109], v[122:125], v[46:49], v[106:109]
	v_mfma_f32_16x16x32_bf16 v[102:105], v[122:125], v[78:81], v[102:105]
	v_mfma_f32_16x16x32_bf16 v[106:109], v[126:129], v[42:45], v[106:109]
	v_mfma_f32_16x16x32_bf16 v[102:105], v[126:129], v[74:77], v[102:105]
	v_mfma_f32_16x16x32_bf16 v[122:125], v[130:133], v[38:41], v[106:109]
	v_mfma_f32_16x16x32_bf16 v[102:105], v[130:133], v[70:73], v[102:105]
	s_setprio 0
	s_nop 3
	v_add_u32_e32 v106, v160, v150
	v_add_u32_e32 v118, v160, v151
	v_add_u32_e32 v126, v160, v152
	ds_read_b128 v[106:109], v106
	ds_read_b128 v[118:121], v118
	v_add_u32_e32 v130, v160, v153
	ds_read_b128 v[126:129], v126
	ds_read_b128 v[160:163], v130
	s_setprio 1
	s_waitcnt lgkmcnt(0)
	v_mfma_f32_16x16x32_bf16 v[130:133], v[110:113], v[66:69], 0
	v_mfma_f32_16x16x32_bf16 v[110:113], v[110:113], v[98:101], 0
	v_mfma_f32_16x16x32_bf16 v[130:133], v[114:117], v[62:65], v[130:133]
	v_mfma_f32_16x16x32_bf16 v[110:113], v[114:117], v[94:97], v[110:113]
	v_mfma_f32_16x16x32_bf16 v[114:117], v[138:141], v[58:61], v[130:133]
	v_mfma_f32_16x16x32_bf16 v[110:113], v[138:141], v[90:93], v[110:113]
	v_mfma_f32_16x16x32_bf16 v[114:117], v[156:159], v[54:57], v[114:117]
	v_mfma_f32_16x16x32_bf16 v[110:113], v[156:159], v[86:89], v[110:113]
	s_setprio 0
	v_add_u32_e32 v172, 0x14000, v134
	s_nop 0
	v_add_u32_e32 v130, v172, v149
	v_add_u32_e32 v131, v172, v137
	ds_read_b128 v[138:141], v130
	ds_read_b128 v[156:159], v131
	v_add_u32_e32 v130, v172, v136
	v_add_u32_e32 v131, v172, v135
	ds_read_b128 v[164:167], v130
	ds_read_b128 v[168:171], v131
	s_setprio 1
	v_mfma_f32_16x16x32_bf16 v[114:117], v[106:109], v[50:53], v[114:117]
	v_mfma_f32_16x16x32_bf16 v[106:109], v[106:109], v[82:85], v[110:113]
	v_mfma_f32_16x16x32_bf16 v[110:113], v[118:121], v[46:49], v[114:117]
	v_mfma_f32_16x16x32_bf16 v[106:109], v[118:121], v[78:81], v[106:109]
	v_mfma_f32_16x16x32_bf16 v[110:113], v[126:129], v[42:45], v[110:113]
	v_mfma_f32_16x16x32_bf16 v[106:109], v[126:129], v[74:77], v[106:109]
	v_mfma_f32_16x16x32_bf16 v[130:133], v[160:163], v[38:41], v[110:113]
	v_mfma_f32_16x16x32_bf16 v[106:109], v[160:163], v[70:73], v[106:109]
	s_setprio 0
	s_nop 3
	v_add_u32_e32 v110, v172, v150
	v_add_u32_e32 v114, v172, v151
	v_add_u32_e32 v118, v172, v152
	v_add_u32_e32 v126, v172, v153
	ds_read_b128 v[110:113], v110
	ds_read_b128 v[114:117], v114
	ds_read_b128 v[118:121], v118
	ds_read_b128 v[126:129], v126
	s_setprio 1
	s_waitcnt lgkmcnt(0)
	v_mfma_f32_16x16x32_bf16 v[160:163], v[138:141], v[66:69], 0
	v_mfma_f32_16x16x32_bf16 v[138:141], v[138:141], v[98:101], 0
	v_mfma_f32_16x16x32_bf16 v[160:163], v[156:159], v[62:65], v[160:163]
	v_mfma_f32_16x16x32_bf16 v[138:141], v[156:159], v[94:97], v[138:141]
	v_mfma_f32_16x16x32_bf16 v[156:159], v[164:167], v[58:61], v[160:163]
	v_mfma_f32_16x16x32_bf16 v[138:141], v[164:167], v[90:93], v[138:141]
	v_mfma_f32_16x16x32_bf16 v[156:159], v[168:171], v[54:57], v[156:159]
	v_mfma_f32_16x16x32_bf16 v[138:141], v[168:171], v[86:89], v[138:141]
	s_setprio 0
	v_add_u32_e32 v176, 0x16000, v134
	s_nop 0
	v_add_u32_e32 v160, v176, v149
	v_add_u32_e32 v164, v176, v137
	v_add_u32_e32 v168, v176, v136
	v_add_u32_e32 v172, v176, v135
	ds_read_b128 v[160:163], v160
	ds_read_b128 v[164:167], v164
	ds_read_b128 v[168:171], v168
	ds_read_b128 v[172:175], v172
	s_setprio 1
	v_mfma_f32_16x16x32_bf16 v[156:159], v[110:113], v[50:53], v[156:159]
	v_mfma_f32_16x16x32_bf16 v[110:113], v[110:113], v[82:85], v[138:141]
	v_mfma_f32_16x16x32_bf16 v[138:141], v[114:117], v[46:49], v[156:159]
	v_mfma_f32_16x16x32_bf16 v[110:113], v[114:117], v[78:81], v[110:113]
	v_mfma_f32_16x16x32_bf16 v[114:117], v[118:121], v[42:45], v[138:141]
	v_mfma_f32_16x16x32_bf16 v[110:113], v[118:121], v[74:77], v[110:113]
	v_mfma_f32_16x16x32_bf16 v[138:141], v[126:129], v[38:41], v[114:117]
	v_mfma_f32_16x16x32_bf16 v[110:113], v[126:129], v[70:73], v[110:113]
	s_setprio 0
	s_nop 3
	v_add_u32_e32 v114, v176, v150
	v_add_u32_e32 v118, v176, v151
	v_add_u32_e32 v126, v176, v152
	v_add_u32_e32 v156, v176, v153
	ds_read_b128 v[114:117], v114
	ds_read_b128 v[118:121], v118
	ds_read_b128 v[126:129], v126
	ds_read_b128 v[156:159], v156
	s_setprio 1
	s_waitcnt lgkmcnt(0)
	v_mfma_f32_16x16x32_bf16 v[176:179], v[160:163], v[66:69], 0
	v_mfma_f32_16x16x32_bf16 v[160:163], v[160:163], v[98:101], 0
	v_mfma_f32_16x16x32_bf16 v[176:179], v[164:167], v[62:65], v[176:179]
	v_mfma_f32_16x16x32_bf16 v[160:163], v[164:167], v[94:97], v[160:163]
	v_mfma_f32_16x16x32_bf16 v[164:167], v[168:171], v[58:61], v[176:179]
	v_mfma_f32_16x16x32_bf16 v[160:163], v[168:171], v[90:93], v[160:163]
	v_mfma_f32_16x16x32_bf16 v[164:167], v[172:175], v[54:57], v[164:167]
	v_mfma_f32_16x16x32_bf16 v[160:163], v[172:175], v[86:89], v[160:163]
	s_setprio 0
	v_add_u32_e32 v184, 0x18000, v134
	v_add_u32_e32 v168, v184, v149
	v_add_u32_e32 v172, v184, v137
	v_add_u32_e32 v176, v184, v136
	v_add_u32_e32 v180, v184, v135
	ds_read_b128 v[168:171], v168
	ds_read_b128 v[172:175], v172
	ds_read_b128 v[176:179], v176
	ds_read_b128 v[180:183], v180
	s_setprio 1
	v_mfma_f32_16x16x32_bf16 v[164:167], v[114:117], v[50:53], v[164:167]
	v_mfma_f32_16x16x32_bf16 v[114:117], v[114:117], v[82:85], v[160:163]
	v_mfma_f32_16x16x32_bf16 v[160:163], v[118:121], v[46:49], v[164:167]
	v_mfma_f32_16x16x32_bf16 v[114:117], v[118:121], v[78:81], v[114:117]
	v_mfma_f32_16x16x32_bf16 v[118:121], v[126:129], v[42:45], v[160:163]
	v_mfma_f32_16x16x32_bf16 v[114:117], v[126:129], v[74:77], v[114:117]
	v_mfma_f32_16x16x32_bf16 v[160:163], v[156:159], v[38:41], v[118:121]
	v_mfma_f32_16x16x32_bf16 v[114:117], v[156:159], v[70:73], v[114:117]
	s_setprio 0
	s_nop 3
	v_add_u32_e32 v118, v184, v150
	v_add_u32_e32 v126, v184, v151
	v_add_u32_e32 v156, v184, v152
	v_add_u32_e32 v164, v184, v153
	ds_read_b128 v[118:121], v118
	ds_read_b128 v[126:129], v126
	ds_read_b128 v[156:159], v156
	ds_read_b128 v[164:167], v164
	s_setprio 1
	s_waitcnt lgkmcnt(0)
	v_mfma_f32_16x16x32_bf16 v[184:187], v[168:171], v[66:69], 0
	v_mfma_f32_16x16x32_bf16 v[168:171], v[168:171], v[98:101], 0
	v_mfma_f32_16x16x32_bf16 v[184:187], v[172:175], v[62:65], v[184:187]
	v_mfma_f32_16x16x32_bf16 v[168:171], v[172:175], v[94:97], v[168:171]
	v_mfma_f32_16x16x32_bf16 v[172:175], v[176:179], v[58:61], v[184:187]
	v_mfma_f32_16x16x32_bf16 v[168:171], v[176:179], v[90:93], v[168:171]
	v_mfma_f32_16x16x32_bf16 v[172:175], v[180:183], v[54:57], v[172:175]
	v_mfma_f32_16x16x32_bf16 v[168:171], v[180:183], v[86:89], v[168:171]
	s_setprio 0
	v_add_u32_e32 v192, 0x1a000, v134
	v_add_u32_e32 v176, v192, v149
	v_add_u32_e32 v180, v192, v137
	v_add_u32_e32 v184, v192, v136
	v_add_u32_e32 v188, v192, v135
	ds_read_b128 v[176:179], v176
	ds_read_b128 v[180:183], v180
	ds_read_b128 v[184:187], v184
	ds_read_b128 v[188:191], v188
	s_setprio 1
	v_mfma_f32_16x16x32_bf16 v[172:175], v[118:121], v[50:53], v[172:175]
	v_mfma_f32_16x16x32_bf16 v[118:121], v[118:121], v[82:85], v[168:171]
	v_mfma_f32_16x16x32_bf16 v[168:171], v[126:129], v[46:49], v[172:175]
	v_mfma_f32_16x16x32_bf16 v[118:121], v[126:129], v[78:81], v[118:121]
	v_mfma_f32_16x16x32_bf16 v[126:129], v[156:159], v[42:45], v[168:171]
	v_mfma_f32_16x16x32_bf16 v[118:121], v[156:159], v[74:77], v[118:121]
	v_mfma_f32_16x16x32_bf16 v[156:159], v[164:167], v[38:41], v[126:129]
	v_mfma_f32_16x16x32_bf16 v[118:121], v[164:167], v[70:73], v[118:121]
	s_setprio 0
	s_nop 3
	v_add_u32_e32 v126, v192, v150
	v_add_u32_e32 v164, v192, v151
	v_add_u32_e32 v168, v192, v152
	v_add_u32_e32 v172, v192, v153
	ds_read_b128 v[126:129], v126
	ds_read_b128 v[164:167], v164
	ds_read_b128 v[168:171], v168
	ds_read_b128 v[172:175], v172
	s_setprio 1
	s_waitcnt lgkmcnt(0)
	v_mfma_f32_16x16x32_bf16 v[192:195], v[176:179], v[66:69], 0
	v_mfma_f32_16x16x32_bf16 v[176:179], v[176:179], v[98:101], 0
	v_mfma_f32_16x16x32_bf16 v[192:195], v[180:183], v[62:65], v[192:195]
	v_mfma_f32_16x16x32_bf16 v[176:179], v[180:183], v[94:97], v[176:179]
	v_mfma_f32_16x16x32_bf16 v[180:183], v[184:187], v[58:61], v[192:195]
	v_mfma_f32_16x16x32_bf16 v[176:179], v[184:187], v[90:93], v[176:179]
	v_mfma_f32_16x16x32_bf16 v[180:183], v[188:191], v[54:57], v[180:183]
	v_mfma_f32_16x16x32_bf16 v[176:179], v[188:191], v[86:89], v[176:179]
	s_setprio 0
	v_add_u32_e32 v200, 0x1c000, v134
	v_add_u32_e32 v184, v200, v149
	v_add_u32_e32 v188, v200, v137
	v_add_u32_e32 v192, v200, v136
	v_add_u32_e32 v196, v200, v135
	ds_read_b128 v[184:187], v184
	ds_read_b128 v[188:191], v188
	ds_read_b128 v[192:195], v192
	ds_read_b128 v[196:199], v196
	s_setprio 1
	v_mfma_f32_16x16x32_bf16 v[180:183], v[126:129], v[50:53], v[180:183]
	v_mfma_f32_16x16x32_bf16 v[126:129], v[126:129], v[82:85], v[176:179]
	v_mfma_f32_16x16x32_bf16 v[176:179], v[164:167], v[46:49], v[180:183]
	v_mfma_f32_16x16x32_bf16 v[126:129], v[164:167], v[78:81], v[126:129]
	v_mfma_f32_16x16x32_bf16 v[164:167], v[168:171], v[42:45], v[176:179]
	v_mfma_f32_16x16x32_bf16 v[126:129], v[168:171], v[74:77], v[126:129]
	v_mfma_f32_16x16x32_bf16 v[164:167], v[172:175], v[38:41], v[164:167]
	v_mfma_f32_16x16x32_bf16 v[126:129], v[172:175], v[70:73], v[126:129]
	s_setprio 0
	v_add_u32_e32 v168, v200, v150
	v_add_u32_e32 v172, v200, v151
	v_add_u32_e32 v176, v200, v152
	v_add_u32_e32 v180, v200, v153
	ds_read_b128 v[168:171], v168
	ds_read_b128 v[172:175], v172
	ds_read_b128 v[176:179], v176
	ds_read_b128 v[180:183], v180
	s_setprio 1
	s_waitcnt lgkmcnt(0)
	v_mfma_f32_16x16x32_bf16 v[200:203], v[184:187], v[66:69], 0
	v_mfma_f32_16x16x32_bf16 v[184:187], v[184:187], v[98:101], 0
	v_mfma_f32_16x16x32_bf16 v[200:203], v[188:191], v[62:65], v[200:203]
	v_mfma_f32_16x16x32_bf16 v[184:187], v[188:191], v[94:97], v[184:187]
	v_mfma_f32_16x16x32_bf16 v[188:191], v[192:195], v[58:61], v[200:203]
	v_mfma_f32_16x16x32_bf16 v[184:187], v[192:195], v[90:93], v[184:187]
	v_mfma_f32_16x16x32_bf16 v[188:191], v[196:199], v[54:57], v[188:191]
	v_mfma_f32_16x16x32_bf16 v[184:187], v[196:199], v[86:89], v[184:187]
	s_setprio 0
	v_add_u32_e32 v208, 0x1e000, v134
	v_add_u32_e32 v134, v208, v149
	v_add_u32_e32 v137, v208, v137
	ds_read_b128 v[192:195], v134
	ds_read_b128 v[196:199], v137
	v_add_u32_e32 v134, v208, v136
	v_add_u32_e32 v135, v208, v135
	ds_read_b128 v[200:203], v134
	ds_read_b128 v[204:207], v135
	s_setprio 1
	v_mfma_f32_16x16x32_bf16 v[134:137], v[168:171], v[50:53], v[188:191]
	v_mfma_f32_16x16x32_bf16 v[168:171], v[168:171], v[82:85], v[184:187]
	v_mfma_f32_16x16x32_bf16 v[134:137], v[172:175], v[46:49], v[134:137]
	v_mfma_f32_16x16x32_bf16 v[168:171], v[172:175], v[78:81], v[168:171]
	v_mfma_f32_16x16x32_bf16 v[134:137], v[176:179], v[42:45], v[134:137]
	v_mfma_f32_16x16x32_bf16 v[168:171], v[176:179], v[74:77], v[168:171]
	v_mfma_f32_16x16x32_bf16 v[172:175], v[180:183], v[38:41], v[134:137]
	v_mfma_f32_16x16x32_bf16 v[134:137], v[180:183], v[70:73], v[168:171]
	s_setprio 0
	v_add_u32_e32 v149, v208, v150
	v_add_u32_e32 v150, v208, v151
	s_nop 2
	ds_read_b128 v[168:171], v149
	ds_read_b128 v[176:179], v150
	v_add_u32_e32 v149, v208, v152
	v_add_u32_e32 v180, v208, v153
	ds_read_b128 v[150:153], v149
	ds_read_b128 v[180:183], v180
	s_setprio 1
	s_waitcnt lgkmcnt(0)
	v_mfma_f32_16x16x32_bf16 v[66:69], v[192:195], v[66:69], 0
	v_mfma_f32_16x16x32_bf16 v[98:101], v[192:195], v[98:101], 0
	v_mfma_f32_16x16x32_bf16 v[62:65], v[196:199], v[62:65], v[66:69]
	v_mfma_f32_16x16x32_bf16 v[66:69], v[196:199], v[94:97], v[98:101]
	v_mfma_f32_16x16x32_bf16 v[58:61], v[200:203], v[58:61], v[62:65]
	v_mfma_f32_16x16x32_bf16 v[62:65], v[200:203], v[90:93], v[66:69]
	v_mfma_f32_16x16x32_bf16 v[54:57], v[204:207], v[54:57], v[58:61]
	v_mfma_f32_16x16x32_bf16 v[58:61], v[204:207], v[86:89], v[62:65]
	s_setprio 0
	s_setprio 1
	v_mfma_f32_16x16x32_bf16 v[50:53], v[168:171], v[50:53], v[54:57]
	v_mfma_f32_16x16x32_bf16 v[54:57], v[168:171], v[82:85], v[58:61]
	v_mfma_f32_16x16x32_bf16 v[46:49], v[176:179], v[46:49], v[50:53]
	v_mfma_f32_16x16x32_bf16 v[50:53], v[176:179], v[78:81], v[54:57]
	v_mfma_f32_16x16x32_bf16 v[42:45], v[150:153], v[42:45], v[46:49]
	v_mfma_f32_16x16x32_bf16 v[46:49], v[150:153], v[74:77], v[50:53]
	v_mfma_f32_16x16x32_bf16 v[50:53], v[180:183], v[38:41], v[42:45]
	v_mfma_f32_16x16x32_bf16 v[66:69], v[180:183], v[70:73], v[46:49]
	s_setprio 0
	v_mul_f32_e32 v39, v148, v130
	v_mul_f32_e32 v38, v148, v122
	v_exp_f32_e32 v40, v39
	v_mul_f32_e32 v39, v148, v123
	v_mul_f32_e32 v42, v148, v124
	v_mul_f32_e32 v44, v148, v125
	v_exp_f32_e32 v38, v38
	v_exp_f32_e32 v39, v39
	v_mul_f32_e32 v41, v148, v131
	v_exp_f32_e32 v42, v42
	v_mul_f32_e32 v43, v148, v132
	v_exp_f32_e32 v44, v44
	v_mul_f32_e32 v45, v148, v133
	v_exp_f32_e32 v41, v41
	v_exp_f32_e32 v43, v43
	v_exp_f32_e32 v45, v45
	v_add_f32_e32 v46, v38, v39
	v_add_f32_e32 v47, v42, v44
	v_add_f32_e32 v46, v46, v47
	v_add_f32_e32 v47, v40, v41
	v_add_f32_e32 v48, v43, v45
	v_add_f32_e32 v47, v47, v48
	v_cvt_pk_bf16_f32 v40, v40, v41
	v_cvt_pk_bf16_f32 v41, v43, v45
	v_mul_f32_e32 v43, v148, v160
	v_add_f32_e32 v46, v46, v47
	v_cvt_pk_bf16_f32 v38, v38, v39
	v_cvt_pk_bf16_f32 v39, v42, v44
	v_mul_f32_e32 v42, v148, v138
	v_exp_f32_e32 v44, v43
	v_mul_f32_e32 v43, v148, v139
	v_mul_f32_e32 v47, v148, v140
	v_mul_f32_e32 v49, v148, v141
	v_exp_f32_e32 v42, v42
	v_exp_f32_e32 v43, v43
	v_mul_f32_e32 v45, v148, v161
	v_exp_f32_e32 v47, v47
	v_mul_f32_e32 v48, v148, v162
	v_exp_f32_e32 v49, v49
	v_mul_f32_e32 v54, v148, v163
	v_exp_f32_e32 v45, v45
	v_exp_f32_e32 v48, v48
	v_exp_f32_e32 v54, v54
	v_add_f32_e32 v55, v42, v43
	v_add_f32_e32 v56, v47, v49
	v_add_f32_e32 v55, v55, v56
	v_add_f32_e32 v56, v44, v45
	v_add_f32_e32 v57, v48, v54
	v_add_f32_e32 v56, v56, v57
	v_add_f32_e32 v46, v155, v46
	v_add_f32_e32 v55, v55, v56
	v_add_f32_e32 v46, v46, v55
	v_cvt_pk_bf16_f32 v42, v42, v43
	v_cvt_pk_bf16_f32 v43, v47, v49
	v_mul_f32_e32 v47, v148, v156
	v_mul_f32_e32 v49, v148, v157
	v_mul_f32_e32 v55, v148, v158
	v_mul_f32_e32 v57, v148, v159
	v_cvt_pk_bf16_f32 v44, v44, v45
	v_cvt_pk_bf16_f32 v45, v48, v54
	v_exp_f32_e32 v47, v47
	v_mul_f32_e32 v48, v148, v164
	v_exp_f32_e32 v49, v49
	v_mul_f32_e32 v54, v148, v165
	v_exp_f32_e32 v55, v55
	v_mul_f32_e32 v56, v148, v166
	v_exp_f32_e32 v57, v57
	v_mul_f32_e32 v58, v148, v167
	v_exp_f32_e32 v48, v48
	v_exp_f32_e32 v54, v54
	v_exp_f32_e32 v56, v56
	v_exp_f32_e32 v58, v58
	v_add_f32_e32 v59, v47, v49
	v_add_f32_e32 v60, v55, v57
	v_add_f32_e32 v59, v59, v60
	v_add_f32_e32 v60, v48, v54
	v_add_f32_e32 v61, v56, v58
	v_add_f32_e32 v60, v60, v61
	v_add_f32_e32 v59, v59, v60
	v_mul_f32_e32 v50, v148, v50
	v_mul_f32_e32 v51, v148, v51
	v_mul_f32_e32 v52, v148, v52
	v_add_f32_e32 v59, v46, v59
	v_cvt_pk_bf16_f32 v46, v47, v49
	v_cvt_pk_bf16_f32 v47, v55, v57
	v_cvt_pk_bf16_f32 v48, v48, v54
	v_cvt_pk_bf16_f32 v49, v56, v58
	v_mul_f32_e32 v54, v148, v172
	v_exp_f32_e32 v55, v50
	v_mul_f32_e32 v50, v148, v173
	v_exp_f32_e32 v56, v51
	v_mul_f32_e32 v51, v148, v174
	v_exp_f32_e32 v57, v52
	v_mul_f32_e32 v52, v148, v175
	v_exp_f32_e32 v54, v54
	v_exp_f32_e32 v50, v50
	v_exp_f32_e32 v51, v51
	v_exp_f32_e32 v52, v52
	v_mul_f32_e32 v53, v148, v53
	v_exp_f32_e32 v53, v53
	v_add_f32_e32 v58, v54, v50
	v_add_f32_e32 v60, v51, v52
	v_add_f32_e32 v58, v58, v60
	v_add_f32_e32 v60, v55, v56
	v_add_f32_e32 v61, v57, v53
	v_add_f32_e32 v60, v60, v61
	v_add_f32_e32 v58, v58, v60
	v_cvt_pk_bf16_f32 v51, v51, v52
	v_cvt_pk_bf16_f32 v52, v55, v56
	v_mul_f32_e32 v55, v147, v106
	v_add_f32_e32 v74, v59, v58
	v_cvt_pk_bf16_f32 v50, v54, v50
	v_mul_f32_e32 v54, v147, v102
	v_exp_f32_e32 v56, v55
	v_mul_f32_e32 v55, v147, v103
	v_mul_f32_e32 v58, v147, v104
	v_mul_f32_e32 v60, v147, v105
	v_cvt_pk_bf16_f32 v53, v57, v53
	v_exp_f32_e32 v54, v54
	v_exp_f32_e32 v55, v55
	v_mul_f32_e32 v57, v147, v107
	v_exp_f32_e32 v58, v58
	v_mul_f32_e32 v59, v147, v108
	v_exp_f32_e32 v60, v60
	v_mul_f32_e32 v61, v147, v109
	v_exp_f32_e32 v57, v57
	v_exp_f32_e32 v59, v59
	v_exp_f32_e32 v61, v61
	v_add_f32_e32 v62, v54, v55
	v_add_f32_e32 v63, v58, v60
	v_add_f32_e32 v62, v62, v63
	v_add_f32_e32 v63, v56, v57
	v_add_f32_e32 v64, v59, v61
	v_add_f32_e32 v63, v63, v64
	v_cvt_pk_bf16_f32 v56, v56, v57
	v_cvt_pk_bf16_f32 v57, v59, v61
	v_mul_f32_e32 v59, v147, v114
	v_add_f32_e32 v62, v62, v63
	v_cvt_pk_bf16_f32 v54, v54, v55
	v_cvt_pk_bf16_f32 v55, v58, v60
	v_mul_f32_e32 v58, v147, v110
	v_exp_f32_e32 v60, v59
	v_mul_f32_e32 v59, v147, v111
	v_mul_f32_e32 v63, v147, v112
	v_mul_f32_e32 v65, v147, v113
	v_exp_f32_e32 v58, v58
	v_exp_f32_e32 v59, v59
	v_mul_f32_e32 v61, v147, v115
	v_exp_f32_e32 v63, v63
	v_mul_f32_e32 v64, v147, v116
	v_exp_f32_e32 v65, v65
	v_mul_f32_e32 v70, v147, v117
	v_exp_f32_e32 v61, v61
	v_exp_f32_e32 v64, v64
	v_exp_f32_e32 v70, v70
	v_add_f32_e32 v71, v58, v59
	v_add_f32_e32 v72, v63, v65
	v_add_f32_e32 v71, v71, v72
	v_add_f32_e32 v72, v60, v61
	v_add_f32_e32 v73, v64, v70
	v_add_f32_e32 v72, v72, v73
	v_add_f32_e32 v62, v154, v62
	v_add_f32_e32 v71, v71, v72
	v_add_f32_e32 v62, v62, v71
	v_cvt_pk_bf16_f32 v58, v58, v59
	v_cvt_pk_bf16_f32 v59, v63, v65
	v_mul_f32_e32 v63, v147, v118
	v_mul_f32_e32 v65, v147, v119
	v_mul_f32_e32 v71, v147, v120
	v_mul_f32_e32 v73, v147, v121
	v_cvt_pk_bf16_f32 v60, v60, v61
	v_cvt_pk_bf16_f32 v61, v64, v70
	v_exp_f32_e32 v63, v63
	v_mul_f32_e32 v64, v147, v126
	v_exp_f32_e32 v65, v65
	v_mul_f32_e32 v70, v147, v127
	v_exp_f32_e32 v71, v71
	v_mul_f32_e32 v72, v147, v128
	v_exp_f32_e32 v73, v73
	v_mul_f32_e32 v75, v147, v129
	v_exp_f32_e32 v64, v64
	v_exp_f32_e32 v70, v70
	v_exp_f32_e32 v72, v72
	v_exp_f32_e32 v75, v75
	v_add_f32_e32 v76, v63, v65
	v_add_f32_e32 v77, v71, v73
	v_add_f32_e32 v76, v76, v77
	v_add_f32_e32 v77, v64, v70
	v_add_f32_e32 v78, v72, v75
	v_add_f32_e32 v77, v77, v78
	v_add_f32_e32 v76, v76, v77
	v_mul_f32_e32 v66, v147, v66
	v_mul_f32_e32 v67, v147, v67
	v_mul_f32_e32 v68, v147, v68
	v_add_f32_e32 v76, v62, v76
	v_cvt_pk_bf16_f32 v62, v63, v65
	v_cvt_pk_bf16_f32 v63, v71, v73
	v_cvt_pk_bf16_f32 v64, v64, v70
	v_cvt_pk_bf16_f32 v65, v72, v75
	v_mul_f32_e32 v70, v147, v134
	v_exp_f32_e32 v71, v66
	v_mul_f32_e32 v66, v147, v135
	v_exp_f32_e32 v72, v67
	v_mul_f32_e32 v67, v147, v136
	v_exp_f32_e32 v73, v68
	v_mul_f32_e32 v68, v147, v137
	v_exp_f32_e32 v70, v70
	v_exp_f32_e32 v66, v66
	v_exp_f32_e32 v67, v67
	v_exp_f32_e32 v68, v68
	v_mul_f32_e32 v69, v147, v69
	v_exp_f32_e32 v69, v69
	v_add_f32_e32 v75, v70, v66
	v_add_f32_e32 v77, v67, v68
	v_add_f32_e32 v75, v75, v77
	v_add_f32_e32 v77, v71, v72
	v_add_f32_e32 v78, v73, v69
	v_add_f32_e32 v77, v77, v78
	v_add_f32_e32 v75, v75, v77
	v_add_f32_e32 v75, v76, v75
	s_waitcnt vmcnt(0)
	s_barrier
	s_add_i32 s9, s8, 64
	v_ashrrev_i32_e32 v76, 5, v5
	v_cvt_pk_bf16_f32 v66, v70, v66
	v_lshl_add_u32 v70, s9, 1, v76
	v_cvt_pk_bf16_f32 v67, v67, v68
	v_cvt_pk_bf16_f32 v68, v71, v72
	v_lshrrev_b32_e32 v71, 1, v70
	v_and_b32_e32 v5, 31, v5
	v_and_b32_e32 v71, 12, v71
	v_and_b32_e32 v77, 3, v76
	v_bitop3_b32 v72, v71, v5, v77 bitop3:0x36
	v_ashrrev_i32_e32 v71, 31, v70
	v_lshlrev_b64 v[70:71], 9, v[70:71]
	v_cvt_pk_bf16_f32 v69, v73, v69
	v_lshl_add_u64 v[70:71], s[4:5], 0, v[70:71]
	v_lshlrev_b32_e32 v72, 4, v72
	v_mov_b32_e32 v73, v4
	s_lshl_b32 s9, s9, 10
	v_lshl_add_u64 v[70:71], v[70:71], 0, v[72:73]
	s_add_i32 m0, s9, 0
	s_add_i32 s9, s8, 0x41
	global_load_lds_dwordx4 v[70:71], off
	v_lshl_add_u32 v70, s9, 1, v76
	v_lshrrev_b32_e32 v71, 1, v70
	v_and_b32_e32 v71, 12, v71
	v_and_b32_e32 v72, 3, v70
	v_bitop3_b32 v72, v71, v5, v72 bitop3:0x36
	v_ashrrev_i32_e32 v71, 31, v70
	v_lshlrev_b64 v[70:71], 9, v[70:71]
	v_lshl_add_u64 v[70:71], s[4:5], 0, v[70:71]
	v_lshlrev_b32_e32 v72, 4, v72
	s_lshl_b32 s9, s9, 10
	v_lshl_add_u64 v[70:71], v[70:71], 0, v[72:73]
	s_add_i32 m0, s9, 0
	s_add_i32 s9, s8, 0x42
	global_load_lds_dwordx4 v[70:71], off
	v_lshl_add_u32 v70, s9, 1, v76
	v_lshrrev_b32_e32 v71, 1, v70
	v_and_b32_e32 v71, 12, v71
	v_bitop3_b32 v72, v71, v5, v77 bitop3:0x36
	v_ashrrev_i32_e32 v71, 31, v70
	v_lshlrev_b64 v[70:71], 9, v[70:71]
	v_lshl_add_u64 v[70:71], s[4:5], 0, v[70:71]
	v_lshlrev_b32_e32 v72, 4, v72
	s_lshl_b32 s9, s9, 10
	v_lshl_add_u64 v[70:71], v[70:71], 0, v[72:73]
	s_add_i32 m0, s9, 0
	s_add_i32 s9, s8, 0x43
	global_load_lds_dwordx4 v[70:71], off
	v_lshl_add_u32 v70, s9, 1, v76
	v_lshrrev_b32_e32 v71, 1, v70
	v_and_b32_e32 v71, 12, v71
	v_and_b32_e32 v72, 3, v70
	v_bitop3_b32 v72, v71, v5, v72 bitop3:0x36
	v_ashrrev_i32_e32 v71, 31, v70
	v_lshlrev_b64 v[70:71], 9, v[70:71]
	v_lshl_add_u64 v[70:71], s[4:5], 0, v[70:71]
	v_lshlrev_b32_e32 v72, 4, v72
	s_lshl_b32 s9, s9, 10
	v_lshl_add_u64 v[70:71], v[70:71], 0, v[72:73]
	s_add_i32 m0, s9, 0
	s_add_i32 s9, s8, 0x44
	global_load_lds_dwordx4 v[70:71], off
	v_lshl_add_u32 v70, s9, 1, v76
	v_lshrrev_b32_e32 v71, 1, v70
	v_and_b32_e32 v71, 12, v71
	v_bitop3_b32 v72, v71, v5, v77 bitop3:0x36
	v_ashrrev_i32_e32 v71, 31, v70
	v_lshlrev_b64 v[70:71], 9, v[70:71]
	v_lshl_add_u64 v[70:71], s[4:5], 0, v[70:71]
	v_lshlrev_b32_e32 v72, 4, v72
	s_lshl_b32 s9, s9, 10
	v_lshl_add_u64 v[70:71], v[70:71], 0, v[72:73]
	s_add_i32 m0, s9, 0
	s_add_i32 s9, s8, 0x45
	global_load_lds_dwordx4 v[70:71], off
	v_lshl_add_u32 v70, s9, 1, v76
	v_lshrrev_b32_e32 v71, 1, v70
	v_and_b32_e32 v71, 12, v71
	v_and_b32_e32 v72, 3, v70
	v_bitop3_b32 v72, v71, v5, v72 bitop3:0x36
	v_ashrrev_i32_e32 v71, 31, v70
	v_lshlrev_b64 v[70:71], 9, v[70:71]
	v_lshl_add_u64 v[70:71], s[4:5], 0, v[70:71]
	v_lshlrev_b32_e32 v72, 4, v72
	s_lshl_b32 s9, s9, 10
	v_lshl_add_u64 v[70:71], v[70:71], 0, v[72:73]
	s_add_i32 m0, s9, 0
	s_add_i32 s9, s8, 0x46
	global_load_lds_dwordx4 v[70:71], off
	v_lshl_add_u32 v70, s9, 1, v76
	v_lshrrev_b32_e32 v71, 1, v70
	v_and_b32_e32 v71, 12, v71
	v_bitop3_b32 v72, v71, v5, v77 bitop3:0x36
	v_ashrrev_i32_e32 v71, 31, v70
	v_lshlrev_b64 v[70:71], 9, v[70:71]
	v_lshl_add_u64 v[70:71], s[4:5], 0, v[70:71]
	v_lshlrev_b32_e32 v72, 4, v72
	s_lshl_b32 s9, s9, 10
	v_lshl_add_u64 v[70:71], v[70:71], 0, v[72:73]
	s_add_i32 m0, s9, 0
	s_addk_i32 s8, 0x47
	global_load_lds_dwordx4 v[70:71], off
	v_lshl_add_u32 v70, s8, 1, v76
	v_lshrrev_b32_e32 v71, 1, v70
	v_and_b32_e32 v71, 12, v71
	v_and_b32_e32 v72, 3, v70
	v_bitop3_b32 v5, v71, v5, v72 bitop3:0x36
	v_ashrrev_i32_e32 v71, 31, v70
	v_lshlrev_b64 v[70:71], 9, v[70:71]
	v_lshl_add_u64 v[70:71], s[4:5], 0, v[70:71]
	v_lshlrev_b32_e32 v72, 4, v5
	s_lshl_b32 s4, s8, 10
	v_lshl_add_u64 v[70:71], v[70:71], 0, v[72:73]
	s_add_i32 m0, s4, 0
	v_mov_b32_e32 v5, v74
	global_load_lds_dwordx4 v[70:71], off
	s_nop 0
	v_permlane16_swap_b32_e32 v74, v5
	v_add_f32_e32 v5, v74, v5
	v_mov_b32_e32 v70, v5
	s_nop 1
	v_permlane32_swap_b32_e32 v5, v70
	v_add_f32_e32 v5, v5, v70
	v_div_scale_f32 v70, s[4:5], v5, v5, 1.0
	v_rcp_f32_e32 v71, v70
	v_lshl_add_u64 v[2:3], s[2:3], 0, v[2:3]
	v_bfe_u32 v87, v145, 5, 1
	v_lshl_add_u64 v[2:3], v[2:3], 0, s[6:7]
	v_fma_f32 v72, -v70, v71, 1.0
	v_fmac_f32_e32 v71, v72, v71
	v_div_scale_f32 v72, vcc, 1.0, v5, 1.0
	v_mul_f32_e32 v73, v72, v71
	v_fma_f32 v74, -v70, v73, v72
	v_fmac_f32_e32 v73, v74, v71
	v_fma_f32 v70, -v70, v73, v72
	v_div_fmas_f32 v70, v70, v71, v73
	v_div_fixup_f32 v5, v70, v5, 1.0
	v_mov_b32_e32 v70, v75
	s_nop 1
	v_permlane16_swap_b32_e32 v75, v70
	v_add_f32_e32 v70, v75, v70
	v_mov_b32_e32 v71, v70
	s_nop 1
	v_permlane32_swap_b32_e32 v70, v71
	v_add_f32_e32 v70, v70, v71
	v_div_scale_f32 v71, s[4:5], v70, v70, 1.0
	v_rcp_f32_e32 v72, v71
	v_bitop3_b32 v76, v87, v144, 8 bitop3:0x36
	v_bitop3_b32 v77, v87, v144, 10 bitop3:0x36
	v_bitop3_b32 v78, v87, v144, 12 bitop3:0x36
	v_fma_f32 v73, -v71, v72, 1.0
	v_fmac_f32_e32 v72, v73, v72
	v_div_scale_f32 v73, vcc, 1.0, v70, 1.0
	v_mul_f32_e32 v74, v73, v72
	v_fma_f32 v75, -v71, v74, v73
	v_fmac_f32_e32 v74, v75, v72
	v_fma_f32 v71, -v71, v74, v73
	v_div_fmas_f32 v71, v71, v72, v74
	v_lshlrev_b32_e32 v72, 1, v145
	v_and_b32_e32 v73, 3, v145
	v_and_or_b32 v72, v72, 24, v73
	v_and_b32_e32 v73, 8, v146
	v_lshlrev_b32_e32 v72, 9, v72
	v_add3_u32 v146, 0, v73, v72
	v_bitop3_b32 v72, v87, v145, 15 bitop3:0x78
	v_bitop3_b32 v73, v87, v144, 2 bitop3:0x36
	v_bitop3_b32 v74, v87, v144, 4 bitop3:0x36
	v_bitop3_b32 v75, v87, v144, 6 bitop3:0x36
	v_bitop3_b32 v79, v87, v144, 14 bitop3:0x36
	v_bitop3_b32 v80, v87, v144, 16 bitop3:0x36
	v_bitop3_b32 v81, v87, v144, 18 bitop3:0x36
	v_bitop3_b32 v82, v87, v144, 20 bitop3:0x36
	v_bitop3_b32 v83, v87, v144, 22 bitop3:0x36
	v_bitop3_b32 v84, v87, v144, 24 bitop3:0x36
	v_bitop3_b32 v85, v87, v144, 26 bitop3:0x36
	v_bitop3_b32 v86, v87, v144, 28 bitop3:0x36
	v_bitop3_b32 v87, v87, v144, 30 bitop3:0x36
	v_div_fixup_f32 v136, v71, v70, 1.0
	v_lshl_add_u64 v[70:71], v[2:3], 0, v[142:143]
	v_lshlrev_b32_e32 v149, 4, v72
	v_lshlrev_b32_e32 v151, 4, v73
	v_lshlrev_b32_e32 v153, 4, v74
	v_lshlrev_b32_e32 v154, 4, v75
	v_lshlrev_b32_e32 v143, 4, v76
	v_lshlrev_b32_e32 v147, 4, v77
	v_lshlrev_b32_e32 v150, 4, v78
	v_lshlrev_b32_e32 v152, 4, v79
	v_lshlrev_b32_e32 v139, 4, v80
	v_lshlrev_b32_e32 v141, 4, v81
	v_lshlrev_b32_e32 v145, 4, v82
	v_lshlrev_b32_e32 v148, 4, v83
	v_lshlrev_b32_e32 v137, 4, v84
	v_lshlrev_b32_e32 v138, 4, v85
	v_lshlrev_b32_e32 v140, 4, v86
	v_lshlrev_b32_e32 v142, 4, v87
	v_add_u32_e32 v72, v146, v149
	v_add_u32_e32 v73, v146, v151
	v_add_u32_e32 v74, v146, v153
	v_add_u32_e32 v75, v146, v154
	v_add_u32_e32 v76, v146, v143
	v_add_u32_e32 v77, v146, v147
	v_add_u32_e32 v78, v146, v150
	v_add_u32_e32 v79, v146, v152
	v_add_u32_e32 v80, v146, v139
	v_add_u32_e32 v81, v146, v141
	v_add_u32_e32 v82, v146, v145
	v_add_u32_e32 v83, v146, v148
	v_add_u32_e32 v84, v146, v137
	v_add_u32_e32 v85, v146, v138
	v_add_u32_e32 v86, v146, v140
	v_add_u32_e32 v87, v146, v142
	s_waitcnt vmcnt(8)
	s_waitcnt vmcnt(0) lgkmcnt(0)
	s_barrier
	ds_read2st64_b64 v[88:91], v72 offset1:4
	ds_read2st64_b64 v[92:95], v73 offset1:4
	ds_read2st64_b64 v[96:99], v74 offset1:4
	ds_read2st64_b64 v[100:103], v75 offset1:4
	ds_read2st64_b64 v[104:107], v76 offset1:4
	ds_read2st64_b64 v[108:111], v77 offset1:4
	ds_read2st64_b64 v[112:115], v78 offset1:4
	ds_read2st64_b64 v[116:119], v79 offset1:4
	ds_read2st64_b64 v[120:123], v80 offset1:4
	ds_read2st64_b64 v[124:127], v81 offset1:4
	ds_read2st64_b64 v[128:131], v82 offset1:4
	ds_read2st64_b64 v[132:135], v83 offset1:4
	ds_read2st64_b64 v[156:159], v84 offset1:4
	ds_read2st64_b64 v[160:163], v85 offset1:4
	ds_read2st64_b64 v[164:167], v86 offset1:4
	ds_read2st64_b64 v[168:171], v87 offset1:4
	s_mov_b64 s[2:3], 0xae00000
	v_lshl_add_u64 v[2:3], v[70:71], 0, s[2:3]
	s_setprio 1
	s_waitcnt lgkmcnt(14)
	v_mov_b32_e32 v172, v88
	v_mov_b32_e32 v173, v89
	v_mov_b32_e32 v174, v92
	v_mov_b32_e32 v175, v93
	s_waitcnt lgkmcnt(13)
	v_mov_b32_e32 v180, v96
	v_mov_b32_e32 v181, v97
	s_waitcnt lgkmcnt(12)
	v_mov_b32_e32 v182, v100
	v_mov_b32_e32 v183, v101
	v_mfma_f32_16x16x32_bf16 v[176:179], v[172:175], v[6:9], 0
	v_mfma_f32_16x16x32_bf16 v[172:175], v[172:175], v[22:25], 0
	v_mfma_f32_16x16x32_bf16 v[176:179], v[180:183], v[10:13], v[176:179]
	v_mfma_f32_16x16x32_bf16 v[172:175], v[180:183], v[26:29], v[172:175]
	s_waitcnt lgkmcnt(11)
	v_mov_b32_e32 v180, v104
	v_mov_b32_e32 v181, v105
	s_waitcnt lgkmcnt(10)
	v_mov_b32_e32 v182, v108
	v_mov_b32_e32 v183, v109
	s_nop 1
	v_mfma_f32_16x16x32_bf16 v[176:179], v[180:183], v[14:17], v[176:179]
	v_mfma_f32_16x16x32_bf16 v[172:175], v[180:183], v[30:33], v[172:175]
	s_waitcnt lgkmcnt(9)
	v_mov_b32_e32 v180, v112
	v_mov_b32_e32 v181, v113
	s_waitcnt lgkmcnt(8)
	v_mov_b32_e32 v182, v116
	v_mov_b32_e32 v183, v117
	s_nop 1
	v_mfma_f32_16x16x32_bf16 v[176:179], v[180:183], v[18:21], v[176:179]
	v_mfma_f32_16x16x32_bf16 v[172:175], v[180:183], v[34:37], v[172:175]
	s_waitcnt lgkmcnt(7)
	v_mov_b32_e32 v180, v120
	v_mov_b32_e32 v181, v121
	s_waitcnt lgkmcnt(6)
	v_mov_b32_e32 v182, v124
	v_mov_b32_e32 v183, v125
	s_nop 1
	v_mfma_f32_16x16x32_bf16 v[176:179], v[180:183], v[38:41], v[176:179]
	v_mfma_f32_16x16x32_bf16 v[172:175], v[180:183], v[54:57], v[172:175]
	s_waitcnt lgkmcnt(5)
	v_mov_b32_e32 v180, v128
	v_mov_b32_e32 v181, v129
	s_waitcnt lgkmcnt(4)
	v_mov_b32_e32 v182, v132
	v_mov_b32_e32 v183, v133
	s_nop 1
	v_mfma_f32_16x16x32_bf16 v[176:179], v[180:183], v[42:45], v[176:179]
	v_mfma_f32_16x16x32_bf16 v[172:175], v[180:183], v[58:61], v[172:175]
	s_waitcnt lgkmcnt(3)
	v_mov_b32_e32 v180, v156
	v_mov_b32_e32 v181, v157
	s_waitcnt lgkmcnt(2)
	v_mov_b32_e32 v182, v160
	v_mov_b32_e32 v183, v161
	s_nop 1
	v_mfma_f32_16x16x32_bf16 v[176:179], v[180:183], v[46:49], v[176:179]
	v_mfma_f32_16x16x32_bf16 v[172:175], v[180:183], v[62:65], v[172:175]
	s_waitcnt lgkmcnt(1)
	v_mov_b32_e32 v180, v164
	v_mov_b32_e32 v181, v165
	s_waitcnt lgkmcnt(0)
	v_mov_b32_e32 v182, v168
	v_mov_b32_e32 v183, v169
	s_nop 1
	v_mfma_f32_16x16x32_bf16 v[176:179], v[180:183], v[50:53], v[176:179]
	v_mfma_f32_16x16x32_bf16 v[172:175], v[180:183], v[66:69], v[172:175]
	s_setprio 0
	s_nop 5
	v_mul_f32_e32 v88, v5, v176
	v_mul_f32_e32 v89, v5, v177
	v_cvt_pk_bf16_f32 v88, v88, v89
	v_mul_f32_e32 v89, v5, v178
	v_mul_f32_e32 v92, v5, v179
	v_cvt_pk_bf16_f32 v89, v89, v92
	v_mul_f32_e32 v92, v136, v172
	v_mul_f32_e32 v93, v136, v173
	v_cvt_pk_bf16_f32 v96, v92, v93
	v_mul_f32_e32 v92, v136, v174
	v_mul_f32_e32 v93, v136, v175
	ds_read_b64 v[172:173], v72 offset:16384
	ds_read_b64 v[174:175], v73 offset:16384
	ds_read_b64 v[176:177], v74 offset:16384
	ds_read_b64 v[178:179], v75 offset:16384
	ds_read_b64 v[180:181], v76 offset:16384
	ds_read_b64 v[182:183], v77 offset:16384
	ds_read_b64 v[184:185], v78 offset:16384
	ds_read_b64 v[186:187], v79 offset:16384
	ds_read_b64 v[188:189], v80 offset:16384
	ds_read_b64 v[190:191], v81 offset:16384
	ds_read_b64 v[192:193], v82 offset:16384
	ds_read_b64 v[194:195], v83 offset:16384
	ds_read_b64 v[196:197], v84 offset:16384
	ds_read_b64 v[198:199], v85 offset:16384
	ds_read_b64 v[200:201], v86 offset:16384
	ds_read_b64 v[202:203], v87 offset:16384
	v_cvt_pk_bf16_f32 v97, v92, v93
	s_setprio 1
	v_mov_b32_e32 v92, v90
	v_mov_b32_e32 v93, v91
	v_mov_b32_e32 v100, v98
	v_mov_b32_e32 v101, v99
	v_mov_b32_e32 v108, v106
	v_mfma_f32_16x16x32_bf16 v[204:207], v[92:95], v[6:9], 0
	v_mov_b32_e32 v109, v107
	v_mov_b32_e32 v116, v114
	v_mov_b32_e32 v117, v115
	v_mfma_f32_16x16x32_bf16 v[90:93], v[92:95], v[22:25], 0
	v_mov_b32_e32 v124, v122
	v_mov_b32_e32 v125, v123
	v_mov_b32_e32 v132, v130
	v_mfma_f32_16x16x32_bf16 v[204:207], v[100:103], v[10:13], v[204:207]
	v_mov_b32_e32 v133, v131
	v_mov_b32_e32 v160, v158
	v_mov_b32_e32 v161, v159
	v_mfma_f32_16x16x32_bf16 v[90:93], v[100:103], v[26:29], v[90:93]
	v_mov_b32_e32 v168, v166
	v_mov_b32_e32 v169, v167
	v_mfma_f32_16x16x32_bf16 v[98:101], v[108:111], v[14:17], v[204:207]
	v_mfma_f32_16x16x32_bf16 v[90:93], v[108:111], v[30:33], v[90:93]
	v_mfma_f32_16x16x32_bf16 v[98:101], v[116:119], v[18:21], v[98:101]
	v_mfma_f32_16x16x32_bf16 v[90:93], v[116:119], v[34:37], v[90:93]
	v_mfma_f32_16x16x32_bf16 v[98:101], v[124:127], v[38:41], v[98:101]
	v_mfma_f32_16x16x32_bf16 v[90:93], v[124:127], v[54:57], v[90:93]
	v_mfma_f32_16x16x32_bf16 v[98:101], v[132:135], v[42:45], v[98:101]
	v_mfma_f32_16x16x32_bf16 v[90:93], v[132:135], v[58:61], v[90:93]
	v_mfma_f32_16x16x32_bf16 v[98:101], v[160:163], v[46:49], v[98:101]
	v_mfma_f32_16x16x32_bf16 v[90:93], v[160:163], v[62:65], v[90:93]
	v_mfma_f32_16x16x32_bf16 v[98:101], v[168:171], v[50:53], v[98:101]
	v_mfma_f32_16x16x32_bf16 v[92:95], v[168:171], v[66:69], v[90:93]
	s_setprio 0
	s_nop 5
	v_mul_f32_e32 v90, v5, v98
	v_mul_f32_e32 v91, v5, v99
	v_cvt_pk_bf16_f32 v90, v90, v91
	v_mul_f32_e32 v91, v5, v100
	v_mul_f32_e32 v98, v5, v101
	v_mul_f32_e32 v92, v136, v92
	v_cvt_pk_bf16_f32 v91, v91, v98
	v_mul_f32_e32 v93, v136, v93
	v_cvt_pk_bf16_f32 v98, v92, v93
	v_mul_f32_e32 v92, v136, v94
	s_mov_b32 s2, 0xae00000
	v_mul_f32_e32 v93, v136, v95
	v_cvt_pk_bf16_f32 v99, v92, v93
	v_add_co_u32_e32 v92, vcc, s2, v70
	s_mov_b32 s2, 0xae08000
	s_nop 0
	v_addc_co_u32_e32 v93, vcc, 0, v71, vcc
	v_add_co_u32_e32 v134, vcc, s2, v70
	global_store_dwordx4 v[92:93], v[88:91], off sc1
	s_nop 0
	v_addc_co_u32_e32 v135, vcc, 0, v71, vcc
	global_store_dwordx4 v[134:135], v[96:99], off sc1
	ds_read_b64 v[88:89], v72 offset:18432
	ds_read_b64 v[90:91], v73 offset:18432
	ds_read_b64 v[92:93], v74 offset:18432
	ds_read_b64 v[94:95], v75 offset:18432
	ds_read_b64 v[96:97], v76 offset:18432
	ds_read_b64 v[98:99], v77 offset:18432
	ds_read_b64 v[100:101], v78 offset:18432
	ds_read_b64 v[102:103], v79 offset:18432
	ds_read_b64 v[104:105], v80 offset:18432
	ds_read_b64 v[106:107], v81 offset:18432
	ds_read_b64 v[108:109], v82 offset:18432
	ds_read_b64 v[110:111], v83 offset:18432
	ds_read_b64 v[112:113], v84 offset:18432
	ds_read_b64 v[114:115], v85 offset:18432
	ds_read_b64 v[116:117], v86 offset:18432
	ds_read_b64 v[118:119], v87 offset:18432
	s_setprio 1
	s_waitcnt lgkmcnt(14)
	v_mfma_f32_16x16x32_bf16 v[120:123], v[172:175], v[6:9], 0
	v_mfma_f32_16x16x32_bf16 v[124:127], v[172:175], v[22:25], 0
	v_mfma_f32_16x16x32_bf16 v[120:123], v[176:179], v[10:13], v[120:123]
	v_mfma_f32_16x16x32_bf16 v[124:127], v[176:179], v[26:29], v[124:127]
	v_mfma_f32_16x16x32_bf16 v[120:123], v[180:183], v[14:17], v[120:123]
	v_mfma_f32_16x16x32_bf16 v[124:127], v[180:183], v[30:33], v[124:127]
	v_mfma_f32_16x16x32_bf16 v[120:123], v[184:187], v[18:21], v[120:123]
	v_mfma_f32_16x16x32_bf16 v[124:127], v[184:187], v[34:37], v[124:127]
	v_mfma_f32_16x16x32_bf16 v[120:123], v[188:191], v[38:41], v[120:123]
	v_mfma_f32_16x16x32_bf16 v[124:127], v[188:191], v[54:57], v[124:127]
	v_mfma_f32_16x16x32_bf16 v[120:123], v[192:195], v[42:45], v[120:123]
	v_mfma_f32_16x16x32_bf16 v[124:127], v[192:195], v[58:61], v[124:127]
	v_mfma_f32_16x16x32_bf16 v[120:123], v[196:199], v[46:49], v[120:123]
	v_mfma_f32_16x16x32_bf16 v[124:127], v[196:199], v[62:65], v[124:127]
	v_mfma_f32_16x16x32_bf16 v[120:123], v[200:203], v[50:53], v[120:123]
	v_mfma_f32_16x16x32_bf16 v[124:127], v[200:203], v[66:69], v[124:127]
	s_setprio 0
	ds_read_b64 v[128:129], v72 offset:32768
	ds_read_b64 v[130:131], v73 offset:32768
	ds_read_b64 v[156:157], v74 offset:32768
	ds_read_b64 v[158:159], v75 offset:32768
	ds_read_b64 v[160:161], v76 offset:32768
	ds_read_b64 v[162:163], v77 offset:32768
	ds_read_b64 v[164:165], v78 offset:32768
	ds_read_b64 v[166:167], v79 offset:32768
	ds_read_b64 v[168:169], v80 offset:32768
	ds_read_b64 v[170:171], v81 offset:32768
	ds_read_b64 v[172:173], v82 offset:32768
	ds_read_b64 v[174:175], v83 offset:32768
	ds_read_b64 v[176:177], v84 offset:32768
	ds_read_b64 v[178:179], v85 offset:32768
	ds_read_b64 v[180:181], v86 offset:32768
	ds_read_b64 v[182:183], v87 offset:32768
	v_mul_f32_e32 v70, v5, v120
	v_mul_f32_e32 v71, v5, v121
	v_cvt_pk_bf16_f32 v120, v70, v71
	v_mul_f32_e32 v70, v5, v122
	v_mul_f32_e32 v71, v5, v123
	v_cvt_pk_bf16_f32 v121, v70, v71
	v_mul_f32_e32 v70, v136, v124
	v_mul_f32_e32 v71, v136, v125
	v_cvt_pk_bf16_f32 v124, v70, v71
	v_mul_f32_e32 v70, v136, v126
	v_mul_f32_e32 v71, v136, v127
	v_cvt_pk_bf16_f32 v125, v70, v71
	s_setprio 1
	v_mfma_f32_16x16x32_bf16 v[184:187], v[88:91], v[6:9], 0
	v_mfma_f32_16x16x32_bf16 v[88:91], v[88:91], v[22:25], 0
	s_waitcnt lgkmcnt(14)
	v_mfma_f32_16x16x32_bf16 v[184:187], v[92:95], v[10:13], v[184:187]
	v_mfma_f32_16x16x32_bf16 v[88:91], v[92:95], v[26:29], v[88:91]
	v_mfma_f32_16x16x32_bf16 v[92:95], v[96:99], v[14:17], v[184:187]
	v_mfma_f32_16x16x32_bf16 v[88:91], v[96:99], v[30:33], v[88:91]
	v_mfma_f32_16x16x32_bf16 v[92:95], v[100:103], v[18:21], v[92:95]
	v_mfma_f32_16x16x32_bf16 v[88:91], v[100:103], v[34:37], v[88:91]
	v_mfma_f32_16x16x32_bf16 v[92:95], v[104:107], v[38:41], v[92:95]
	v_mfma_f32_16x16x32_bf16 v[88:91], v[104:107], v[54:57], v[88:91]
	v_mfma_f32_16x16x32_bf16 v[92:95], v[108:111], v[42:45], v[92:95]
	v_mfma_f32_16x16x32_bf16 v[88:91], v[108:111], v[58:61], v[88:91]
	v_mfma_f32_16x16x32_bf16 v[92:95], v[112:115], v[46:49], v[92:95]
	v_mfma_f32_16x16x32_bf16 v[88:91], v[112:115], v[62:65], v[88:91]
	v_mfma_f32_16x16x32_bf16 v[92:95], v[116:119], v[50:53], v[92:95]
	v_mfma_f32_16x16x32_bf16 v[88:91], v[116:119], v[66:69], v[88:91]
	s_setprio 0
	s_nop 5
	v_mul_f32_e32 v70, v5, v92
	v_mul_f32_e32 v71, v5, v93
	v_cvt_pk_bf16_f32 v122, v70, v71
	v_mul_f32_e32 v70, v5, v94
	v_mul_f32_e32 v71, v5, v95
	v_cvt_pk_bf16_f32 v123, v70, v71
	v_mul_f32_e32 v70, v136, v88
	v_mul_f32_e32 v71, v136, v89
	v_cvt_pk_bf16_f32 v126, v70, v71
	v_mul_f32_e32 v70, v136, v90
	v_mul_f32_e32 v71, v136, v91
	v_cvt_pk_bf16_f32 v127, v70, v71
	global_store_dwordx4 v[2:3], v[120:123], off offset:64 sc1
	global_store_dwordx4 v[134:135], v[124:127], off offset:64 sc1
	ds_read_b64 v[88:89], v72 offset:34816
	ds_read_b64 v[90:91], v73 offset:34816
	ds_read_b64 v[92:93], v74 offset:34816
	ds_read_b64 v[94:95], v75 offset:34816
	ds_read_b64 v[96:97], v76 offset:34816
	ds_read_b64 v[98:99], v77 offset:34816
	ds_read_b64 v[100:101], v78 offset:34816
	ds_read_b64 v[102:103], v79 offset:34816
	ds_read_b64 v[104:105], v80 offset:34816
	ds_read_b64 v[106:107], v81 offset:34816
	ds_read_b64 v[108:109], v82 offset:34816
	ds_read_b64 v[110:111], v83 offset:34816
	ds_read_b64 v[112:113], v84 offset:34816
	ds_read_b64 v[114:115], v85 offset:34816
	ds_read_b64 v[116:117], v86 offset:34816
	ds_read_b64 v[118:119], v87 offset:34816
	s_setprio 1
	v_mfma_f32_16x16x32_bf16 v[120:123], v[128:131], v[6:9], 0
	v_mfma_f32_16x16x32_bf16 v[124:127], v[128:131], v[22:25], 0
	s_waitcnt lgkmcnt(14)
	v_mfma_f32_16x16x32_bf16 v[120:123], v[156:159], v[10:13], v[120:123]
	v_mfma_f32_16x16x32_bf16 v[124:127], v[156:159], v[26:29], v[124:127]
	v_mfma_f32_16x16x32_bf16 v[120:123], v[160:163], v[14:17], v[120:123]
	v_mfma_f32_16x16x32_bf16 v[124:127], v[160:163], v[30:33], v[124:127]
	v_mfma_f32_16x16x32_bf16 v[120:123], v[164:167], v[18:21], v[120:123]
	v_mfma_f32_16x16x32_bf16 v[124:127], v[164:167], v[34:37], v[124:127]
	v_mfma_f32_16x16x32_bf16 v[120:123], v[168:171], v[38:41], v[120:123]
	v_mfma_f32_16x16x32_bf16 v[124:127], v[168:171], v[54:57], v[124:127]
	v_mfma_f32_16x16x32_bf16 v[120:123], v[172:175], v[42:45], v[120:123]
	v_mfma_f32_16x16x32_bf16 v[124:127], v[172:175], v[58:61], v[124:127]
	v_mfma_f32_16x16x32_bf16 v[120:123], v[176:179], v[46:49], v[120:123]
	v_mfma_f32_16x16x32_bf16 v[124:127], v[176:179], v[62:65], v[124:127]
	v_mfma_f32_16x16x32_bf16 v[120:123], v[180:183], v[50:53], v[120:123]
	v_mfma_f32_16x16x32_bf16 v[124:127], v[180:183], v[66:69], v[124:127]
	s_setprio 0
	ds_read_b64 v[128:129], v72 offset:49152
	ds_read_b64 v[130:131], v73 offset:49152
	ds_read_b64 v[156:157], v74 offset:49152
	ds_read_b64 v[158:159], v75 offset:49152
	ds_read_b64 v[160:161], v76 offset:49152
	ds_read_b64 v[162:163], v77 offset:49152
	ds_read_b64 v[164:165], v78 offset:49152
	ds_read_b64 v[166:167], v79 offset:49152
	ds_read_b64 v[168:169], v80 offset:49152
	ds_read_b64 v[170:171], v81 offset:49152
	ds_read_b64 v[172:173], v82 offset:49152
	ds_read_b64 v[174:175], v83 offset:49152
	ds_read_b64 v[176:177], v84 offset:49152
	ds_read_b64 v[178:179], v85 offset:49152
	ds_read_b64 v[180:181], v86 offset:49152
	ds_read_b64 v[182:183], v87 offset:49152
	v_mul_f32_e32 v70, v5, v120
	v_mul_f32_e32 v71, v5, v121
	v_cvt_pk_bf16_f32 v120, v70, v71
	v_mul_f32_e32 v70, v5, v122
	v_mul_f32_e32 v71, v5, v123
	v_cvt_pk_bf16_f32 v121, v70, v71
	v_mul_f32_e32 v70, v136, v124
	v_mul_f32_e32 v71, v136, v125
	v_cvt_pk_bf16_f32 v124, v70, v71
	v_mul_f32_e32 v70, v136, v126
	v_mul_f32_e32 v71, v136, v127
	v_cvt_pk_bf16_f32 v125, v70, v71
	s_setprio 1
	v_mfma_f32_16x16x32_bf16 v[184:187], v[88:91], v[6:9], 0
	v_mfma_f32_16x16x32_bf16 v[88:91], v[88:91], v[22:25], 0
	s_waitcnt lgkmcnt(14)
	v_mfma_f32_16x16x32_bf16 v[184:187], v[92:95], v[10:13], v[184:187]
	v_mfma_f32_16x16x32_bf16 v[88:91], v[92:95], v[26:29], v[88:91]
	v_mfma_f32_16x16x32_bf16 v[92:95], v[96:99], v[14:17], v[184:187]
	v_mfma_f32_16x16x32_bf16 v[88:91], v[96:99], v[30:33], v[88:91]
	v_mfma_f32_16x16x32_bf16 v[92:95], v[100:103], v[18:21], v[92:95]
	v_mfma_f32_16x16x32_bf16 v[88:91], v[100:103], v[34:37], v[88:91]
	v_mfma_f32_16x16x32_bf16 v[92:95], v[104:107], v[38:41], v[92:95]
	v_mfma_f32_16x16x32_bf16 v[88:91], v[104:107], v[54:57], v[88:91]
	v_mfma_f32_16x16x32_bf16 v[92:95], v[108:111], v[42:45], v[92:95]
	v_mfma_f32_16x16x32_bf16 v[88:91], v[108:111], v[58:61], v[88:91]
	v_mfma_f32_16x16x32_bf16 v[92:95], v[112:115], v[46:49], v[92:95]
	v_mfma_f32_16x16x32_bf16 v[88:91], v[112:115], v[62:65], v[88:91]
	v_mfma_f32_16x16x32_bf16 v[92:95], v[116:119], v[50:53], v[92:95]
	v_mfma_f32_16x16x32_bf16 v[88:91], v[116:119], v[66:69], v[88:91]
	s_setprio 0
	s_nop 5
	v_mul_f32_e32 v70, v5, v92
	v_mul_f32_e32 v71, v5, v93
	v_cvt_pk_bf16_f32 v122, v70, v71
	v_mul_f32_e32 v70, v5, v94
	v_mul_f32_e32 v71, v5, v95
	v_cvt_pk_bf16_f32 v123, v70, v71
	v_mul_f32_e32 v70, v136, v88
	v_mul_f32_e32 v71, v136, v89
	v_cvt_pk_bf16_f32 v126, v70, v71
	v_mul_f32_e32 v70, v136, v90
	v_mul_f32_e32 v71, v136, v91
	v_cvt_pk_bf16_f32 v127, v70, v71
	global_store_dwordx4 v[2:3], v[120:123], off offset:128 sc1
	global_store_dwordx4 v[134:135], v[124:127], off offset:128 sc1
	ds_read_b64 v[70:71], v72 offset:51200
	ds_read_b64 v[72:73], v73 offset:51200
	ds_read_b64 v[88:89], v74 offset:51200
	ds_read_b64 v[90:91], v75 offset:51200
	ds_read_b64 v[74:75], v76 offset:51200
	ds_read_b64 v[76:77], v77 offset:51200
	ds_read_b64 v[92:93], v78 offset:51200
	ds_read_b64 v[94:95], v79 offset:51200
	ds_read_b64 v[78:79], v80 offset:51200
	ds_read_b64 v[80:81], v81 offset:51200
	ds_read_b64 v[96:97], v82 offset:51200
	ds_read_b64 v[98:99], v83 offset:51200
	ds_read_b64 v[82:83], v84 offset:51200
	ds_read_b64 v[84:85], v85 offset:51200
	ds_read_b64 v[100:101], v86 offset:51200
	ds_read_b64 v[102:103], v87 offset:51200
	s_setprio 1
	v_mfma_f32_16x16x32_bf16 v[104:107], v[128:131], v[6:9], 0
	v_mfma_f32_16x16x32_bf16 v[108:111], v[128:131], v[22:25], 0
	s_waitcnt lgkmcnt(14)
	v_mfma_f32_16x16x32_bf16 v[104:107], v[156:159], v[10:13], v[104:107]
	v_mfma_f32_16x16x32_bf16 v[108:111], v[156:159], v[26:29], v[108:111]
	v_mfma_f32_16x16x32_bf16 v[104:107], v[160:163], v[14:17], v[104:107]
	v_mfma_f32_16x16x32_bf16 v[108:111], v[160:163], v[30:33], v[108:111]
	v_mfma_f32_16x16x32_bf16 v[104:107], v[164:167], v[18:21], v[104:107]
	v_mfma_f32_16x16x32_bf16 v[108:111], v[164:167], v[34:37], v[108:111]
	v_mfma_f32_16x16x32_bf16 v[104:107], v[168:171], v[38:41], v[104:107]
	v_mfma_f32_16x16x32_bf16 v[108:111], v[168:171], v[54:57], v[108:111]
	v_mfma_f32_16x16x32_bf16 v[104:107], v[172:175], v[42:45], v[104:107]
	v_mfma_f32_16x16x32_bf16 v[108:111], v[172:175], v[58:61], v[108:111]
	v_mfma_f32_16x16x32_bf16 v[104:107], v[176:179], v[46:49], v[104:107]
	v_mfma_f32_16x16x32_bf16 v[108:111], v[176:179], v[62:65], v[108:111]
	v_mfma_f32_16x16x32_bf16 v[104:107], v[180:183], v[50:53], v[104:107]
	v_mfma_f32_16x16x32_bf16 v[108:111], v[180:183], v[66:69], v[108:111]
	s_setprio 0
	s_nop 5
	v_mul_f32_e32 v86, v5, v104
	v_mul_f32_e32 v87, v5, v105
	v_cvt_pk_bf16_f32 v86, v86, v87
	v_mul_f32_e32 v87, v5, v106
	v_mul_f32_e32 v104, v5, v107
	v_cvt_pk_bf16_f32 v87, v87, v104
	v_mul_f32_e32 v104, v136, v108
	v_mul_f32_e32 v105, v136, v109
	v_cvt_pk_bf16_f32 v104, v104, v105
	v_mul_f32_e32 v105, v136, v110
	v_mul_f32_e32 v106, v136, v111
	v_cvt_pk_bf16_f32 v105, v105, v106
	s_setprio 1
	v_mfma_f32_16x16x32_bf16 v[106:109], v[70:73], v[6:9], 0
	v_mfma_f32_16x16x32_bf16 v[70:73], v[70:73], v[22:25], 0
	s_waitcnt lgkmcnt(12)
	v_mfma_f32_16x16x32_bf16 v[106:109], v[88:91], v[10:13], v[106:109]
	v_mfma_f32_16x16x32_bf16 v[70:73], v[88:91], v[26:29], v[70:73]
	s_waitcnt lgkmcnt(10)
	v_mfma_f32_16x16x32_bf16 v[88:91], v[74:77], v[14:17], v[106:109]
	v_mfma_f32_16x16x32_bf16 v[70:73], v[74:77], v[30:33], v[70:73]
	s_waitcnt lgkmcnt(8)
	v_mfma_f32_16x16x32_bf16 v[74:77], v[92:95], v[18:21], v[88:91]
	v_mfma_f32_16x16x32_bf16 v[70:73], v[92:95], v[34:37], v[70:73]
	s_waitcnt lgkmcnt(6)
	v_mfma_f32_16x16x32_bf16 v[74:77], v[78:81], v[38:41], v[74:77]
	v_mfma_f32_16x16x32_bf16 v[70:73], v[78:81], v[54:57], v[70:73]
	s_waitcnt lgkmcnt(4)
	v_mfma_f32_16x16x32_bf16 v[74:77], v[96:99], v[42:45], v[74:77]
	v_mfma_f32_16x16x32_bf16 v[70:73], v[96:99], v[58:61], v[70:73]
	s_waitcnt lgkmcnt(2)
	v_mfma_f32_16x16x32_bf16 v[74:77], v[82:85], v[46:49], v[74:77]
	v_mfma_f32_16x16x32_bf16 v[70:73], v[82:85], v[62:65], v[70:73]
	s_waitcnt lgkmcnt(0)
	v_mfma_f32_16x16x32_bf16 v[74:77], v[100:103], v[50:53], v[74:77]
	v_mfma_f32_16x16x32_bf16 v[70:73], v[100:103], v[66:69], v[70:73]
	s_setprio 0
	s_nop 5
	v_mul_f32_e32 v74, v5, v74
	v_mul_f32_e32 v75, v5, v75
	v_mul_f32_e32 v70, v136, v70
	v_cvt_pk_bf16_f32 v88, v74, v75
	v_mul_f32_e32 v74, v5, v76
	v_mul_f32_e32 v75, v5, v77
	v_cvt_pk_bf16_f32 v89, v74, v75
	v_mul_f32_e32 v71, v136, v71
	v_cvt_pk_bf16_f32 v106, v70, v71
	v_mul_f32_e32 v70, v136, v72
	v_add_u32_e32 v78, 0x10000, v146
	v_mul_f32_e32 v71, v136, v73
	v_cvt_pk_bf16_f32 v107, v70, v71
	global_store_dwordx4 v[2:3], v[86:89], off offset:192 sc1
	global_store_dwordx4 v[134:135], v[104:107], off offset:192 sc1
	v_add_u32_e32 v70, v78, v149
	v_add_u32_e32 v72, v78, v151
	v_add_u32_e32 v74, v78, v153
	v_add_u32_e32 v76, v78, v154
	v_add_u32_e32 v79, v78, v143
	v_add_u32_e32 v80, v78, v147
	v_add_u32_e32 v81, v78, v150
	s_waitcnt vmcnt(0)
	s_barrier
	ds_read_b64 v[70:71], v70
	ds_read_b64 v[72:73], v72
	ds_read_b64 v[74:75], v74
	ds_read_b64 v[76:77], v76
	v_add_u32_e32 v86, v78, v152
	ds_read_b64 v[82:83], v79
	ds_read_b64 v[84:85], v80
	ds_read_b64 v[90:91], v81
	ds_read_b64 v[92:93], v86
	v_add_u32_e32 v79, v78, v139
	v_add_u32_e32 v80, v78, v141
	v_add_u32_e32 v81, v78, v145
	v_add_u32_e32 v86, v78, v148
	ds_read_b64 v[94:95], v79
	ds_read_b64 v[96:97], v80
	ds_read_b64 v[98:99], v81
	ds_read_b64 v[100:101], v86
	v_add_u32_e32 v79, v78, v137
	v_add_u32_e32 v80, v78, v138
	v_add_u32_e32 v81, v78, v140
	v_add_u32_e32 v78, v78, v142
	ds_read_b64 v[102:103], v79
	ds_read_b64 v[104:105], v80
	ds_read_b64 v[106:107], v81
	ds_read_b64 v[108:109], v78
	v_add_u32_e32 v78, 0x10800, v146
	v_add_u32_e32 v79, v78, v149
	v_add_u32_e32 v80, v78, v151
	v_add_u32_e32 v81, v78, v153
	v_add_u32_e32 v86, v78, v154
	ds_read_b64 v[110:111], v79
	ds_read_b64 v[112:113], v80
	ds_read_b64 v[118:119], v81
	ds_read_b64 v[120:121], v86
	v_add_u32_e32 v79, v78, v143
	v_add_u32_e32 v80, v78, v147
	v_add_u32_e32 v81, v78, v150
	v_add_u32_e32 v86, v78, v152
	ds_read_b64 v[126:127], v79
	ds_read_b64 v[128:129], v80
	ds_read_b64 v[130:131], v81
	ds_read_b64 v[132:133], v86
	v_add_u32_e32 v79, v78, v139
	v_add_u32_e32 v80, v78, v141
	v_add_u32_e32 v81, v78, v145
	v_add_u32_e32 v88, v78, v148
	ds_read_b64 v[156:157], v79
	ds_read_b64 v[158:159], v80
	ds_read_b64 v[86:87], v81
	ds_read_b64 v[88:89], v88
	v_add_u32_e32 v79, v78, v137
	v_add_u32_e32 v80, v78, v138
	v_add_u32_e32 v81, v78, v140
	v_add_u32_e32 v114, v78, v142
	ds_read_b64 v[160:161], v79
	ds_read_b64 v[162:163], v80
	ds_read_b64 v[78:79], v81
	ds_read_b64 v[80:81], v114
	s_setprio 1
	s_waitcnt lgkmcnt(14)
	v_mfma_f32_16x16x32_bf16 v[114:117], v[70:73], v[6:9], 0
	v_mfma_f32_16x16x32_bf16 v[70:73], v[70:73], v[22:25], 0
	v_mfma_f32_16x16x32_bf16 v[114:117], v[74:77], v[10:13], v[114:117]
	v_mfma_f32_16x16x32_bf16 v[70:73], v[74:77], v[26:29], v[70:73]
	v_mfma_f32_16x16x32_bf16 v[74:77], v[82:85], v[14:17], v[114:117]
	v_mfma_f32_16x16x32_bf16 v[70:73], v[82:85], v[30:33], v[70:73]
	v_mfma_f32_16x16x32_bf16 v[74:77], v[90:93], v[18:21], v[74:77]
	v_mfma_f32_16x16x32_bf16 v[70:73], v[90:93], v[34:37], v[70:73]
	v_mfma_f32_16x16x32_bf16 v[74:77], v[94:97], v[38:41], v[74:77]
	v_mfma_f32_16x16x32_bf16 v[70:73], v[94:97], v[54:57], v[70:73]
	v_mfma_f32_16x16x32_bf16 v[74:77], v[98:101], v[42:45], v[74:77]
	v_mfma_f32_16x16x32_bf16 v[70:73], v[98:101], v[58:61], v[70:73]
	v_mfma_f32_16x16x32_bf16 v[74:77], v[102:105], v[46:49], v[74:77]
	v_mfma_f32_16x16x32_bf16 v[70:73], v[102:105], v[62:65], v[70:73]
	v_mfma_f32_16x16x32_bf16 v[74:77], v[106:109], v[50:53], v[74:77]
	v_mfma_f32_16x16x32_bf16 v[70:73], v[106:109], v[66:69], v[70:73]
	s_setprio 0
	v_add_u32_e32 v96, 0x14000, v146
	v_add_u32_e32 v97, v96, v139
	ds_read_b64 v[98:99], v97
	v_add_u32_e32 v97, v96, v141
	ds_read_b64 v[100:101], v97
	v_add_u32_e32 v97, v96, v145
	ds_read_b64 v[106:107], v97
	v_add_u32_e32 v97, v96, v148
	v_mul_f32_e32 v74, v5, v74
	v_mul_f32_e32 v70, v136, v70
	ds_read_b64 v[108:109], v97
	v_add_u32_e32 v97, v96, v137
	v_mul_f32_e32 v75, v5, v75
	v_cvt_pk_bf16_f32 v94, v74, v75
	v_mul_f32_e32 v74, v5, v76
	v_mul_f32_e32 v71, v136, v71
	v_cvt_pk_bf16_f32 v102, v70, v71
	v_mul_f32_e32 v70, v136, v72
	ds_read_b64 v[114:115], v97
	v_add_u32_e32 v97, v96, v138
	v_mul_f32_e32 v75, v5, v77
	v_cvt_pk_bf16_f32 v95, v74, v75
	v_mul_f32_e32 v71, v136, v73
	v_cvt_pk_bf16_f32 v103, v70, v71
	v_add_u32_e32 v70, v96, v149
	v_add_u32_e32 v72, v96, v151
	v_add_u32_e32 v74, v96, v153
	v_add_u32_e32 v76, v96, v154
	v_add_u32_e32 v82, v96, v143
	v_add_u32_e32 v84, v96, v147
	v_add_u32_e32 v90, v96, v150
	v_add_u32_e32 v92, v96, v152
	ds_read_b64 v[116:117], v97
	v_add_u32_e32 v97, v96, v140
	v_add_u32_e32 v96, v96, v142
	ds_read_b64 v[70:71], v70
	ds_read_b64 v[72:73], v72
	ds_read_b64 v[74:75], v74
	ds_read_b64 v[76:77], v76
	ds_read_b64 v[82:83], v82
	ds_read_b64 v[84:85], v84
	ds_read_b64 v[90:91], v90
	ds_read_b64 v[92:93], v92
	ds_read_b64 v[122:123], v97
	ds_read_b64 v[124:125], v96
	s_setprio 1
	v_mfma_f32_16x16x32_bf16 v[164:167], v[110:113], v[6:9], 0
	v_mfma_f32_16x16x32_bf16 v[110:113], v[110:113], v[22:25], 0
	s_waitcnt lgkmcnt(14)
	v_mfma_f32_16x16x32_bf16 v[164:167], v[118:121], v[10:13], v[164:167]
	v_mfma_f32_16x16x32_bf16 v[110:113], v[118:121], v[26:29], v[110:113]
	v_mfma_f32_16x16x32_bf16 v[118:121], v[126:129], v[14:17], v[164:167]
	v_mfma_f32_16x16x32_bf16 v[110:113], v[126:129], v[30:33], v[110:113]
	v_mfma_f32_16x16x32_bf16 v[118:121], v[130:133], v[18:21], v[118:121]
	v_mfma_f32_16x16x32_bf16 v[110:113], v[130:133], v[34:37], v[110:113]
	v_mfma_f32_16x16x32_bf16 v[118:121], v[156:159], v[38:41], v[118:121]
	v_mfma_f32_16x16x32_bf16 v[110:113], v[156:159], v[54:57], v[110:113]
	v_mfma_f32_16x16x32_bf16 v[118:121], v[86:89], v[42:45], v[118:121]
	v_mfma_f32_16x16x32_bf16 v[86:89], v[86:89], v[58:61], v[110:113]
	v_mfma_f32_16x16x32_bf16 v[110:113], v[160:163], v[46:49], v[118:121]
	v_mfma_f32_16x16x32_bf16 v[86:89], v[160:163], v[62:65], v[86:89]
	v_mfma_f32_16x16x32_bf16 v[110:113], v[78:81], v[50:53], v[110:113]
	v_mfma_f32_16x16x32_bf16 v[78:81], v[78:81], v[66:69], v[86:89]
	s_setprio 0
	s_nop 5
	v_mul_f32_e32 v86, v5, v110
	v_mul_f32_e32 v87, v5, v111
	v_mul_f32_e32 v78, v136, v78
	v_cvt_pk_bf16_f32 v96, v86, v87
	v_mul_f32_e32 v86, v5, v112
	v_mul_f32_e32 v87, v5, v113
	v_cvt_pk_bf16_f32 v97, v86, v87
	v_mul_f32_e32 v79, v136, v79
	v_cvt_pk_bf16_f32 v104, v78, v79
	v_mul_f32_e32 v78, v136, v80
	v_add_u32_e32 v132, 0x14800, v146
	v_mul_f32_e32 v79, v136, v81
	v_cvt_pk_bf16_f32 v105, v78, v79
	global_store_dwordx4 v[2:3], v[94:97], off offset:256 sc1
	global_store_dwordx4 v[134:135], v[102:105], off offset:256 sc1
	v_add_u32_e32 v78, v132, v149
	v_add_u32_e32 v80, v132, v151
	v_add_u32_e32 v86, v132, v153
	v_add_u32_e32 v88, v132, v154
	v_add_u32_e32 v94, v132, v143
	v_add_u32_e32 v96, v132, v147
	v_add_u32_e32 v102, v132, v150
	v_add_u32_e32 v104, v132, v152
	v_add_u32_e32 v110, v132, v139
	v_add_u32_e32 v112, v132, v141
	v_add_u32_e32 v118, v132, v145
	v_add_u32_e32 v120, v132, v148
	v_add_u32_e32 v126, v132, v137
	v_add_u32_e32 v128, v132, v138
	v_add_u32_e32 v130, v132, v140
	v_add_u32_e32 v132, v132, v142
	ds_read_b64 v[78:79], v78
	ds_read_b64 v[80:81], v80
	ds_read_b64 v[86:87], v86
	ds_read_b64 v[88:89], v88
	ds_read_b64 v[94:95], v94
	ds_read_b64 v[96:97], v96
	ds_read_b64 v[102:103], v102
	ds_read_b64 v[104:105], v104
	ds_read_b64 v[110:111], v110
	ds_read_b64 v[112:113], v112
	ds_read_b64 v[118:119], v118
	ds_read_b64 v[120:121], v120
	ds_read_b64 v[126:127], v126
	ds_read_b64 v[128:129], v128
	ds_read_b64 v[130:131], v130
	ds_read_b64 v[132:133], v132
	s_setprio 1
	s_waitcnt lgkmcnt(14)
	v_mfma_f32_16x16x32_bf16 v[156:159], v[70:73], v[6:9], 0
	v_mfma_f32_16x16x32_bf16 v[70:73], v[70:73], v[22:25], 0
	v_mfma_f32_16x16x32_bf16 v[156:159], v[74:77], v[10:13], v[156:159]
	v_mfma_f32_16x16x32_bf16 v[70:73], v[74:77], v[26:29], v[70:73]
	v_mfma_f32_16x16x32_bf16 v[74:77], v[82:85], v[14:17], v[156:159]
	v_mfma_f32_16x16x32_bf16 v[70:73], v[82:85], v[30:33], v[70:73]
	v_mfma_f32_16x16x32_bf16 v[74:77], v[90:93], v[18:21], v[74:77]
	v_mfma_f32_16x16x32_bf16 v[70:73], v[90:93], v[34:37], v[70:73]
	v_mfma_f32_16x16x32_bf16 v[74:77], v[98:101], v[38:41], v[74:77]
	v_mfma_f32_16x16x32_bf16 v[70:73], v[98:101], v[54:57], v[70:73]
	v_mfma_f32_16x16x32_bf16 v[74:77], v[106:109], v[42:45], v[74:77]
	v_mfma_f32_16x16x32_bf16 v[70:73], v[106:109], v[58:61], v[70:73]
	v_mfma_f32_16x16x32_bf16 v[74:77], v[114:117], v[46:49], v[74:77]
	v_mfma_f32_16x16x32_bf16 v[70:73], v[114:117], v[62:65], v[70:73]
	v_mfma_f32_16x16x32_bf16 v[74:77], v[122:125], v[50:53], v[74:77]
	v_mfma_f32_16x16x32_bf16 v[70:73], v[122:125], v[66:69], v[70:73]
	s_setprio 0
	s_nop 5
	v_mul_f32_e32 v74, v5, v74
	v_mul_f32_e32 v70, v136, v70
	v_mul_f32_e32 v75, v5, v75
	v_cvt_pk_bf16_f32 v156, v74, v75
	v_mul_f32_e32 v74, v5, v76
	v_mul_f32_e32 v71, v136, v71
	v_cvt_pk_bf16_f32 v160, v70, v71
	v_mul_f32_e32 v70, v136, v72
	v_add_u32_e32 v124, 0x18000, v146
	v_mul_f32_e32 v75, v5, v77
	v_cvt_pk_bf16_f32 v157, v74, v75
	v_mul_f32_e32 v71, v136, v73
	v_cvt_pk_bf16_f32 v161, v70, v71
	v_add_u32_e32 v70, v124, v149
	v_add_u32_e32 v72, v124, v151
	v_add_u32_e32 v74, v124, v153
	v_add_u32_e32 v76, v124, v154
	v_add_u32_e32 v82, v124, v143
	v_add_u32_e32 v84, v124, v147
	v_add_u32_e32 v90, v124, v150
	v_add_u32_e32 v92, v124, v152
	v_add_u32_e32 v98, v124, v139
	v_add_u32_e32 v100, v124, v141
	v_add_u32_e32 v106, v124, v145
	v_add_u32_e32 v108, v124, v148
	v_add_u32_e32 v114, v124, v137
	v_add_u32_e32 v116, v124, v138
	v_add_u32_e32 v122, v124, v140
	v_add_u32_e32 v124, v124, v142
	ds_read_b64 v[70:71], v70
	ds_read_b64 v[72:73], v72
	ds_read_b64 v[74:75], v74
	ds_read_b64 v[76:77], v76
	ds_read_b64 v[82:83], v82
	ds_read_b64 v[84:85], v84
	ds_read_b64 v[90:91], v90
	ds_read_b64 v[92:93], v92
	ds_read_b64 v[98:99], v98
	ds_read_b64 v[100:101], v100
	ds_read_b64 v[106:107], v106
	ds_read_b64 v[108:109], v108
	ds_read_b64 v[114:115], v114
	ds_read_b64 v[116:117], v116
	ds_read_b64 v[122:123], v122
	ds_read_b64 v[124:125], v124
	s_setprio 1
	v_mfma_f32_16x16x32_bf16 v[162:165], v[78:81], v[6:9], 0
	v_mfma_f32_16x16x32_bf16 v[78:81], v[78:81], v[22:25], 0
	s_waitcnt lgkmcnt(14)
	v_mfma_f32_16x16x32_bf16 v[162:165], v[86:89], v[10:13], v[162:165]
	v_mfma_f32_16x16x32_bf16 v[78:81], v[86:89], v[26:29], v[78:81]
	v_mfma_f32_16x16x32_bf16 v[86:89], v[94:97], v[14:17], v[162:165]
	v_mfma_f32_16x16x32_bf16 v[78:81], v[94:97], v[30:33], v[78:81]
	v_mfma_f32_16x16x32_bf16 v[86:89], v[102:105], v[18:21], v[86:89]
	v_mfma_f32_16x16x32_bf16 v[78:81], v[102:105], v[34:37], v[78:81]
	v_mfma_f32_16x16x32_bf16 v[86:89], v[110:113], v[38:41], v[86:89]
	v_mfma_f32_16x16x32_bf16 v[78:81], v[110:113], v[54:57], v[78:81]
	v_mfma_f32_16x16x32_bf16 v[86:89], v[118:121], v[42:45], v[86:89]
	v_mfma_f32_16x16x32_bf16 v[78:81], v[118:121], v[58:61], v[78:81]
	v_mfma_f32_16x16x32_bf16 v[86:89], v[126:129], v[46:49], v[86:89]
	v_mfma_f32_16x16x32_bf16 v[78:81], v[126:129], v[62:65], v[78:81]
	v_mfma_f32_16x16x32_bf16 v[86:89], v[130:133], v[50:53], v[86:89]
	v_mfma_f32_16x16x32_bf16 v[78:81], v[130:133], v[66:69], v[78:81]
	s_setprio 0
	s_nop 5
	v_mul_f32_e32 v86, v5, v86
	v_mul_f32_e32 v87, v5, v87
	v_mul_f32_e32 v78, v136, v78
	v_cvt_pk_bf16_f32 v158, v86, v87
	v_mul_f32_e32 v86, v5, v88
	v_mul_f32_e32 v87, v5, v89
	v_cvt_pk_bf16_f32 v159, v86, v87
	v_mul_f32_e32 v79, v136, v79
	v_cvt_pk_bf16_f32 v162, v78, v79
	v_mul_f32_e32 v78, v136, v80
	v_add_u32_e32 v132, 0x18800, v146
	v_mul_f32_e32 v79, v136, v81
	v_cvt_pk_bf16_f32 v163, v78, v79
	global_store_dwordx4 v[2:3], v[156:159], off offset:320 sc1
	global_store_dwordx4 v[134:135], v[160:163], off offset:320 sc1
	v_add_u32_e32 v78, v132, v149
	v_add_u32_e32 v80, v132, v151
	v_add_u32_e32 v86, v132, v153
	v_add_u32_e32 v88, v132, v154
	v_add_u32_e32 v94, v132, v143
	v_add_u32_e32 v96, v132, v147
	v_add_u32_e32 v102, v132, v150
	v_add_u32_e32 v104, v132, v152
	v_add_u32_e32 v110, v132, v139
	v_add_u32_e32 v112, v132, v141
	v_add_u32_e32 v118, v132, v145
	v_add_u32_e32 v120, v132, v148
	v_add_u32_e32 v126, v132, v137
	v_add_u32_e32 v128, v132, v138
	v_add_u32_e32 v130, v132, v140
	v_add_u32_e32 v132, v132, v142
	ds_read_b64 v[78:79], v78
	ds_read_b64 v[80:81], v80
	ds_read_b64 v[86:87], v86
	ds_read_b64 v[88:89], v88
	ds_read_b64 v[94:95], v94
	ds_read_b64 v[96:97], v96
	ds_read_b64 v[102:103], v102
	ds_read_b64 v[104:105], v104
	ds_read_b64 v[110:111], v110
	ds_read_b64 v[112:113], v112
	ds_read_b64 v[118:119], v118
	ds_read_b64 v[120:121], v120
	ds_read_b64 v[126:127], v126
	ds_read_b64 v[128:129], v128
	ds_read_b64 v[130:131], v130
	ds_read_b64 v[132:133], v132
	s_setprio 1
	v_mfma_f32_16x16x32_bf16 v[156:159], v[70:73], v[6:9], 0
	v_mfma_f32_16x16x32_bf16 v[70:73], v[70:73], v[22:25], 0
	s_waitcnt lgkmcnt(14)
	v_mfma_f32_16x16x32_bf16 v[156:159], v[74:77], v[10:13], v[156:159]
	v_mfma_f32_16x16x32_bf16 v[70:73], v[74:77], v[26:29], v[70:73]
	v_mfma_f32_16x16x32_bf16 v[74:77], v[82:85], v[14:17], v[156:159]
	v_mfma_f32_16x16x32_bf16 v[70:73], v[82:85], v[30:33], v[70:73]
	v_mfma_f32_16x16x32_bf16 v[74:77], v[90:93], v[18:21], v[74:77]
	v_mfma_f32_16x16x32_bf16 v[70:73], v[90:93], v[34:37], v[70:73]
	v_mfma_f32_16x16x32_bf16 v[74:77], v[98:101], v[38:41], v[74:77]
	v_mfma_f32_16x16x32_bf16 v[70:73], v[98:101], v[54:57], v[70:73]
	v_mfma_f32_16x16x32_bf16 v[74:77], v[106:109], v[42:45], v[74:77]
	v_mfma_f32_16x16x32_bf16 v[70:73], v[106:109], v[58:61], v[70:73]
	v_mfma_f32_16x16x32_bf16 v[74:77], v[114:117], v[46:49], v[74:77]
	v_mfma_f32_16x16x32_bf16 v[70:73], v[114:117], v[62:65], v[70:73]
	v_mfma_f32_16x16x32_bf16 v[74:77], v[122:125], v[50:53], v[74:77]
	v_mfma_f32_16x16x32_bf16 v[70:73], v[122:125], v[66:69], v[70:73]
	s_setprio 0
	s_nop 5
	v_mul_f32_e32 v74, v5, v74
	v_mul_f32_e32 v70, v136, v70
	v_mul_f32_e32 v75, v5, v75
	v_cvt_pk_bf16_f32 v156, v74, v75
	v_mul_f32_e32 v74, v5, v76
	v_mul_f32_e32 v71, v136, v71
	v_cvt_pk_bf16_f32 v160, v70, v71
	v_mul_f32_e32 v70, v136, v72
	v_add_u32_e32 v124, 0x1c000, v146
	v_mul_f32_e32 v75, v5, v77
	v_cvt_pk_bf16_f32 v157, v74, v75
	v_mul_f32_e32 v71, v136, v73
	v_cvt_pk_bf16_f32 v161, v70, v71
	v_add_u32_e32 v70, v124, v149
	v_add_u32_e32 v72, v124, v151
	v_add_u32_e32 v74, v124, v153
	v_add_u32_e32 v76, v124, v154
	v_add_u32_e32 v82, v124, v143
	v_add_u32_e32 v84, v124, v147
	v_add_u32_e32 v90, v124, v150
	v_add_u32_e32 v92, v124, v152
	v_add_u32_e32 v98, v124, v139
	v_add_u32_e32 v100, v124, v141
	v_add_u32_e32 v106, v124, v145
	v_add_u32_e32 v108, v124, v148
	v_add_u32_e32 v114, v124, v137
	v_add_u32_e32 v116, v124, v138
	v_add_u32_e32 v122, v124, v140
	v_add_u32_e32 v124, v124, v142
	ds_read_b64 v[70:71], v70
	ds_read_b64 v[72:73], v72
	ds_read_b64 v[74:75], v74
	ds_read_b64 v[76:77], v76
	ds_read_b64 v[82:83], v82
	ds_read_b64 v[84:85], v84
	ds_read_b64 v[90:91], v90
	ds_read_b64 v[92:93], v92
	ds_read_b64 v[98:99], v98
	ds_read_b64 v[100:101], v100
	ds_read_b64 v[106:107], v106
	ds_read_b64 v[108:109], v108
	ds_read_b64 v[114:115], v114
	ds_read_b64 v[116:117], v116
	ds_read_b64 v[122:123], v122
	ds_read_b64 v[124:125], v124
	s_setprio 1
	v_mfma_f32_16x16x32_bf16 v[162:165], v[78:81], v[6:9], 0
	v_mfma_f32_16x16x32_bf16 v[78:81], v[78:81], v[22:25], 0
	s_waitcnt lgkmcnt(14)
	v_mfma_f32_16x16x32_bf16 v[162:165], v[86:89], v[10:13], v[162:165]
	v_mfma_f32_16x16x32_bf16 v[78:81], v[86:89], v[26:29], v[78:81]
	v_mfma_f32_16x16x32_bf16 v[86:89], v[94:97], v[14:17], v[162:165]
	v_mfma_f32_16x16x32_bf16 v[78:81], v[94:97], v[30:33], v[78:81]
	v_mfma_f32_16x16x32_bf16 v[86:89], v[102:105], v[18:21], v[86:89]
	v_mfma_f32_16x16x32_bf16 v[78:81], v[102:105], v[34:37], v[78:81]
	v_mfma_f32_16x16x32_bf16 v[86:89], v[110:113], v[38:41], v[86:89]
	v_mfma_f32_16x16x32_bf16 v[78:81], v[110:113], v[54:57], v[78:81]
	v_mfma_f32_16x16x32_bf16 v[86:89], v[118:121], v[42:45], v[86:89]
	v_mfma_f32_16x16x32_bf16 v[78:81], v[118:121], v[58:61], v[78:81]
	v_mfma_f32_16x16x32_bf16 v[86:89], v[126:129], v[46:49], v[86:89]
	v_mfma_f32_16x16x32_bf16 v[78:81], v[126:129], v[62:65], v[78:81]
	v_mfma_f32_16x16x32_bf16 v[86:89], v[130:133], v[50:53], v[86:89]
	v_mfma_f32_16x16x32_bf16 v[78:81], v[130:133], v[66:69], v[78:81]
	s_setprio 0
	s_nop 5
	v_mul_f32_e32 v86, v5, v86
	v_mul_f32_e32 v87, v5, v87
	v_mul_f32_e32 v78, v136, v78
	v_cvt_pk_bf16_f32 v158, v86, v87
	v_mul_f32_e32 v86, v5, v88
	v_mul_f32_e32 v87, v5, v89
	v_cvt_pk_bf16_f32 v159, v86, v87
	v_mul_f32_e32 v79, v136, v79
	v_cvt_pk_bf16_f32 v162, v78, v79
	v_mul_f32_e32 v78, v136, v80
	v_add_u32_e32 v132, 0x1c800, v146
	v_mul_f32_e32 v79, v136, v81
	v_cvt_pk_bf16_f32 v163, v78, v79
	global_store_dwordx4 v[2:3], v[156:159], off offset:384 sc1
	global_store_dwordx4 v[134:135], v[160:163], off offset:384 sc1
	v_add_u32_e32 v78, v132, v149
	v_add_u32_e32 v80, v132, v151
	v_add_u32_e32 v86, v132, v153
	v_add_u32_e32 v88, v132, v154
	v_add_u32_e32 v94, v132, v143
	v_add_u32_e32 v96, v132, v147
	v_add_u32_e32 v102, v132, v150
	v_add_u32_e32 v104, v132, v152
	v_add_u32_e32 v110, v132, v139
	v_add_u32_e32 v112, v132, v141
	v_add_u32_e32 v118, v132, v145
	v_add_u32_e32 v120, v132, v148
	v_add_u32_e32 v126, v132, v137
	v_add_u32_e32 v128, v132, v138
	v_add_u32_e32 v130, v132, v140
	v_add_u32_e32 v132, v132, v142
	ds_read_b64 v[78:79], v78
	ds_read_b64 v[80:81], v80
	ds_read_b64 v[86:87], v86
	ds_read_b64 v[88:89], v88
	ds_read_b64 v[94:95], v94
	ds_read_b64 v[96:97], v96
	ds_read_b64 v[102:103], v102
	ds_read_b64 v[104:105], v104
	ds_read_b64 v[110:111], v110
	ds_read_b64 v[112:113], v112
	ds_read_b64 v[118:119], v118
	ds_read_b64 v[120:121], v120
	ds_read_b64 v[126:127], v126
	ds_read_b64 v[128:129], v128
	ds_read_b64 v[130:131], v130
	ds_read_b64 v[132:133], v132
	s_setprio 1
	v_mfma_f32_16x16x32_bf16 v[138:141], v[70:73], v[6:9], 0
	v_mfma_f32_16x16x32_bf16 v[70:73], v[70:73], v[22:25], 0
	s_waitcnt lgkmcnt(14)
	v_mfma_f32_16x16x32_bf16 v[138:141], v[74:77], v[10:13], v[138:141]
	v_mfma_f32_16x16x32_bf16 v[70:73], v[74:77], v[26:29], v[70:73]
	v_mfma_f32_16x16x32_bf16 v[74:77], v[82:85], v[14:17], v[138:141]
	v_mfma_f32_16x16x32_bf16 v[70:73], v[82:85], v[30:33], v[70:73]
	v_mfma_f32_16x16x32_bf16 v[74:77], v[90:93], v[18:21], v[74:77]
	v_mfma_f32_16x16x32_bf16 v[70:73], v[90:93], v[34:37], v[70:73]
	v_mfma_f32_16x16x32_bf16 v[74:77], v[98:101], v[38:41], v[74:77]
	v_mfma_f32_16x16x32_bf16 v[70:73], v[98:101], v[54:57], v[70:73]
	v_mfma_f32_16x16x32_bf16 v[74:77], v[106:109], v[42:45], v[74:77]
	v_mfma_f32_16x16x32_bf16 v[70:73], v[106:109], v[58:61], v[70:73]
	v_mfma_f32_16x16x32_bf16 v[74:77], v[114:117], v[46:49], v[74:77]
	v_mfma_f32_16x16x32_bf16 v[70:73], v[114:117], v[62:65], v[70:73]
	v_mfma_f32_16x16x32_bf16 v[74:77], v[122:125], v[50:53], v[74:77]
	v_mfma_f32_16x16x32_bf16 v[70:73], v[122:125], v[66:69], v[70:73]
	s_setprio 0
	s_nop 5
	v_mul_f32_e32 v74, v5, v74
	v_mul_f32_e32 v75, v5, v75
	v_mul_f32_e32 v70, v136, v70
	v_mul_f32_e32 v71, v136, v71
	v_cvt_pk_bf16_f32 v74, v74, v75
	v_mul_f32_e32 v75, v5, v76
	v_cvt_pk_bf16_f32 v70, v70, v71
	v_mul_f32_e32 v71, v136, v72
	v_mul_f32_e32 v76, v5, v77
	v_cvt_pk_bf16_f32 v75, v75, v76
	v_mul_f32_e32 v72, v136, v73
	v_cvt_pk_bf16_f32 v71, v71, v72
	s_setprio 1
	v_mfma_f32_16x16x32_bf16 v[6:9], v[78:81], v[6:9], 0
	v_mfma_f32_16x16x32_bf16 v[22:25], v[78:81], v[22:25], 0
	s_waitcnt lgkmcnt(12)
	v_mfma_f32_16x16x32_bf16 v[6:9], v[86:89], v[10:13], v[6:9]
	v_mfma_f32_16x16x32_bf16 v[10:13], v[86:89], v[26:29], v[22:25]
	s_waitcnt lgkmcnt(10)
	v_mfma_f32_16x16x32_bf16 v[6:9], v[94:97], v[14:17], v[6:9]
	v_mfma_f32_16x16x32_bf16 v[10:13], v[94:97], v[30:33], v[10:13]
	s_waitcnt lgkmcnt(8)
	v_mfma_f32_16x16x32_bf16 v[6:9], v[102:105], v[18:21], v[6:9]
	v_mfma_f32_16x16x32_bf16 v[10:13], v[102:105], v[34:37], v[10:13]
	s_waitcnt lgkmcnt(6)
	v_mfma_f32_16x16x32_bf16 v[6:9], v[110:113], v[38:41], v[6:9]
	v_mfma_f32_16x16x32_bf16 v[10:13], v[110:113], v[54:57], v[10:13]
	s_waitcnt lgkmcnt(4)
	v_mfma_f32_16x16x32_bf16 v[6:9], v[118:121], v[42:45], v[6:9]
	v_mfma_f32_16x16x32_bf16 v[10:13], v[118:121], v[58:61], v[10:13]
	s_waitcnt lgkmcnt(2)
	v_mfma_f32_16x16x32_bf16 v[6:9], v[126:129], v[46:49], v[6:9]
	v_mfma_f32_16x16x32_bf16 v[10:13], v[126:129], v[62:65], v[10:13]
	s_waitcnt lgkmcnt(0)
	v_mfma_f32_16x16x32_bf16 v[6:9], v[130:133], v[50:53], v[6:9]
	v_mfma_f32_16x16x32_bf16 v[10:13], v[130:133], v[66:69], v[10:13]
	s_setprio 0
	s_nop 5
	v_mul_f32_e32 v6, v5, v6
	v_mul_f32_e32 v7, v5, v7
	v_cvt_pk_bf16_f32 v76, v6, v7
	v_mul_f32_e32 v6, v5, v8
	v_mul_f32_e32 v5, v5, v9
	v_cvt_pk_bf16_f32 v77, v6, v5
	v_mul_f32_e32 v5, v136, v10
	v_mul_f32_e32 v6, v136, v11
	v_cvt_pk_bf16_f32 v72, v5, v6
	v_mul_f32_e32 v5, v136, v12
	v_mul_f32_e32 v6, v136, v13
	v_cvt_pk_bf16_f32 v73, v5, v6
	global_store_dwordx4 v[2:3], v[74:77], off offset:448 sc1
	global_store_dwordx4 v[134:135], v[70:73], off offset:448 sc1
	s_barrier

.LBB0_851:
	s_or_b64 exec, exec, s[2:3]
	s_mov_b32 s8, s87
	s_mov_b32 s6, s87
	s_mov_b32 s4, s87
	s_mov_b32 s2, s87
	v_mov_b32_e32 v6, v0
	s_waitcnt lgkmcnt(0)
	s_barrier
	s_movk_i32 s11, 0x400
	v_readfirstlane_b32 s10, v6
	s_and_b64 vcc, exec, s[50:51]
	s_cbranch_vccnz .LBB0_894
	v_lshlrev_b32_e32 v3, 4, v6
	v_add_u32_e32 v2, 0x2000, v3
	v_ashrrev_i32_e32 v5, 31, v2
	v_lshrrev_b32_e32 v5, 22, v5
	v_add_u32_e32 v5, v2, v5
	v_ashrrev_i32_e32 v7, 10, v5
	v_mul_i32_i24_e32 v5, 0x400, v7
	v_sub_u32_e32 v2, v2, v5
	v_lshrrev_b32_e32 v5, 4, v2
	v_bitop3_b32 v2, v5, v2, 32 bitop3:0x6c
	s_ashr_i32 s9, s8, 31
	v_ashrrev_i32_e32 v5, 31, v2
	s_lshl_b64 s[8:9], s[8:9], 3
	v_lshrrev_b32_e32 v5, 26, v5
	s_add_u32 s8, s0, s8
	v_add_u32_e32 v5, v2, v5
	v_lshlrev_b32_e32 v10, 3, v7
	s_addc_u32 s9, s1, s9
	s_ashr_i32 s7, s6, 31
	v_ashrrev_i32_e32 v8, 6, v5
	v_and_b32_e32 v10, -16, v10
	s_lshl_b64 s[6:7], s[6:7], 3
	v_add_u32_e32 v10, v8, v10
	s_add_u32 s6, s0, s6
	v_lshrrev_b32_e32 v11, 2, v10
	v_lshlrev_b32_e32 v12, 1, v10
	v_and_b32_e32 v5, 0xc0, v5
	s_addc_u32 s7, s1, s7
	s_ashr_i32 s5, s4, 31
	v_and_b32_e32 v9, 3, v8
	v_and_b32_e32 v11, 4, v11
	v_and_b32_e32 v12, 0x1fffd8, v12
	v_sub_u32_e32 v2, v2, v5
	s_lshl_b64 s[4:5], s[4:5], 3
	v_or3_b32 v11, v9, v11, v12
	v_lshlrev_b32_e32 v9, 5, v7
	v_ashrrev_i16_sdwa v2, v238, sext(v2) dst_sel:DWORD dst_unused:UNUSED_PAD src0_sel:DWORD src1_sel:BYTE_0
	s_add_u32 s4, s0, s4
	v_and_b32_e32 v12, 32, v9
	v_bfe_i32 v9, v2, 0, 16
	s_addc_u32 s5, s1, s5
	s_ashr_i32 s3, s2, 31
	v_add_lshl_u32 v5, v12, v9, 1
	s_lshl_b64 s[2:3], s[2:3], 3
	v_lshl_add_u32 v2, v11, 11, v5
	v_lshl_add_u32 v202, v10, 11, v5
	v_bfe_i32 v5, v6, 27, 1
	s_add_u32 s2, s0, s2
	v_lshrrev_b32_e32 v5, 22, v5
	s_addc_u32 s3, s1, s3
	v_add_u32_e32 v5, v3, v5
	s_mov_b64 s[12:13], s[100:101]
	s_nop 0
	s_mov_b64 s[4:5], s[100:101]
	s_nop 0
	s_mov_b64 s[6:7], s[100:101]
	s_nop 0
	s_mov_b64 s[2:3], s[100:101]
	v_and_b32_e32 v5, 0xfffffc00, v5
	s_lshl_b32 s8, s38, 1
	v_sub_u32_e32 v3, v3, v5
	s_waitcnt lgkmcnt(0)
	s_add_u32 s8, s12, s8
	v_lshrrev_b32_e32 v5, 4, v3
	v_ashrrev_i32_e32 v11, 31, v6
	s_addc_u32 s9, s13, 0
	v_bitop3_b32 v3, v5, v3, 32 bitop3:0x6c
	v_lshrrev_b32_e32 v11, 26, v11
	s_add_u32 s36, s8, 0x1e00000
	v_ashrrev_i32_e32 v5, 31, v3
	v_add_u32_e32 v11, v6, v11
	s_addc_u32 s37, s9, 0
	v_lshrrev_b32_e32 v5, 26, v5
	v_ashrrev_i32_e32 v11, 6, v11
	s_add_u32 s2, s2, s81
	v_add_u32_e32 v5, v3, v5
	v_lshlrev_b32_e32 v13, 3, v11
	s_addc_u32 s3, s3, 0
	v_ashrrev_i32_e32 v10, 6, v5
	v_and_b32_e32 v13, -16, v13
	s_add_u32 s38, s2, 0xae00000
	v_add_u32_e32 v13, v10, v13
	s_addc_u32 s39, s3, 0
	s_ashr_i32 s9, s10, 6
	v_lshrrev_b32_e32 v14, 2, v13
	v_lshlrev_b32_e32 v15, 1, v13
	v_and_b32_e32 v5, 0xc0, v5
	s_ashr_i32 s8, s10, 8
	s_lshl_b32 s2, s9, 10
	v_and_b32_e32 v12, 3, v10
	v_and_b32_e32 v14, 4, v14
	v_and_b32_e32 v15, 0x1fffd8, v15
	v_sub_u32_e32 v3, v3, v5
	v_readlane_b32 s12, v253, 60
	v_or3_b32 v14, v12, v14, v15
	v_lshlrev_b32_e32 v12, 5, v11
	v_ashrrev_i16_sdwa v3, v238, sext(v3) dst_sel:DWORD dst_unused:UNUSED_PAD src0_sel:DWORD src1_sel:BYTE_0
	v_readlane_b32 s13, v253, 61
	s_add_u32 s22, s36, s12
	v_and_b32_e32 v15, 32, v12
	v_bfe_i32 v12, v3, 0, 16
	s_addc_u32 s23, s37, s13
	s_add_i32 s40, s2, 0
	v_add_lshl_u32 v3, v15, v12, 1
	s_add_i32 s41, s40, 0x10000
	s_add_i32 s42, s40, 0x12000
	v_lshl_add_u32 v204, v14, 11, v3
	s_mov_b32 m0, s41
	s_add_u32 s2, s22, 0x10000
	global_load_lds_dwordx4 v204, s[22:23]
	s_mov_b32 m0, s42
	s_addc_u32 s3, s23, 0
	s_add_i32 s43, s40, 0x14000
	global_load_lds_dwordx4 v2, s[22:23]
	s_mov_b32 m0, s43
	s_add_i32 s44, s40, 0x16000
	global_load_lds_dwordx4 v204, s[2:3]
	s_mov_b32 m0, s44
	v_lshl_add_u32 v206, v13, 11, v3
	global_load_lds_dwordx4 v2, s[2:3]
	v_readlane_b32 s2, v253, 58
	v_readlane_b32 s3, v253, 59
	s_add_u32 s24, s38, s2
	s_addc_u32 s25, s39, s3
	s_add_i32 s45, s40, 0x2000
	s_mov_b32 m0, s40
	s_add_u32 s2, s24, 0x40000
	global_load_lds_dwordx4 v206, s[24:25]
	s_mov_b32 m0, s45
	s_addc_u32 s3, s25, 0
	s_add_i32 s46, s40, 0x4000
	v_mov_b32_e32 v205, v4
	global_load_lds_dwordx4 v202, s[24:25]
	s_mov_b32 m0, s46
	s_add_i32 s47, s40, 0x6000
	v_lshl_add_u64 v[14:15], s[22:23], 0, v[204:205]
	v_mov_b32_e32 v3, v4
	global_load_lds_dwordx4 v206, s[2:3]
	s_mov_b32 m0, s47
	s_add_i32 s48, s40, 0x18000
	v_lshl_add_u64 v[16:17], s[22:23], 0, v[2:3]
	v_mov_b32_e32 v207, v4
	global_load_lds_dwordx4 v202, s[2:3]
	v_lshl_add_u64 v[14:15], v[14:15], 0, s[68:69]
	s_mov_b32 m0, s48
	s_add_i32 s49, s40, 0x1a000
	v_lshl_add_u64 v[18:19], s[24:25], 0, v[206:207]
	v_mov_b32_e32 v203, v4
	global_load_lds_dwordx4 v[14:15], off
	v_lshl_add_u64 v[14:15], v[16:17], 0, s[68:69]
	s_mov_b32 m0, s49
	s_add_i32 s50, s40, 0x8000
	s_add_i32 s51, s40, 0xa000
	v_lshl_add_u64 v[20:21], s[24:25], 0, v[202:203]
	global_load_lds_dwordx4 v[14:15], off
	v_lshl_add_u64 v[14:15], v[18:19], 0, s[68:69]
	s_mov_b32 m0, s50
	s_add_u32 s2, s22, 0x10080
	global_load_lds_dwordx4 v[14:15], off
	v_lshl_add_u64 v[14:15], v[20:21], 0, s[68:69]
	s_mov_b32 m0, s51
	s_addc_u32 s3, s23, 0
	s_add_i32 s52, s40, 0x1c000
	global_load_lds_dwordx4 v[14:15], off
	s_mov_b32 m0, s52
	s_add_i32 s53, s40, 0x1e000
	global_load_lds_dwordx4 v204, s[2:3]
	s_mov_b32 m0, s53
	s_cmp_eq_u32 s8, 1
	global_load_lds_dwordx4 v2, s[2:3]
	s_cselect_b64 s[2:3], -1, 0
	s_cmp_lg_u32 s8, 1
	s_cbranch_scc1 .LBB0_854
	s_barrier

.LBB0_931:
	s_or_b64 exec, exec, s[2:3]
	v_readlane_b32 s12, v253, 35
	s_mov_b32 s8, s87
	s_mov_b32 s6, s87
	s_mov_b32 s2, s87
	s_mov_b32 s4, s87
	s_waitcnt lgkmcnt(0)
	v_mov_b32_e32 v2, v0
	v_readlane_b32 s13, v253, 36
	s_barrier
	s_lshl_b32 s36, s46, 22
	s_movk_i32 s11, 0x400
	v_readfirstlane_b32 s10, v2
	s_andn2_b64 vcc, exec, s[12:13]
	s_cbranch_vccnz .LBB0_962
	v_lshlrev_b32_e32 v5, 4, v2
	v_add_u32_e32 v6, 0x2000, v5
	s_ashr_i32 s9, s8, 31
	v_ashrrev_i32_e32 v3, 31, v6
	s_lshl_b64 s[8:9], s[8:9], 3
	v_lshrrev_b32_e32 v3, 22, v3
	s_add_u32 s8, s0, s8
	v_add_u32_e32 v3, v6, v3
	s_addc_u32 s9, s1, s9
	v_ashrrev_i32_e32 v3, 10, v3
	s_mov_b64 s[8:9], s[100:101]
	v_mul_i32_i24_e32 v7, 0x400, v3
	v_sub_u32_e32 v6, v6, v7
	v_lshrrev_b32_e32 v7, 4, v6
	v_bitop3_b32 v7, v7, v6, 32 bitop3:0x6c
	v_ashrrev_i32_e32 v6, 31, v7
	s_waitcnt lgkmcnt(0)
	s_add_u32 s3, s8, s89
	v_lshrrev_b32_e32 v6, 26, v6
	s_addc_u32 s5, s9, 0
	v_add_u32_e32 v8, v7, v6
	v_lshlrev_b32_e32 v10, 3, v3
	s_add_u32 s37, s3, 0x7600000
	v_ashrrev_i32_e32 v6, 6, v8
	v_and_b32_e32 v10, -16, v10
	s_addc_u32 s38, s5, 0
	s_ashr_i32 s7, s6, 31
	v_add_u32_e32 v10, v6, v10
	s_lshl_b64 s[6:7], s[6:7], 3
	v_lshrrev_b32_e32 v11, 2, v10
	v_lshlrev_b32_e32 v12, 1, v10
	v_and_b32_e32 v8, 0xc0, v8
	s_add_u32 s6, s0, s6
	v_and_b32_e32 v9, 3, v6
	v_and_b32_e32 v11, 4, v11
	v_and_b32_e32 v12, 0x1fffd8, v12
	v_sub_u32_e32 v7, v7, v8
	s_addc_u32 s7, s1, s7
	v_or3_b32 v9, v9, v11, v12
	v_lshlrev_b32_e32 v11, 5, v3
	v_ashrrev_i16_sdwa v7, v238, sext(v7) dst_sel:DWORD dst_unused:UNUSED_PAD src0_sel:DWORD src1_sel:BYTE_0
	s_mov_b64 s[6:7], s[100:101]
	v_and_b32_e32 v11, 32, v11
	v_bfe_i32 v7, v7, 0, 16
	v_add_lshl_u32 v8, v11, v7, 1
	v_lshl_add_u32 v198, v9, 11, v8
	v_lshl_add_u32 v200, v10, 11, v8
	v_bfe_i32 v8, v2, 27, 1
	v_lshrrev_b32_e32 v8, 22, v8
	s_lshl_b32 s3, s36, 1
	v_add_u32_e32 v8, v5, v8
	s_waitcnt lgkmcnt(0)
	s_add_u32 s3, s6, s3
	v_and_b32_e32 v8, 0xfffffc00, v8
	s_addc_u32 s5, s7, 0
	v_sub_u32_e32 v5, v5, v8
	s_add_u32 s39, s3, 0x2600000
	v_lshrrev_b32_e32 v8, 4, v5
	v_ashrrev_i32_e32 v9, 31, v2
	s_addc_u32 s40, s5, 0
	s_ashr_i32 s3, s2, 31
	v_bitop3_b32 v5, v8, v5, 32 bitop3:0x6c
	v_lshrrev_b32_e32 v9, 26, v9
	s_lshl_b64 s[2:3], s[2:3], 3
	v_ashrrev_i32_e32 v8, 31, v5
	v_add_u32_e32 v9, v2, v9
	s_add_u32 s2, s0, s2
	v_lshrrev_b32_e32 v8, 26, v8
	v_ashrrev_i32_e32 v9, 6, v9
	s_addc_u32 s3, s1, s3
	s_ashr_i32 s5, s4, 31
	v_add_u32_e32 v10, v5, v8
	v_lshlrev_b32_e32 v12, 3, v9
	s_lshl_b64 s[4:5], s[4:5], 3
	v_ashrrev_i32_e32 v8, 6, v10
	v_and_b32_e32 v12, -16, v12
	s_add_u32 s4, s0, s4
	v_add_u32_e32 v12, v8, v12
	s_addc_u32 s5, s1, s5
	s_ashr_i32 s13, s10, 6
	v_lshrrev_b32_e32 v13, 2, v12
	v_lshlrev_b32_e32 v14, 1, v12
	v_and_b32_e32 v10, 0xc0, v10
	s_ashr_i32 s12, s10, 8
	s_lshl_b32 s6, s13, 10
	v_and_b32_e32 v11, 3, v8
	v_and_b32_e32 v13, 4, v13
	v_and_b32_e32 v14, 0x1fffd8, v14
	v_sub_u32_e32 v5, v5, v10
	v_readlane_b32 s8, v253, 56
	v_or3_b32 v11, v11, v13, v14
	v_lshlrev_b32_e32 v13, 5, v9
	v_ashrrev_i16_sdwa v5, v238, sext(v5) dst_sel:DWORD dst_unused:UNUSED_PAD src0_sel:DWORD src1_sel:BYTE_0
	v_readlane_b32 s9, v253, 57
	s_add_u32 s22, s39, s8
	v_and_b32_e32 v13, 32, v13
	v_bfe_i32 v10, v5, 0, 16
	s_addc_u32 s23, s40, s9
	s_add_i32 s41, s6, 0
	v_add_lshl_u32 v5, v13, v10, 1
	s_add_i32 s42, s41, 0x10000
	s_add_i32 s43, s41, 0x12000
	v_lshl_add_u32 v202, v11, 11, v5
	s_mov_b32 m0, s42
	s_add_u32 s6, s22, 0x10000
	global_load_lds_dwordx4 v202, s[22:23]
	s_mov_b32 m0, s43
	s_addc_u32 s7, s23, 0
	s_add_i32 s44, s41, 0x14000
	global_load_lds_dwordx4 v198, s[22:23]
	s_mov_b32 m0, s44
	s_add_i32 s45, s41, 0x16000
	global_load_lds_dwordx4 v202, s[6:7]
	s_mov_b32 m0, s45
	v_lshl_add_u32 v204, v12, 11, v5
	global_load_lds_dwordx4 v198, s[6:7]
	v_readlane_b32 s6, v253, 52
	v_readlane_b32 s7, v253, 53
	s_add_u32 s24, s37, s6
	s_addc_u32 s25, s38, s7
	s_add_i32 s46, s41, 0x2000
	s_mov_b32 m0, s41
	s_add_u32 s6, s24, 0x40000
	global_load_lds_dwordx4 v204, s[24:25]
	s_mov_b32 m0, s46
	s_addc_u32 s7, s25, 0
	s_add_i32 s47, s41, 0x4000
	v_mov_b32_e32 v203, v4
	global_load_lds_dwordx4 v200, s[24:25]
	s_mov_b32 m0, s47
	s_add_i32 s48, s41, 0x6000
	v_lshl_add_u64 v[12:13], s[22:23], 0, v[202:203]
	v_mov_b32_e32 v199, v4
	global_load_lds_dwordx4 v204, s[6:7]
	s_mov_b32 m0, s48
	s_add_i32 s49, s41, 0x18000
	v_lshl_add_u64 v[14:15], s[22:23], 0, v[198:199]
	v_mov_b32_e32 v205, v4
	global_load_lds_dwordx4 v200, s[6:7]
	v_lshl_add_u64 v[12:13], v[12:13], 0, s[68:69]
	s_mov_b32 m0, s49
	s_add_i32 s50, s41, 0x1a000
	v_lshl_add_u64 v[16:17], s[24:25], 0, v[204:205]
	v_mov_b32_e32 v201, v4
	global_load_lds_dwordx4 v[12:13], off
	v_lshl_add_u64 v[12:13], v[14:15], 0, s[68:69]
	s_mov_b32 m0, s50
	s_add_i32 s51, s41, 0x8000
	s_add_i32 s52, s41, 0xa000
	v_lshl_add_u64 v[18:19], s[24:25], 0, v[200:201]
	global_load_lds_dwordx4 v[12:13], off
	v_lshl_add_u64 v[12:13], v[16:17], 0, s[68:69]
	s_mov_b32 m0, s51
	s_add_u32 s6, s22, 0x10080
	global_load_lds_dwordx4 v[12:13], off
	v_lshl_add_u64 v[12:13], v[18:19], 0, s[68:69]
	s_mov_b32 m0, s52
	s_addc_u32 s7, s23, 0
	s_add_i32 s53, s41, 0x1c000
	global_load_lds_dwordx4 v[12:13], off
	s_mov_b32 m0, s53
	s_add_i32 s54, s41, 0x1e000
	global_load_lds_dwordx4 v202, s[6:7]
	s_mov_b32 m0, s54
	s_cmp_eq_u32 s12, 1
	global_load_lds_dwordx4 v198, s[6:7]
	s_mov_b64 s[8:9], s[100:101]
	s_mov_b64 s[6:7], s[100:101]
	s_cselect_b64 s[2:3], -1, 0
	s_cmp_lg_u32 s12, 1
	s_cbranch_scc1 .LBB0_934
	s_barrier

.LBB0_999:
	s_or_b64 exec, exec, s[2:3]
	s_cmp_lg_u32 s46, 3
	s_mov_b32 s4, s87
	s_waitcnt lgkmcnt(0)
	s_barrier
	s_cselect_b64 s[2:3], -1, 0
	s_ashr_i32 s5, s4, 31
	s_lshl_b64 s[4:5], s[4:5], 3
	s_add_u32 s4, s0, s4
	s_addc_u32 s5, s1, s5
	s_mov_b64 s[6:7], s[100:101]
	s_mov_b32 s4, s87
	s_ashr_i32 s5, s4, 31
	s_lshl_b64 s[4:5], s[4:5], 3
	s_add_u32 s4, s0, s4
	s_addc_u32 s5, s1, s5
	s_mov_b64 s[8:9], s[100:101]
	s_mov_b64 s[10:11], 0
	s_and_b64 vcc, exec, s[2:3]
	s_mov_b64 s[12:13], 0
	s_cbranch_vccnz .LBB0_1001
	s_mov_b32 s4, s87
	s_ashr_i32 s5, s4, 31
	s_lshl_b64 s[4:5], s[4:5], 3
	s_add_u32 s4, s0, s4
	s_addc_u32 s5, s1, s5
	s_load_dwordx2 s[4:5], s[4:5], 0xd0
	s_waitcnt lgkmcnt(0)
	s_add_u32 s12, s4, s80
	s_addc_u32 s13, s5, 0
.LBB0_1001:
	s_mov_b32 s4, s87
	s_ashr_i32 s5, s4, 31
	s_lshl_b64 s[4:5], s[4:5], 3
	s_add_u32 s4, s0, s4
	s_addc_u32 s5, s1, s5
	s_mov_b32 s14, s87
	s_mov_b64 s[4:5], s[100:101]
	s_ashr_i32 s15, s14, 31
	s_lshl_b64 s[14:15], s[14:15], 3
	s_add_u32 s14, s0, s14
	s_addc_u32 s15, s1, s15
	s_mov_b64 s[18:19], s[100:101]
	v_readlane_b32 s14, v254, 26
	v_readlane_b32 s15, v254, 27
	s_andn2_b64 vcc, exec, s[14:15]
	s_cbranch_vccnz .LBB0_1003
	s_mov_b32 s10, s87
	s_ashr_i32 s11, s10, 31
	s_lshl_b64 s[10:11], s[10:11], 3
	s_add_u32 s10, s0, s10
	s_addc_u32 s11, s1, s11
	s_load_dwordx2 s[10:11], s[10:11], 0xd0
	s_waitcnt lgkmcnt(0)
	s_add_u32 s10, s10, s80
	s_addc_u32 s11, s11, 0
	s_add_u32 s10, s10, 0x800000
	s_addc_u32 s11, s11, 0

	.amdhsa_kernel _Z6mk_fwd4Args
		.amdhsa_group_segment_fixed_size 0
		.amdhsa_private_segment_fixed_size 0
		.amdhsa_kernarg_size 488
		.amdhsa_user_sgpr_count 2
		.amdhsa_user_sgpr_dispatch_ptr 0
		.amdhsa_user_sgpr_queue_ptr 0
		.amdhsa_user_sgpr_kernarg_segment_ptr 1
		.amdhsa_user_sgpr_dispatch_id 0
		.amdhsa_user_sgpr_kernarg_preload_length 0
		.amdhsa_user_sgpr_kernarg_preload_offset 0
		.amdhsa_user_sgpr_private_segment_size 0
		.amdhsa_uses_dynamic_stack 0
		.amdhsa_enable_private_segment 0
		.amdhsa_system_sgpr_workgroup_id_x 1
		.amdhsa_system_sgpr_workgroup_id_y 0
		.amdhsa_system_sgpr_workgroup_id_z 0
		.amdhsa_system_sgpr_workgroup_info 0
		.amdhsa_system_vgpr_workitem_id 0
		.amdhsa_next_free_vgpr 255
		.amdhsa_next_free_sgpr 102
		.amdhsa_accum_offset 256
		.amdhsa_reserve_vcc 1
		.amdhsa_float_round_mode_32 0
		.amdhsa_float_round_mode_16_64 0
		.amdhsa_float_denorm_mode_32 3
		.amdhsa_float_denorm_mode_16_64 3
		.amdhsa_dx10_clamp 1
		.amdhsa_ieee_mode 1
		.amdhsa_fp16_overflow 0
		.amdhsa_tg_split 0
		.amdhsa_exception_fp_ieee_invalid_op 0
		.amdhsa_exception_fp_denorm_src 0
		.amdhsa_exception_fp_ieee_div_zero 0
		.amdhsa_exception_fp_ieee_overflow 0
		.amdhsa_exception_fp_ieee_underflow 0
		.amdhsa_exception_fp_ieee_inexact 0
		.amdhsa_exception_int_div_zero 0
	.end_amdhsa_kernel

amdhsa.kernels:
  - .agpr_count:     0
    .args:
      - .offset:         0
        .size:           232
        .value_kind:     by_value
      - .offset:         232
        .size:           4
        .value_kind:     hidden_block_count_x
      - .offset:         236
        .size:           4
        .value_kind:     hidden_block_count_y
      - .offset:         240
        .size:           4
        .value_kind:     hidden_block_count_z
      - .offset:         244
        .size:           2
        .value_kind:     hidden_group_size_x
      - .offset:         246
        .size:           2
        .value_kind:     hidden_group_size_y
      - .offset:         248
        .size:           2
        .value_kind:     hidden_group_size_z
      - .offset:         250
        .size:           2
        .value_kind:     hidden_remainder_x
      - .offset:         252
        .size:           2
        .value_kind:     hidden_remainder_y
      - .offset:         254
        .size:           2
        .value_kind:     hidden_remainder_z
      - .offset:         272
        .size:           8
        .value_kind:     hidden_global_offset_x
      - .offset:         280
        .size:           8
        .value_kind:     hidden_global_offset_y
      - .offset:         288
        .size:           8
        .value_kind:     hidden_global_offset_z
      - .offset:         296
        .size:           2
        .value_kind:     hidden_grid_dims
      - .offset:         352
        .size:           4
        .value_kind:     hidden_dynamic_lds_size
    .group_segment_fixed_size: 0
    .kernarg_segment_align: 8
    .kernarg_segment_size: 488
    .language:       OpenCL C
    .language_version:
      - 2
      - 0
    .max_flat_workgroup_size: 512
    .name:           _Z6mk_fwd4Args
    .private_segment_fixed_size: 0
    .sgpr_count:     108
    .sgpr_spill_count: 235
    .symbol:         _Z6mk_fwd4Args.kd
    .uniform_work_group_size: 1
    .uses_dynamic_stack: false
    .vgpr_count:     255
    .vgpr_spill_count: 0
    .wavefront_size: 64
